# FFT: spectrum-product loads issued before the pass barrier, sign/swap moves folded into packed-op modifiers, no barrier between fwd and inv pass 4
# speedup vs baseline: 1.0115x; 1.0115x over previous
.LBB0_288:
	v_mov_b32_e32 v38, v0
	v_add_u32_e32 v66, 0x200, v0
	v_ashrrev_i32_e32 v1, 7, v0
	v_ashrrev_i32_e32 v4, 7, v66
	v_mad_u64_u32 v[2:3], s[40:41], v1, s25, v[60:61]
	v_mad_u64_u32 v[4:5], s[40:41], v4, s25, v[60:61]
	v_cvt_f32_i32_e32 v38, v38
	v_add_u32_e32 v1, 0x10200, v2
	v_add_u32_e32 v3, 0x10200, v4
	v_add_u32_e32 v5, 0x14280, v2
	ds_read_b64 v[6:7], v2
	ds_read_b64 v[8:9], v4
	ds_read_b64 v[10:11], v2 offset:16512
	ds_read_b64 v[12:13], v4 offset:16512
	ds_read_b64 v[14:15], v2 offset:33024
	ds_read_b64 v[16:17], v4 offset:33024
	ds_read_b64 v[18:19], v2 offset:49536
	ds_read_b64 v[20:21], v4 offset:49536
	ds_read_b64 v[22:23], v1
	ds_read_b64 v[24:25], v3
	ds_read_b64 v[26:27], v5
	v_add_u32_e32 v87, 0x18300, v2
	ds_read_b64 v[30:31], v87
	v_add_u32_e32 v88, 0x18300, v4
	v_add_u32_e32 v89, 0x1c380, v2
	v_mul_f32_e32 v39, 0x38800000, v38
	ds_read_b64 v[32:33], v88
	ds_read_b64 v[34:35], v89
	v_cos_f32_e32 v38, v39
	v_add_u32_e32 v86, 0x14280, v4
	v_sin_f32_e32 v40, v39
	ds_read_b64 v[28:29], v86
	s_waitcnt lgkmcnt(6)
	v_pk_add_f32 v[84:85], v[6:7], v[22:23]
	v_pk_add_f32 v[6:7], v[6:7], v[22:23] neg_lo:[0,1] neg_hi:[0,1]
	s_waitcnt lgkmcnt(4)
	v_pk_add_f32 v[22:23], v[10:11], v[26:27]
	v_pk_add_f32 v[10:11], v[10:11], v[26:27] neg_lo:[0,1] neg_hi:[0,1]
	v_add_u32_e32 v90, 0x1c380, v4
	v_mul_f32_e32 v26, 0x3f3504f3, v11
	ds_read_b64 v[36:37], v90
	v_mov_b32_e32 v41, v38
	v_pk_fma_f32 v[10:11], v[10:11], s[56:57], v[26:27] op_sel_hi:[0,1,0]
	s_waitcnt lgkmcnt(4)
	v_pk_add_f32 v[26:27], v[14:15], v[30:31]
	v_pk_add_f32 v[14:15], v[14:15], v[30:31] neg_lo:[0,1] neg_hi:[0,1]
	v_xor_b32_e32 v39, 0x80000000, v40
	v_pk_mul_f32 v[42:43], v[40:41], v[40:41] op_sel_hi:[1,0] neg_lo:[0,1] neg_hi:[0,1]
	v_xor_b32_e32 v31, 0x80000000, v14
	v_mov_b32_e32 v30, v15
	s_waitcnt lgkmcnt(2)
	v_pk_add_f32 v[14:15], v[18:19], v[34:35]
	v_pk_add_f32 v[18:19], v[18:19], v[34:35] neg_lo:[0,1] neg_hi:[0,1]
	v_pk_fma_f32 v[42:43], v[38:39], v[38:39], v[42:43] op_sel_hi:[1,0,1]
	v_mul_f32_e32 v34, 0xbf3504f3, v18
	v_pk_fma_f32 v[18:19], v[18:19], s[56:57], v[34:35] op_sel:[1,0,0] op_sel_hi:[1,1,0]
	v_pk_add_f32 v[34:35], v[84:85], v[26:27]
	v_pk_add_f32 v[26:27], v[84:85], v[26:27] neg_lo:[0,1] neg_hi:[0,1]
	v_pk_add_f32 v[84:85], v[22:23], v[14:15]
	v_pk_add_f32 v[14:15], v[22:23], v[14:15] neg_lo:[0,1] neg_hi:[0,1]
	v_pk_mul_f32 v[44:45], v[40:41], v[42:43] op_sel:[0,1]
	v_pk_mul_f32 v[48:49], v[42:43], v[42:43] op_sel:[1,1] op_sel_hi:[1,0] neg_lo:[0,1]
	v_xor_b32_e32 v23, 0x80000000, v14
	v_mov_b32_e32 v22, v15
	v_pk_add_f32 v[14:15], v[6:7], v[30:31]
	v_pk_add_f32 v[6:7], v[6:7], v[30:31] neg_lo:[0,1] neg_hi:[0,1]
	v_pk_add_f32 v[30:31], v[10:11], v[18:19]
	v_pk_add_f32 v[10:11], v[10:11], v[18:19] neg_lo:[0,1] neg_hi:[0,1]
	v_pk_fma_f32 v[44:45], v[38:39], v[42:43], v[44:45] op_sel_hi:[1,0,1]
	v_pk_fma_f32 v[48:49], v[42:43], v[42:43], v[48:49] op_sel_hi:[1,0,1]
	v_xor_b32_e32 v19, 0x80000000, v10
	v_mov_b32_e32 v18, v11
	v_pk_add_f32 v[10:11], v[34:35], v[84:85]
	v_pk_add_f32 v[34:35], v[34:35], v[84:85] neg_lo:[0,1] neg_hi:[0,1]
	v_pk_add_f32 v[84:85], v[26:27], v[22:23]
	v_pk_add_f32 v[22:23], v[26:27], v[22:23] neg_lo:[0,1] neg_hi:[0,1]
	v_pk_add_f32 v[26:27], v[14:15], v[30:31]
	v_pk_mul_f32 v[50:51], v[40:41], v[48:49] op_sel:[0,1]
	v_pk_add_f32 v[14:15], v[14:15], v[30:31] neg_lo:[0,1] neg_hi:[0,1]
	v_pk_add_f32 v[30:31], v[6:7], v[18:19]
	v_pk_add_f32 v[6:7], v[6:7], v[18:19] neg_lo:[0,1] neg_hi:[0,1]
	v_pk_mul_f32 v[18:19], v[40:41], v[26:27] op_sel:[0,1]
	v_pk_fma_f32 v[50:51], v[38:39], v[48:49], v[50:51] op_sel_hi:[1,0,1]
	v_pk_fma_f32 v[18:19], v[38:39], v[26:27], v[18:19] op_sel_hi:[1,0,1]
	v_pk_mul_f32 v[38:39], v[44:45], v[30:31] op_sel:[1,1] op_sel_hi:[0,1] neg_lo:[1,0]
	v_pk_mul_f32 v[52:53], v[42:43], v[48:49] op_sel:[1,1] op_sel_hi:[0,1] neg_lo:[1,0]
	v_pk_fma_f32 v[30:31], v[44:45], v[30:31], v[38:39] op_sel_hi:[1,0,1]
	v_pk_mul_f32 v[38:39], v[48:49], v[34:35] op_sel:[1,1] op_sel_hi:[0,1] neg_lo:[1,0]
	v_pk_fma_f32 v[52:53], v[42:43], v[48:49], v[52:53] op_sel_hi:[1,0,1]
	v_pk_fma_f32 v[34:35], v[48:49], v[34:35], v[38:39] op_sel_hi:[1,0,1]
	v_pk_mul_f32 v[38:39], v[50:51], v[14:15] op_sel:[1,1] op_sel_hi:[0,1] neg_lo:[1,0]
	v_pk_mul_f32 v[82:83], v[48:49], v[44:45] op_sel:[1,1] op_sel_hi:[1,0] neg_lo:[0,1]
	v_pk_fma_f32 v[14:15], v[50:51], v[14:15], v[38:39] op_sel_hi:[1,0,1]
	v_pk_fma_f32 v[82:83], v[44:45], v[48:49], v[82:83] op_sel_hi:[1,0,1]
	v_pk_mul_f32 v[38:39], v[52:53], v[22:23] op_sel:[1,1] op_sel_hi:[0,1] neg_lo:[1,0]
	v_pk_mul_f32 v[26:27], v[42:43], v[84:85] op_sel:[1,1] op_sel_hi:[0,1] neg_lo:[1,0]
	v_pk_fma_f32 v[22:23], v[52:53], v[22:23], v[38:39] op_sel_hi:[1,0,1]
	v_pk_mul_f32 v[38:39], v[82:83], v[6:7] op_sel:[1,1] op_sel_hi:[0,1] neg_lo:[1,0]
	v_pk_fma_f32 v[26:27], v[42:43], v[84:85], v[26:27] op_sel_hi:[1,0,1]
	v_pk_fma_f32 v[6:7], v[82:83], v[6:7], v[38:39] op_sel_hi:[1,0,1]
	v_cvt_f32_i32_e32 v38, v66
	v_pk_add_f32 v[84:85], v[8:9], v[24:25]
	v_pk_add_f32 v[8:9], v[8:9], v[24:25] neg_lo:[0,1] neg_hi:[0,1]
	s_waitcnt lgkmcnt(1)
	v_pk_add_f32 v[24:25], v[12:13], v[28:29]
	v_mul_f32_e32 v39, 0x38800000, v38
	v_cos_f32_e32 v38, v39
	v_sin_f32_e32 v40, v39
	v_pk_add_f32 v[12:13], v[12:13], v[28:29] neg_lo:[0,1] neg_hi:[0,1]
	v_cmp_lt_i32_e32 vcc, s28, v0
	v_mul_f32_e32 v28, 0x3f3504f3, v13
	v_mov_b32_e32 v41, v38
	v_pk_fma_f32 v[12:13], v[12:13], s[56:57], v[28:29] op_sel_hi:[0,1,0]
	v_pk_add_f32 v[28:29], v[16:17], v[32:33]
	v_pk_add_f32 v[16:17], v[16:17], v[32:33] neg_lo:[0,1] neg_hi:[0,1]
	v_xor_b32_e32 v39, 0x80000000, v40
	v_pk_mul_f32 v[42:43], v[40:41], v[40:41] op_sel_hi:[1,0] neg_lo:[0,1] neg_hi:[0,1]
	v_xor_b32_e32 v33, 0x80000000, v16
	v_mov_b32_e32 v32, v17
	s_waitcnt lgkmcnt(0)
	v_pk_add_f32 v[16:17], v[20:21], v[36:37]
	v_pk_add_f32 v[20:21], v[20:21], v[36:37] neg_lo:[0,1] neg_hi:[0,1]
	v_pk_fma_f32 v[42:43], v[38:39], v[38:39], v[42:43] op_sel_hi:[1,0,1]
	v_mul_f32_e32 v36, 0xbf3504f3, v20
	v_xor_b32_e32 v46, 0x80000000, v43
	v_mov_b32_e32 v47, v42
	v_pk_fma_f32 v[20:21], v[20:21], s[56:57], v[36:37] op_sel:[1,0,0] op_sel_hi:[1,1,0]
	v_pk_add_f32 v[36:37], v[84:85], v[28:29]
	v_pk_add_f32 v[28:29], v[84:85], v[28:29] neg_lo:[0,1] neg_hi:[0,1]
	v_pk_add_f32 v[84:85], v[24:25], v[16:17]
	v_pk_add_f32 v[16:17], v[24:25], v[16:17] neg_lo:[0,1] neg_hi:[0,1]
	v_pk_mul_f32 v[44:45], v[40:41], v[42:43] op_sel:[0,1]
	v_pk_mul_f32 v[48:49], v[42:43], v[46:47] op_sel:[1,0]
	v_xor_b32_e32 v25, 0x80000000, v16
	v_mov_b32_e32 v24, v17
	v_pk_add_f32 v[16:17], v[8:9], v[32:33]
	v_pk_add_f32 v[8:9], v[8:9], v[32:33] neg_lo:[0,1] neg_hi:[0,1]
	v_pk_add_f32 v[32:33], v[12:13], v[20:21]
	v_pk_add_f32 v[12:13], v[12:13], v[20:21] neg_lo:[0,1] neg_hi:[0,1]
	v_pk_fma_f32 v[44:45], v[38:39], v[42:43], v[44:45] op_sel_hi:[1,0,1]
	v_pk_fma_f32 v[48:49], v[42:43], v[42:43], v[48:49] op_sel_hi:[1,0,1]
	v_xor_b32_e32 v21, 0x80000000, v12
	v_mov_b32_e32 v20, v13
	v_pk_add_f32 v[12:13], v[36:37], v[84:85]
	v_pk_add_f32 v[36:37], v[36:37], v[84:85] neg_lo:[0,1] neg_hi:[0,1]
	v_pk_add_f32 v[84:85], v[28:29], v[24:25]
	v_pk_add_f32 v[24:25], v[28:29], v[24:25] neg_lo:[0,1] neg_hi:[0,1]
	v_pk_add_f32 v[28:29], v[16:17], v[32:33]
	v_pk_mul_f32 v[50:51], v[40:41], v[48:49] op_sel:[0,1]
	v_xor_b32_e32 v54, 0x80000000, v45
	v_mov_b32_e32 v55, v44
	v_pk_add_f32 v[16:17], v[16:17], v[32:33] neg_lo:[0,1] neg_hi:[0,1]
	v_pk_add_f32 v[32:33], v[8:9], v[20:21]
	v_pk_add_f32 v[8:9], v[8:9], v[20:21] neg_lo:[0,1] neg_hi:[0,1]
	v_pk_mul_f32 v[20:21], v[40:41], v[28:29] op_sel:[0,1]
	v_pk_fma_f32 v[50:51], v[38:39], v[48:49], v[50:51] op_sel_hi:[1,0,1]
	v_pk_fma_f32 v[20:21], v[38:39], v[28:29], v[20:21] op_sel_hi:[1,0,1]
	v_pk_mul_f32 v[38:39], v[54:55], v[32:33] op_sel:[0,1]
	v_pk_mul_f32 v[52:53], v[46:47], v[48:49] op_sel:[0,1]
	v_pk_fma_f32 v[32:33], v[44:45], v[32:33], v[38:39] op_sel_hi:[1,0,1]
	v_pk_mul_f32 v[38:39], v[48:49], v[36:37] op_sel:[1,1] op_sel_hi:[0,1] neg_lo:[1,0]
	v_pk_fma_f32 v[52:53], v[42:43], v[48:49], v[52:53] op_sel_hi:[1,0,1]
	v_pk_fma_f32 v[36:37], v[48:49], v[36:37], v[38:39] op_sel_hi:[1,0,1]
	v_pk_mul_f32 v[38:39], v[50:51], v[16:17] op_sel:[1,1] op_sel_hi:[0,1] neg_lo:[1,0]
	v_pk_mul_f32 v[82:83], v[48:49], v[54:55] op_sel:[1,0]
	v_pk_fma_f32 v[16:17], v[50:51], v[16:17], v[38:39] op_sel_hi:[1,0,1]
	v_pk_fma_f32 v[82:83], v[44:45], v[48:49], v[82:83] op_sel_hi:[1,0,1]
	v_pk_mul_f32 v[38:39], v[52:53], v[24:25] op_sel:[1,1] op_sel_hi:[0,1] neg_lo:[1,0]
	v_pk_mul_f32 v[28:29], v[46:47], v[84:85] op_sel:[0,1]
	v_pk_fma_f32 v[24:25], v[52:53], v[24:25], v[38:39] op_sel_hi:[1,0,1]
	v_pk_mul_f32 v[38:39], v[82:83], v[8:9] op_sel:[1,1] op_sel_hi:[0,1] neg_lo:[1,0]
	v_add_u32_e32 v0, 0x400, v0
	s_or_b64 s[88:89], vcc, s[88:89]
	v_pk_fma_f32 v[28:29], v[42:43], v[84:85], v[28:29] op_sel_hi:[1,0,1]
	v_pk_fma_f32 v[8:9], v[82:83], v[8:9], v[38:39] op_sel_hi:[1,0,1]
	ds_write_b64 v2, v[10:11]
	ds_write_b64 v4, v[12:13]
	ds_write_b64 v1, v[34:35]
	ds_write_b64 v3, v[36:37]
	ds_write_b64 v2, v[26:27] offset:33024
	ds_write_b64 v4, v[28:29] offset:33024
	ds_write_b64 v87, v[22:23]
	ds_write_b64 v88, v[24:25]
	ds_write_b64 v2, v[18:19] offset:16512
	ds_write_b64 v4, v[20:21] offset:16512
	ds_write_b64 v5, v[14:15]
	ds_write_b64 v86, v[16:17]
	ds_write_b64 v2, v[30:31] offset:49536
	ds_write_b64 v4, v[32:33] offset:49536
	ds_write_b64 v89, v[6:7]
	ds_write_b64 v90, v[8:9]
	s_andn2_b64 exec, exec, s[88:89]
	s_cbranch_execnz .LBB0_288

.LBB0_291:
	v_lshrrev_b32_e32 v0, 3, v66
	v_add_u32_e32 v1, 0x200, v66
	v_and_b32_e32 v0, 0x1ffffff0, v0
	v_lshrrev_b32_e32 v1, 3, v1
	v_and_b32_e32 v1, 0x1ffffff0, v1
	v_mad_u64_u32 v[82:83], s[40:41], v0, s25, v[60:61]
	v_mov_b32_e32 v86, v65
	v_mov_b32_e32 v140, v65
	v_mad_u64_u32 v[84:85], s[40:41], v1, s25, v[60:61]
	v_add_u32_e32 v16, 0x2000, v82
	ds_read2_b64 v[134:137], v82 offset1:129
	ds_read2_b64 v[12:15], v84 offset1:129
	ds_read2_b64 v[142:145], v16 offset0:8 offset1:137
	v_add_u32_e32 v16, 0x2000, v84
	v_add_u32_e32 v0, 0x800, v82
	ds_read2_b64 v[28:31], v16 offset0:8 offset1:137
	v_add_u32_e32 v16, 0x2800, v82
	ds_read2_b64 v[48:51], v0 offset0:2 offset1:131
	ds_read2_b64 v[52:55], v16 offset0:10 offset1:139
	v_add_u32_e32 v0, 0x800, v84
	v_add_u32_e32 v16, 0x2800, v84
	ds_read2_b64 v[8:11], v0 offset0:2 offset1:131
	v_add_u32_e32 v0, 0x1000, v82
	ds_read2_b64 v[24:27], v16 offset0:10 offset1:139
	v_add_u32_e32 v16, 0x3000, v82
	s_waitcnt lgkmcnt(5)
	v_pk_add_f32 v[132:133], v[134:135], v[142:143]
	v_pk_add_f32 v[130:131], v[134:135], v[142:143] neg_lo:[0,1] neg_hi:[0,1]
	v_pk_add_f32 v[134:135], v[136:137], v[144:145]
	v_pk_add_f32 v[136:137], v[136:137], v[144:145] neg_lo:[0,1] neg_hi:[0,1]
	ds_read2_b64 v[40:43], v0 offset0:4 offset1:133
	ds_read2_b64 v[44:47], v16 offset0:12 offset1:141
	v_pk_mul_f32 v[138:139], v[136:137], s[42:43] op_sel_hi:[0,1]
	s_mov_b32 s65, s42
	v_add_u32_e32 v0, 0x1000, v84
	v_add_u32_e32 v16, 0x3000, v84
	v_pk_fma_f32 v[136:137], v[136:137], s[64:65], v[138:139] op_sel:[1,0,0]
	s_waitcnt lgkmcnt(4)
	v_pk_add_f32 v[138:139], v[48:49], v[52:53]
	v_pk_add_f32 v[48:49], v[48:49], v[52:53] neg_lo:[0,1] neg_hi:[0,1]
	ds_read2_b64 v[4:7], v0 offset0:4 offset1:133
	v_add_u32_e32 v0, 0x1800, v82
	ds_read2_b64 v[20:23], v16 offset0:12 offset1:141
	v_add_u32_e32 v16, 0x3800, v82
	v_mul_f32_e32 v52, 0x3f3504f3, v49
	ds_read2_b64 v[32:35], v0 offset0:6 offset1:135
	ds_read2_b64 v[36:39], v16 offset0:14 offset1:143
	v_pk_fma_f32 v[48:49], v[48:49], s[56:57], v[52:53] op_sel_hi:[0,1,0]
	v_pk_add_f32 v[52:53], v[50:51], v[54:55]
	v_pk_add_f32 v[50:51], v[50:51], v[54:55] neg_lo:[0,1] neg_hi:[0,1]
	s_mov_b32 s66, s64
	v_pk_mul_f32 v[54:55], v[50:51], s[66:67] op_sel_hi:[0,1]
	s_mov_b32 s44, s42
	s_mov_b32 s45, s64
	v_cvt_f32_i32_e32 v83, v86
	v_pk_fma_f32 v[50:51], v[50:51], s[44:45], v[54:55] op_sel:[1,0,0]
	s_waitcnt lgkmcnt(4)
	v_pk_add_f32 v[54:55], v[40:41], v[44:45]
	v_pk_add_f32 v[40:41], v[40:41], v[44:45] neg_lo:[0,1] neg_hi:[0,1]
	s_mov_b32 s58, s43
	v_xor_b32_e32 v45, 0x80000000, v40
	v_mov_b32_e32 v44, v41
	v_pk_add_f32 v[40:41], v[42:43], v[46:47]
	v_pk_add_f32 v[42:43], v[42:43], v[46:47] neg_lo:[0,1] neg_hi:[0,1]
	s_mov_b32 s59, s67
	v_pk_mul_f32 v[46:47], v[42:43], s[58:59] op_sel_hi:[0,1]
	v_pk_fma_f32 v[42:43], v[42:43], s[42:43], v[46:47] op_sel:[1,0,0]
	s_waitcnt lgkmcnt(0)
	v_pk_add_f32 v[46:47], v[32:33], v[36:37]
	v_pk_add_f32 v[32:33], v[32:33], v[36:37] neg_lo:[0,1] neg_hi:[0,1]
	v_mul_f32_e32 v83, 0x3a000000, v83
	v_mul_f32_e32 v36, 0xbf3504f3, v32
	v_cos_f32_e32 v94, v83
	v_pk_fma_f32 v[32:33], v[32:33], s[56:57], v[36:37] op_sel:[1,0,0] op_sel_hi:[1,1,0]
	v_pk_add_f32 v[36:37], v[34:35], v[38:39]
	v_pk_add_f32 v[34:35], v[34:35], v[38:39] neg_lo:[0,1] neg_hi:[0,1]
	s_mov_b32 s40, s67
	s_mov_b32 s41, s43
	v_sin_f32_e32 v98, v83
	v_pk_mul_f32 v[38:39], v[34:35], s[40:41] op_sel_hi:[0,1]
	v_pk_fma_f32 v[34:35], v[34:35], s[66:67], v[38:39] op_sel:[1,0,0]
	v_pk_add_f32 v[38:39], v[132:133], v[54:55]
	v_pk_add_f32 v[54:55], v[132:133], v[54:55] neg_lo:[0,1] neg_hi:[0,1]
	v_pk_add_f32 v[132:133], v[134:135], v[40:41]
	v_pk_add_f32 v[40:41], v[134:135], v[40:41] neg_lo:[0,1] neg_hi:[0,1]
	v_mov_b32_e32 v99, v94
	v_mul_f32_e32 v134, 0x3f3504f3, v41
	v_pk_fma_f32 v[40:41], v[40:41], s[56:57], v[134:135] op_sel_hi:[0,1,0]
	v_pk_add_f32 v[134:135], v[138:139], v[46:47]
	v_pk_add_f32 v[46:47], v[138:139], v[46:47] neg_lo:[0,1] neg_hi:[0,1]
	v_xor_b32_e32 v95, 0x80000000, v98
	v_pk_mul_f32 v[86:87], v[98:99], v[98:99] op_sel_hi:[1,0] neg_lo:[0,1] neg_hi:[0,1]
	v_xor_b32_e32 v139, 0x80000000, v46
	v_mov_b32_e32 v138, v47
	v_pk_add_f32 v[46:47], v[52:53], v[36:37]
	v_pk_add_f32 v[36:37], v[52:53], v[36:37] neg_lo:[0,1] neg_hi:[0,1]
	v_pk_fma_f32 v[100:101], v[94:95], v[94:95], v[86:87] op_sel_hi:[1,0,1]
	v_mul_f32_e32 v52, 0xbf3504f3, v36
	v_pk_mul_f32 v[86:87], v[98:99], v[100:101] op_sel:[0,1]
	v_pk_fma_f32 v[36:37], v[36:37], s[56:57], v[52:53] op_sel:[1,0,0] op_sel_hi:[1,1,0]
	v_pk_add_f32 v[52:53], v[130:131], v[44:45]
	v_pk_add_f32 v[44:45], v[130:131], v[44:45] neg_lo:[0,1] neg_hi:[0,1]
	v_pk_add_f32 v[130:131], v[136:137], v[42:43]
	v_pk_add_f32 v[42:43], v[136:137], v[42:43] neg_lo:[0,1] neg_hi:[0,1]
	v_pk_fma_f32 v[102:103], v[94:95], v[100:101], v[86:87] op_sel_hi:[1,0,1]
	v_pk_mul_f32 v[86:87], v[100:101], v[100:101] op_sel:[1,1] op_sel_hi:[1,0] neg_lo:[0,1]
	v_mul_f32_e32 v136, 0x3f3504f3, v43
	v_pk_fma_f32 v[106:107], v[100:101], v[100:101], v[86:87] op_sel_hi:[1,0,1]
	v_pk_fma_f32 v[42:43], v[42:43], s[56:57], v[136:137] op_sel_hi:[0,1,0]
	v_pk_add_f32 v[136:137], v[48:49], v[32:33]
	v_pk_add_f32 v[32:33], v[48:49], v[32:33] neg_lo:[0,1] neg_hi:[0,1]
	v_pk_mul_f32 v[86:87], v[98:99], v[106:107] op_sel:[0,1]
	v_xor_b32_e32 v49, 0x80000000, v32
	v_mov_b32_e32 v48, v33
	v_pk_add_f32 v[32:33], v[50:51], v[34:35]
	v_pk_add_f32 v[34:35], v[50:51], v[34:35] neg_lo:[0,1] neg_hi:[0,1]
	v_pk_fma_f32 v[108:109], v[94:95], v[106:107], v[86:87] op_sel_hi:[1,0,1]
	v_pk_mul_f32 v[86:87], v[100:101], v[106:107] op_sel:[1,1] op_sel_hi:[0,1] neg_lo:[1,0]
	v_mul_f32_e32 v50, 0xbf3504f3, v34
	v_pk_fma_f32 v[110:111], v[100:101], v[106:107], v[86:87] op_sel_hi:[1,0,1]
	v_pk_mul_f32 v[86:87], v[106:107], v[102:103] op_sel:[1,1] op_sel_hi:[1,0] neg_lo:[0,1]
	v_pk_fma_f32 v[34:35], v[34:35], s[56:57], v[50:51] op_sel:[1,0,0] op_sel_hi:[1,1,0]
	v_pk_add_f32 v[50:51], v[38:39], v[134:135]
	v_pk_add_f32 v[38:39], v[38:39], v[134:135] neg_lo:[0,1] neg_hi:[0,1]
	v_pk_add_f32 v[134:135], v[132:133], v[46:47]
	v_pk_add_f32 v[46:47], v[132:133], v[46:47] neg_lo:[0,1] neg_hi:[0,1]
	v_pk_fma_f32 v[114:115], v[102:103], v[106:107], v[86:87] op_sel_hi:[1,0,1]
	v_pk_mul_f32 v[86:87], v[106:107], v[106:107] op_sel:[1,1] op_sel_hi:[1,0] neg_lo:[0,1]
	v_xor_b32_e32 v133, 0x80000000, v46
	v_mov_b32_e32 v132, v47
	v_pk_add_f32 v[46:47], v[54:55], v[138:139]
	v_pk_add_f32 v[54:55], v[54:55], v[138:139] neg_lo:[0,1] neg_hi:[0,1]
	v_pk_add_f32 v[138:139], v[40:41], v[36:37]
	v_pk_add_f32 v[36:37], v[40:41], v[36:37] neg_lo:[0,1] neg_hi:[0,1]
	v_pk_fma_f32 v[116:117], v[106:107], v[106:107], v[86:87] op_sel_hi:[1,0,1]
	v_xor_b32_e32 v41, 0x80000000, v36
	v_mov_b32_e32 v40, v37
	v_pk_add_f32 v[36:37], v[52:53], v[136:137]
	v_pk_add_f32 v[52:53], v[52:53], v[136:137] neg_lo:[0,1] neg_hi:[0,1]
	v_pk_add_f32 v[136:137], v[130:131], v[32:33]
	v_pk_add_f32 v[32:33], v[130:131], v[32:33] neg_lo:[0,1] neg_hi:[0,1]
	v_pk_mul_f32 v[86:87], v[98:99], v[116:117] op_sel:[0,1]
	v_xor_b32_e32 v131, 0x80000000, v32
	v_mov_b32_e32 v130, v33
	v_pk_add_f32 v[32:33], v[44:45], v[48:49]
	v_pk_add_f32 v[44:45], v[44:45], v[48:49] neg_lo:[0,1] neg_hi:[0,1]
	v_pk_add_f32 v[48:49], v[42:43], v[34:35]
	v_pk_add_f32 v[34:35], v[42:43], v[34:35] neg_lo:[0,1] neg_hi:[0,1]
	v_pk_fma_f32 v[112:113], v[94:95], v[116:117], v[86:87] op_sel_hi:[1,0,1]
	v_pk_mul_f32 v[86:87], v[100:101], v[116:117] op_sel:[1,1] op_sel_hi:[0,1] neg_lo:[1,0]
	v_xor_b32_e32 v43, 0x80000000, v34
	v_mov_b32_e32 v42, v35
	v_pk_add_f32 v[34:35], v[50:51], v[134:135]
	v_pk_add_f32 v[50:51], v[50:51], v[134:135] neg_lo:[0,1] neg_hi:[0,1]
	v_pk_add_f32 v[134:135], v[38:39], v[132:133]
	v_pk_add_f32 v[38:39], v[38:39], v[132:133] neg_lo:[0,1] neg_hi:[0,1]
	v_pk_add_f32 v[132:133], v[46:47], v[138:139]
	v_pk_add_f32 v[46:47], v[46:47], v[138:139] neg_lo:[0,1] neg_hi:[0,1]
	v_pk_add_f32 v[138:139], v[54:55], v[40:41]
	v_pk_add_f32 v[40:41], v[54:55], v[40:41] neg_lo:[0,1] neg_hi:[0,1]
	v_pk_add_f32 v[54:55], v[36:37], v[136:137]
	v_pk_fma_f32 v[104:105], v[100:101], v[116:117], v[86:87] op_sel_hi:[1,0,1]
	v_pk_mul_f32 v[86:87], v[102:103], v[116:117] op_sel:[1,1] op_sel_hi:[0,1] neg_lo:[1,0]
	v_pk_add_f32 v[36:37], v[36:37], v[136:137] neg_lo:[0,1] neg_hi:[0,1]
	v_pk_add_f32 v[136:137], v[52:53], v[130:131]
	v_pk_add_f32 v[52:53], v[52:53], v[130:131] neg_lo:[0,1] neg_hi:[0,1]
	v_pk_add_f32 v[130:131], v[32:33], v[48:49]
	v_pk_add_f32 v[48:49], v[32:33], v[48:49] neg_lo:[0,1] neg_hi:[0,1]
	v_pk_mul_f32 v[32:33], v[98:99], v[54:55] op_sel:[0,1]
	v_pk_fma_f32 v[96:97], v[102:103], v[116:117], v[86:87] op_sel_hi:[1,0,1]
	v_pk_mul_f32 v[86:87], v[106:107], v[116:117] op_sel:[1,1] op_sel_hi:[0,1] neg_lo:[1,0]
	v_pk_add_f32 v[142:143], v[44:45], v[42:43]
	v_pk_add_f32 v[42:43], v[44:45], v[42:43] neg_lo:[0,1] neg_hi:[0,1]
	v_pk_fma_f32 v[44:45], v[94:95], v[54:55], v[32:33] op_sel_hi:[1,0,1]
	v_pk_mul_f32 v[32:33], v[100:101], v[132:133] op_sel:[1,1] op_sel_hi:[0,1] neg_lo:[1,0]
	v_pk_mul_f32 v[94:95], v[106:107], v[134:135] op_sel:[1,1] op_sel_hi:[0,1] neg_lo:[1,0]
	v_pk_fma_f32 v[86:87], v[106:107], v[116:117], v[86:87] op_sel_hi:[1,0,1]
	v_pk_fma_f32 v[54:55], v[100:101], v[132:133], v[32:33] op_sel_hi:[1,0,1]
	v_pk_fma_f32 v[94:95], v[106:107], v[134:135], v[94:95] op_sel_hi:[1,0,1]
	v_pk_mul_f32 v[100:101], v[110:111], v[138:139] op_sel:[1,1] op_sel_hi:[0,1] neg_lo:[1,0]
	v_pk_fma_f32 v[100:101], v[110:111], v[138:139], v[100:101] op_sel_hi:[1,0,1]
	v_pk_mul_f32 v[106:107], v[116:117], v[50:51] op_sel:[1,1] op_sel_hi:[0,1] neg_lo:[1,0]
	v_pk_add_f32 v[138:139], v[12:13], v[28:29]
	v_pk_add_f32 v[12:13], v[12:13], v[28:29] neg_lo:[0,1] neg_hi:[0,1]
	v_pk_add_f32 v[28:29], v[14:15], v[30:31]
	v_pk_add_f32 v[14:15], v[14:15], v[30:31] neg_lo:[0,1] neg_hi:[0,1]
	v_pk_fma_f32 v[50:51], v[116:117], v[50:51], v[106:107] op_sel_hi:[1,0,1]
	v_pk_mul_f32 v[30:31], v[14:15], s[42:43] op_sel_hi:[0,1]
	v_pk_mul_f32 v[106:107], v[112:113], v[36:37] op_sel:[1,1] op_sel_hi:[0,1] neg_lo:[1,0]
	v_pk_fma_f32 v[14:15], v[14:15], s[64:65], v[30:31] op_sel:[1,0,0]
	v_pk_add_f32 v[30:31], v[8:9], v[24:25]
	v_pk_add_f32 v[8:9], v[8:9], v[24:25] neg_lo:[0,1] neg_hi:[0,1]
	v_add_u32_e32 v0, 0x1800, v84
	v_add_u32_e32 v16, 0x3800, v84
	v_pk_fma_f32 v[36:37], v[112:113], v[36:37], v[106:107] op_sel_hi:[1,0,1]
	v_mul_f32_e32 v24, 0x3f3504f3, v9
	ds_read2_b64 v[0:3], v0 offset0:6 offset1:135
	ds_read2_b64 v[16:19], v16 offset0:14 offset1:143
	v_pk_mul_f32 v[106:107], v[104:105], v[46:47] op_sel:[1,1] op_sel_hi:[0,1] neg_lo:[1,0]
	v_pk_fma_f32 v[8:9], v[8:9], s[56:57], v[24:25] op_sel_hi:[0,1,0]
	v_pk_add_f32 v[24:25], v[10:11], v[26:27]
	v_pk_add_f32 v[10:11], v[10:11], v[26:27] neg_lo:[0,1] neg_hi:[0,1]
	v_pk_fma_f32 v[46:47], v[104:105], v[46:47], v[106:107] op_sel_hi:[1,0,1]
	v_pk_mul_f32 v[26:27], v[10:11], s[66:67] op_sel_hi:[0,1]
	v_pk_mul_f32 v[104:105], v[96:97], v[48:49] op_sel:[1,1] op_sel_hi:[0,1] neg_lo:[1,0]
	v_pk_fma_f32 v[10:11], v[10:11], s[44:45], v[26:27] op_sel:[1,0,0]
	v_pk_add_f32 v[26:27], v[4:5], v[20:21]
	v_pk_add_f32 v[4:5], v[4:5], v[20:21] neg_lo:[0,1] neg_hi:[0,1]
	v_pk_mul_f32 v[88:89], v[116:117], v[108:109] op_sel:[1,1] op_sel_hi:[1,0] neg_lo:[0,1]
	v_pk_fma_f32 v[48:49], v[96:97], v[48:49], v[104:105] op_sel_hi:[1,0,1]
	v_xor_b32_e32 v21, 0x80000000, v4
	v_mov_b32_e32 v20, v5
	v_pk_add_f32 v[4:5], v[6:7], v[22:23]
	v_pk_add_f32 v[6:7], v[6:7], v[22:23] neg_lo:[0,1] neg_hi:[0,1]
	v_pk_fma_f32 v[88:89], v[108:109], v[116:117], v[88:89] op_sel_hi:[1,0,1]
	v_pk_mul_f32 v[96:97], v[86:87], v[38:39] op_sel:[1,1] op_sel_hi:[0,1] neg_lo:[1,0]
	v_pk_mul_f32 v[22:23], v[6:7], s[58:59] op_sel_hi:[0,1]
	v_pk_mul_f32 v[90:91], v[116:117], v[110:111] op_sel:[1,1] op_sel_hi:[1,0] neg_lo:[0,1]
	v_pk_fma_f32 v[38:39], v[86:87], v[38:39], v[96:97] op_sel_hi:[1,0,1]
	v_pk_fma_f32 v[6:7], v[6:7], s[42:43], v[22:23] op_sel:[1,0,0]
	s_waitcnt lgkmcnt(0)
	v_pk_add_f32 v[22:23], v[0:1], v[16:17]
	v_pk_add_f32 v[0:1], v[0:1], v[16:17] neg_lo:[0,1] neg_hi:[0,1]
	v_pk_fma_f32 v[90:91], v[110:111], v[116:117], v[90:91] op_sel_hi:[1,0,1]
	v_pk_mul_f32 v[86:87], v[88:89], v[52:53] op_sel:[1,1] op_sel_hi:[0,1] neg_lo:[1,0]
	v_cvt_f32_i32_e32 v83, v140
	v_mul_f32_e32 v16, 0xbf3504f3, v0
	v_pk_mul_f32 v[92:93], v[116:117], v[114:115] op_sel:[1,1] op_sel_hi:[1,0] neg_lo:[0,1]
	v_pk_fma_f32 v[52:53], v[88:89], v[52:53], v[86:87] op_sel_hi:[1,0,1]
	v_pk_fma_f32 v[0:1], v[0:1], s[56:57], v[16:17] op_sel:[1,0,0] op_sel_hi:[1,1,0]
	v_pk_add_f32 v[16:17], v[2:3], v[18:19]
	v_pk_add_f32 v[2:3], v[2:3], v[18:19] neg_lo:[0,1] neg_hi:[0,1]
	v_pk_fma_f32 v[92:93], v[114:115], v[116:117], v[92:93] op_sel_hi:[1,0,1]
	v_pk_mul_f32 v[86:87], v[90:91], v[40:41] op_sel:[1,1] op_sel_hi:[0,1] neg_lo:[1,0]
	v_pk_mul_f32 v[18:19], v[2:3], s[40:41] op_sel_hi:[0,1]
	v_pk_fma_f32 v[40:41], v[90:91], v[40:41], v[86:87] op_sel_hi:[1,0,1]
	v_pk_fma_f32 v[2:3], v[2:3], s[66:67], v[18:19] op_sel:[1,0,0]
	v_pk_add_f32 v[18:19], v[138:139], v[26:27]
	v_pk_add_f32 v[26:27], v[138:139], v[26:27] neg_lo:[0,1] neg_hi:[0,1]
	v_pk_add_f32 v[138:139], v[28:29], v[4:5]
	v_pk_add_f32 v[4:5], v[28:29], v[4:5] neg_lo:[0,1] neg_hi:[0,1]
	v_pk_mul_f32 v[86:87], v[92:93], v[42:43] op_sel:[1,1] op_sel_hi:[0,1] neg_lo:[1,0]
	v_mul_f32_e32 v83, 0x3a000000, v83
	v_mul_f32_e32 v28, 0x3f3504f3, v5
	v_pk_fma_f32 v[42:43], v[92:93], v[42:43], v[86:87] op_sel_hi:[1,0,1]
	v_cos_f32_e32 v86, v83
	v_pk_fma_f32 v[4:5], v[4:5], s[56:57], v[28:29] op_sel_hi:[0,1,0]
	v_pk_add_f32 v[28:29], v[30:31], v[22:23]
	v_pk_add_f32 v[22:23], v[30:31], v[22:23] neg_lo:[0,1] neg_hi:[0,1]
	v_sin_f32_e32 v88, v83
	v_xor_b32_e32 v31, 0x80000000, v22
	v_mov_b32_e32 v30, v23
	v_pk_add_f32 v[22:23], v[24:25], v[16:17]
	v_pk_add_f32 v[16:17], v[24:25], v[16:17] neg_lo:[0,1] neg_hi:[0,1]
	v_mov_b32_e32 v89, v86
	v_mul_f32_e32 v24, 0xbf3504f3, v16
	v_pk_fma_f32 v[16:17], v[16:17], s[56:57], v[24:25] op_sel:[1,0,0] op_sel_hi:[1,1,0]
	v_pk_add_f32 v[24:25], v[12:13], v[20:21]
	v_pk_add_f32 v[12:13], v[12:13], v[20:21] neg_lo:[0,1] neg_hi:[0,1]
	v_pk_add_f32 v[20:21], v[14:15], v[6:7]
	v_pk_add_f32 v[6:7], v[14:15], v[6:7] neg_lo:[0,1] neg_hi:[0,1]
	v_xor_b32_e32 v87, 0x80000000, v88
	v_mul_f32_e32 v14, 0x3f3504f3, v7
	v_pk_mul_f32 v[90:91], v[88:89], v[88:89] op_sel_hi:[1,0] neg_lo:[0,1] neg_hi:[0,1]
	v_pk_fma_f32 v[6:7], v[6:7], s[56:57], v[14:15] op_sel_hi:[0,1,0]
	v_pk_add_f32 v[14:15], v[8:9], v[0:1]
	v_pk_add_f32 v[0:1], v[8:9], v[0:1] neg_lo:[0,1] neg_hi:[0,1]
	v_pk_fma_f32 v[90:91], v[86:87], v[86:87], v[90:91] op_sel_hi:[1,0,1]
	v_xor_b32_e32 v9, 0x80000000, v0
	v_mov_b32_e32 v8, v1
	v_pk_add_f32 v[0:1], v[10:11], v[2:3]
	v_pk_add_f32 v[2:3], v[10:11], v[2:3] neg_lo:[0,1] neg_hi:[0,1]
	v_xor_b32_e32 v96, 0x80000000, v91
	v_mov_b32_e32 v97, v90
	v_mul_f32_e32 v10, 0xbf3504f3, v2
	v_pk_mul_f32 v[32:33], v[102:103], v[130:131] op_sel:[1,1] op_sel_hi:[0,1] neg_lo:[1,0]
	v_pk_mul_f32 v[104:105], v[90:91], v[96:97] op_sel:[1,0]
	v_pk_fma_f32 v[2:3], v[2:3], s[56:57], v[10:11] op_sel:[1,0,0] op_sel_hi:[1,1,0]
	v_pk_add_f32 v[10:11], v[18:19], v[28:29]
	v_pk_add_f32 v[18:19], v[18:19], v[28:29] neg_lo:[0,1] neg_hi:[0,1]
	v_pk_add_f32 v[28:29], v[138:139], v[22:23]
	v_pk_add_f32 v[22:23], v[138:139], v[22:23] neg_lo:[0,1] neg_hi:[0,1]
	v_pk_fma_f32 v[32:33], v[102:103], v[130:131], v[32:33] op_sel_hi:[1,0,1]
	v_pk_mul_f32 v[102:103], v[114:115], v[142:143] op_sel:[1,1] op_sel_hi:[0,1] neg_lo:[1,0]
	v_pk_fma_f32 v[104:105], v[90:91], v[90:91], v[104:105] op_sel_hi:[1,0,1]
	v_xor_b32_e32 v139, 0x80000000, v22
	v_mov_b32_e32 v138, v23
	v_pk_add_f32 v[22:23], v[26:27], v[30:31]
	v_pk_add_f32 v[26:27], v[26:27], v[30:31] neg_lo:[0,1] neg_hi:[0,1]
	v_pk_add_f32 v[30:31], v[4:5], v[16:17]
	v_pk_add_f32 v[4:5], v[4:5], v[16:17] neg_lo:[0,1] neg_hi:[0,1]
	v_pk_fma_f32 v[102:103], v[114:115], v[142:143], v[102:103] op_sel_hi:[1,0,1]
	v_xor_b32_e32 v114, 0x80000000, v105
	v_mov_b32_e32 v115, v104
	v_xor_b32_e32 v17, 0x80000000, v4
	v_mov_b32_e32 v16, v5
	v_pk_add_f32 v[4:5], v[24:25], v[14:15]
	v_pk_add_f32 v[14:15], v[24:25], v[14:15] neg_lo:[0,1] neg_hi:[0,1]
	v_pk_add_f32 v[24:25], v[20:21], v[0:1]
	v_pk_add_f32 v[0:1], v[20:21], v[0:1] neg_lo:[0,1] neg_hi:[0,1]
	v_pk_mul_f32 v[92:93], v[88:89], v[90:91] op_sel:[0,1]
	v_pk_mul_f32 v[116:117], v[104:105], v[114:115] op_sel:[1,0]
	v_xor_b32_e32 v21, 0x80000000, v0
	v_mov_b32_e32 v20, v1
	v_pk_add_f32 v[0:1], v[12:13], v[8:9]
	v_pk_add_f32 v[8:9], v[12:13], v[8:9] neg_lo:[0,1] neg_hi:[0,1]
	v_pk_add_f32 v[12:13], v[6:7], v[2:3]
	v_pk_add_f32 v[2:3], v[6:7], v[2:3] neg_lo:[0,1] neg_hi:[0,1]
	v_pk_fma_f32 v[92:93], v[86:87], v[90:91], v[92:93] op_sel_hi:[1,0,1]
	v_pk_fma_f32 v[116:117], v[104:105], v[104:105], v[116:117] op_sel_hi:[1,0,1]
	v_xor_b32_e32 v7, 0x80000000, v2
	v_mov_b32_e32 v6, v3
	v_pk_add_f32 v[2:3], v[10:11], v[28:29]
	v_pk_add_f32 v[10:11], v[10:11], v[28:29] neg_lo:[0,1] neg_hi:[0,1]
	v_pk_add_f32 v[28:29], v[18:19], v[138:139]
	v_pk_add_f32 v[18:19], v[18:19], v[138:139] neg_lo:[0,1] neg_hi:[0,1]
	v_pk_add_f32 v[138:139], v[22:23], v[30:31]
	v_pk_add_f32 v[22:23], v[22:23], v[30:31] neg_lo:[0,1] neg_hi:[0,1]
	v_pk_add_f32 v[30:31], v[26:27], v[16:17]
	v_pk_add_f32 v[16:17], v[26:27], v[16:17] neg_lo:[0,1] neg_hi:[0,1]
	v_pk_add_f32 v[26:27], v[4:5], v[24:25]
	v_pk_mul_f32 v[98:99], v[108:109], v[136:137] op_sel:[1,1] op_sel_hi:[0,1] neg_lo:[1,0]
	v_pk_mul_f32 v[106:107], v[88:89], v[104:105] op_sel:[0,1]
	v_xor_b32_e32 v110, 0x80000000, v93
	v_mov_b32_e32 v111, v92
	v_pk_mul_f32 v[118:119], v[88:89], v[116:117] op_sel:[0,1]
	v_pk_add_f32 v[4:5], v[4:5], v[24:25] neg_lo:[0,1] neg_hi:[0,1]
	v_pk_add_f32 v[24:25], v[14:15], v[20:21]
	v_pk_add_f32 v[14:15], v[14:15], v[20:21] neg_lo:[0,1] neg_hi:[0,1]
	v_pk_add_f32 v[20:21], v[0:1], v[12:13]
	v_pk_add_f32 v[0:1], v[0:1], v[12:13] neg_lo:[0,1] neg_hi:[0,1]
	v_pk_add_f32 v[12:13], v[8:9], v[6:7]
	v_pk_add_f32 v[6:7], v[8:9], v[6:7] neg_lo:[0,1] neg_hi:[0,1]
	v_pk_mul_f32 v[8:9], v[88:89], v[26:27] op_sel:[0,1]
	v_pk_fma_f32 v[98:99], v[108:109], v[136:137], v[98:99] op_sel_hi:[1,0,1]
	v_pk_fma_f32 v[106:107], v[86:87], v[104:105], v[106:107] op_sel_hi:[1,0,1]
	v_pk_mul_f32 v[108:109], v[96:97], v[104:105] op_sel:[0,1]
	v_pk_fma_f32 v[118:119], v[86:87], v[116:117], v[118:119] op_sel_hi:[1,0,1]
	v_pk_fma_f32 v[8:9], v[86:87], v[26:27], v[8:9] op_sel_hi:[1,0,1]
	v_pk_mul_f32 v[86:87], v[110:111], v[20:21] op_sel:[0,1]
	v_pk_fma_f32 v[108:109], v[90:91], v[104:105], v[108:109] op_sel_hi:[1,0,1]
	v_pk_mul_f32 v[112:113], v[104:105], v[110:111] op_sel:[1,0]
	v_xor_b32_e32 v126, 0x80000000, v107
	v_mov_b32_e32 v127, v106
	v_pk_fma_f32 v[20:21], v[92:93], v[20:21], v[86:87] op_sel_hi:[1,0,1]
	v_pk_mul_f32 v[86:87], v[114:115], v[28:29] op_sel:[0,1]
	v_pk_fma_f32 v[112:113], v[92:93], v[104:105], v[112:113] op_sel_hi:[1,0,1]
	v_xor_b32_e32 v130, 0x80000000, v109
	v_mov_b32_e32 v131, v108
	v_pk_fma_f32 v[28:29], v[104:105], v[28:29], v[86:87] op_sel_hi:[1,0,1]
	v_pk_mul_f32 v[86:87], v[126:127], v[24:25] op_sel:[0,1]
	v_xor_b32_e32 v134, 0x80000000, v113
	v_mov_b32_e32 v135, v112
	v_pk_fma_f32 v[24:25], v[106:107], v[24:25], v[86:87] op_sel_hi:[1,0,1]
	v_pk_mul_f32 v[86:87], v[130:131], v[30:31] op_sel:[0,1]
	v_pk_mul_f32 v[120:121], v[96:97], v[116:117] op_sel:[0,1]
	v_pk_fma_f32 v[30:31], v[108:109], v[30:31], v[86:87] op_sel_hi:[1,0,1]
	v_pk_mul_f32 v[86:87], v[134:135], v[12:13] op_sel:[0,1]
	v_pk_fma_f32 v[120:121], v[90:91], v[116:117], v[120:121] op_sel_hi:[1,0,1]
	v_pk_fma_f32 v[12:13], v[112:113], v[12:13], v[86:87] op_sel_hi:[1,0,1]
	v_pk_mul_f32 v[86:87], v[116:117], v[10:11] op_sel:[1,1] op_sel_hi:[0,1] neg_lo:[1,0]
	v_pk_mul_f32 v[122:123], v[110:111], v[116:117] op_sel:[0,1]
	v_pk_fma_f32 v[10:11], v[116:117], v[10:11], v[86:87] op_sel_hi:[1,0,1]
	v_pk_mul_f32 v[86:87], v[118:119], v[4:5] op_sel:[1,1] op_sel_hi:[0,1] neg_lo:[1,0]
	v_pk_fma_f32 v[122:123], v[92:93], v[116:117], v[122:123] op_sel_hi:[1,0,1]
	v_pk_fma_f32 v[4:5], v[118:119], v[4:5], v[86:87] op_sel_hi:[1,0,1]
	v_pk_mul_f32 v[86:87], v[120:121], v[22:23] op_sel:[1,1] op_sel_hi:[0,1] neg_lo:[1,0]
	v_pk_mul_f32 v[124:125], v[114:115], v[116:117] op_sel:[0,1]
	v_pk_fma_f32 v[22:23], v[120:121], v[22:23], v[86:87] op_sel_hi:[1,0,1]
	v_pk_fma_f32 v[124:125], v[104:105], v[116:117], v[124:125] op_sel_hi:[1,0,1]
	v_pk_mul_f32 v[86:87], v[122:123], v[0:1] op_sel:[1,1] op_sel_hi:[0,1] neg_lo:[1,0]
	v_pk_mul_f32 v[128:129], v[116:117], v[126:127] op_sel:[1,0]
	v_pk_fma_f32 v[0:1], v[122:123], v[0:1], v[86:87] op_sel_hi:[1,0,1]
	v_pk_fma_f32 v[128:129], v[106:107], v[116:117], v[128:129] op_sel_hi:[1,0,1]
	v_pk_mul_f32 v[86:87], v[124:125], v[18:19] op_sel:[1,1] op_sel_hi:[0,1] neg_lo:[1,0]
	v_pk_mul_f32 v[132:133], v[116:117], v[130:131] op_sel:[1,0]
	v_pk_fma_f32 v[18:19], v[124:125], v[18:19], v[86:87] op_sel_hi:[1,0,1]
	v_pk_fma_f32 v[132:133], v[108:109], v[116:117], v[132:133] op_sel_hi:[1,0,1]
	v_pk_mul_f32 v[86:87], v[128:129], v[14:15] op_sel:[1,1] op_sel_hi:[0,1] neg_lo:[1,0]
	v_pk_mul_f32 v[136:137], v[116:117], v[134:135] op_sel:[1,0]
	v_pk_fma_f32 v[14:15], v[128:129], v[14:15], v[86:87] op_sel_hi:[1,0,1]
	v_pk_fma_f32 v[136:137], v[112:113], v[116:117], v[136:137] op_sel_hi:[1,0,1]
	v_pk_mul_f32 v[86:87], v[132:133], v[16:17] op_sel:[1,1] op_sel_hi:[0,1] neg_lo:[1,0]
	v_cmp_lt_i32_e32 vcc, -1, v66
	v_pk_fma_f32 v[16:17], v[132:133], v[16:17], v[86:87] op_sel_hi:[1,0,1]
	v_pk_mul_f32 v[26:27], v[96:97], v[138:139] op_sel:[0,1]
	v_pk_mul_f32 v[86:87], v[136:137], v[6:7] op_sel:[1,1] op_sel_hi:[0,1] neg_lo:[1,0]
	v_add_u32_e32 v66, 0x400, v66
	s_or_b64 s[88:89], vcc, s[88:89]
	v_pk_fma_f32 v[26:27], v[90:91], v[138:139], v[26:27] op_sel_hi:[1,0,1]
	v_pk_fma_f32 v[6:7], v[136:137], v[6:7], v[86:87] op_sel_hi:[1,0,1]
	ds_write_b64 v82, v[34:35]
	ds_write_b64 v84, v[2:3]
	ds_write_b64 v82, v[50:51] offset:8256
	ds_write_b64 v84, v[10:11] offset:8256
	ds_write_b64 v82, v[94:95] offset:4128
	ds_write_b64 v84, v[28:29] offset:4128
	ds_write_b64 v82, v[38:39] offset:12384
	ds_write_b64 v84, v[18:19] offset:12384
	ds_write_b64 v82, v[54:55] offset:2064
	ds_write_b64 v84, v[26:27] offset:2064
	ds_write_b64 v82, v[46:47] offset:10320
	ds_write_b64 v84, v[22:23] offset:10320
	ds_write_b64 v82, v[100:101] offset:6192
	ds_write_b64 v84, v[30:31] offset:6192
	ds_write_b64 v82, v[40:41] offset:14448
	ds_write_b64 v84, v[16:17] offset:14448
	ds_write_b64 v82, v[44:45] offset:1032
	ds_write_b64 v84, v[8:9] offset:1032
	ds_write_b64 v82, v[36:37] offset:9288
	ds_write_b64 v84, v[4:5] offset:9288
	ds_write_b64 v82, v[98:99] offset:5160
	ds_write_b64 v84, v[24:25] offset:5160
	ds_write_b64 v82, v[52:53] offset:13416
	ds_write_b64 v84, v[14:15] offset:13416
	ds_write_b64 v82, v[32:33] offset:3096
	ds_write_b64 v84, v[20:21] offset:3096
	ds_write_b64 v82, v[48:49] offset:11352
	ds_write_b64 v84, v[0:1] offset:11352
	ds_write_b64 v82, v[102:103] offset:7224
	ds_write_b64 v84, v[12:13] offset:7224
	ds_write_b64 v82, v[42:43] offset:15480
	ds_write_b64 v84, v[6:7] offset:15480
	s_andn2_b64 exec, exec, s[88:89]
	s_cbranch_execnz .LBB0_291

.LBB0_294:
	v_ashrrev_i32_e32 v1, 7, v0
	v_mov_b32_e32 v34, v1
	v_add_u32_e32 v2, 0x200, v0
	v_cvt_f32_i32_e32 v34, v34
	v_ashrrev_i32_e32 v2, 7, v2
	v_mov_b32_e32 v66, v2
	v_lshl_add_u32 v1, v1, 3, v196
	v_mul_f32_e32 v35, 0x3c000000, v34
	v_lshl_add_u32 v82, v2, 3, v196
	ds_read2_b64 v[2:5], v1 offset1:16
	ds_read2_b64 v[6:9], v82 offset1:16
	ds_read2_b64 v[10:13], v1 offset0:32 offset1:48
	ds_read2_b64 v[14:17], v82 offset0:32 offset1:48
	ds_read2_b64 v[18:21], v1 offset0:64 offset1:80
	ds_read2_b64 v[22:25], v82 offset0:64 offset1:80
	ds_read2_b64 v[26:29], v1 offset0:96 offset1:112
	ds_read2_b64 v[30:33], v82 offset0:96 offset1:112
	v_cos_f32_e32 v34, v35
	v_sin_f32_e32 v36, v35
	s_waitcnt lgkmcnt(3)
	v_pk_add_f32 v[54:55], v[2:3], v[18:19]
	v_pk_add_f32 v[2:3], v[2:3], v[18:19] neg_lo:[0,1] neg_hi:[0,1]
	v_pk_add_f32 v[18:19], v[4:5], v[20:21]
	v_pk_add_f32 v[4:5], v[4:5], v[20:21] neg_lo:[0,1] neg_hi:[0,1]
	v_mov_b32_e32 v37, v34
	v_mul_f32_e32 v20, 0x3f3504f3, v5
	v_pk_fma_f32 v[4:5], v[4:5], s[56:57], v[20:21] op_sel_hi:[0,1,0]
	s_waitcnt lgkmcnt(1)
	v_pk_add_f32 v[20:21], v[10:11], v[26:27]
	v_pk_add_f32 v[10:11], v[10:11], v[26:27] neg_lo:[0,1] neg_hi:[0,1]
	v_xor_b32_e32 v35, 0x80000000, v36
	v_pk_mul_f32 v[38:39], v[36:37], v[36:37] op_sel_hi:[1,0] neg_lo:[0,1] neg_hi:[0,1]
	v_xor_b32_e32 v27, 0x80000000, v10
	v_mov_b32_e32 v26, v11
	v_pk_add_f32 v[10:11], v[12:13], v[28:29]
	v_pk_add_f32 v[12:13], v[12:13], v[28:29] neg_lo:[0,1] neg_hi:[0,1]
	v_pk_fma_f32 v[38:39], v[34:35], v[34:35], v[38:39] op_sel_hi:[1,0,1]
	v_mul_f32_e32 v28, 0xbf3504f3, v12
	v_pk_fma_f32 v[12:13], v[12:13], s[56:57], v[28:29] op_sel:[1,0,0] op_sel_hi:[1,1,0]
	v_pk_add_f32 v[28:29], v[54:55], v[20:21]
	v_pk_add_f32 v[20:21], v[54:55], v[20:21] neg_lo:[0,1] neg_hi:[0,1]
	v_pk_add_f32 v[54:55], v[18:19], v[10:11]
	v_pk_add_f32 v[10:11], v[18:19], v[10:11] neg_lo:[0,1] neg_hi:[0,1]
	v_pk_mul_f32 v[40:41], v[36:37], v[38:39] op_sel:[0,1]
	v_pk_mul_f32 v[44:45], v[38:39], v[38:39] op_sel:[1,1] op_sel_hi:[1,0] neg_lo:[0,1]
	v_xor_b32_e32 v19, 0x80000000, v10
	v_mov_b32_e32 v18, v11
	v_pk_add_f32 v[10:11], v[2:3], v[26:27]
	v_pk_add_f32 v[2:3], v[2:3], v[26:27] neg_lo:[0,1] neg_hi:[0,1]
	v_pk_add_f32 v[26:27], v[4:5], v[12:13]
	v_pk_add_f32 v[4:5], v[4:5], v[12:13] neg_lo:[0,1] neg_hi:[0,1]
	v_pk_fma_f32 v[40:41], v[34:35], v[38:39], v[40:41] op_sel_hi:[1,0,1]
	v_pk_fma_f32 v[44:45], v[38:39], v[38:39], v[44:45] op_sel_hi:[1,0,1]
	v_xor_b32_e32 v13, 0x80000000, v4
	v_mov_b32_e32 v12, v5
	v_pk_add_f32 v[4:5], v[28:29], v[54:55]
	v_pk_add_f32 v[28:29], v[28:29], v[54:55] neg_lo:[0,1] neg_hi:[0,1]
	v_pk_add_f32 v[54:55], v[20:21], v[18:19]
	v_pk_add_f32 v[18:19], v[20:21], v[18:19] neg_lo:[0,1] neg_hi:[0,1]
	v_pk_add_f32 v[20:21], v[10:11], v[26:27]
	v_pk_mul_f32 v[46:47], v[36:37], v[44:45] op_sel:[0,1]
	v_pk_add_f32 v[10:11], v[10:11], v[26:27] neg_lo:[0,1] neg_hi:[0,1]
	v_pk_add_f32 v[26:27], v[2:3], v[12:13]
	v_pk_add_f32 v[2:3], v[2:3], v[12:13] neg_lo:[0,1] neg_hi:[0,1]
	v_pk_mul_f32 v[12:13], v[36:37], v[20:21] op_sel:[0,1]
	v_pk_fma_f32 v[46:47], v[34:35], v[44:45], v[46:47] op_sel_hi:[1,0,1]
	v_pk_fma_f32 v[12:13], v[34:35], v[20:21], v[12:13] op_sel_hi:[1,0,1]
	v_pk_mul_f32 v[34:35], v[40:41], v[26:27] op_sel:[1,1] op_sel_hi:[0,1] neg_lo:[1,0]
	v_pk_mul_f32 v[48:49], v[38:39], v[44:45] op_sel:[1,1] op_sel_hi:[0,1] neg_lo:[1,0]
	v_pk_fma_f32 v[26:27], v[40:41], v[26:27], v[34:35] op_sel_hi:[1,0,1]
	v_pk_mul_f32 v[34:35], v[44:45], v[28:29] op_sel:[1,1] op_sel_hi:[0,1] neg_lo:[1,0]
	v_pk_fma_f32 v[48:49], v[38:39], v[44:45], v[48:49] op_sel_hi:[1,0,1]
	v_pk_fma_f32 v[28:29], v[44:45], v[28:29], v[34:35] op_sel_hi:[1,0,1]
	v_pk_mul_f32 v[34:35], v[46:47], v[10:11] op_sel:[1,1] op_sel_hi:[0,1] neg_lo:[1,0]
	v_pk_mul_f32 v[52:53], v[44:45], v[40:41] op_sel:[1,1] op_sel_hi:[1,0] neg_lo:[0,1]
	v_pk_fma_f32 v[10:11], v[46:47], v[10:11], v[34:35] op_sel_hi:[1,0,1]
	v_pk_fma_f32 v[52:53], v[40:41], v[44:45], v[52:53] op_sel_hi:[1,0,1]
	v_pk_mul_f32 v[34:35], v[48:49], v[18:19] op_sel:[1,1] op_sel_hi:[0,1] neg_lo:[1,0]
	v_pk_mul_f32 v[20:21], v[38:39], v[54:55] op_sel:[1,1] op_sel_hi:[0,1] neg_lo:[1,0]
	v_pk_fma_f32 v[18:19], v[48:49], v[18:19], v[34:35] op_sel_hi:[1,0,1]
	v_pk_mul_f32 v[34:35], v[52:53], v[2:3] op_sel:[1,1] op_sel_hi:[0,1] neg_lo:[1,0]
	v_pk_fma_f32 v[20:21], v[38:39], v[54:55], v[20:21] op_sel_hi:[1,0,1]
	v_pk_fma_f32 v[2:3], v[52:53], v[2:3], v[34:35] op_sel_hi:[1,0,1]
	v_cvt_f32_i32_e32 v34, v66
	v_pk_add_f32 v[54:55], v[6:7], v[22:23]
	v_pk_add_f32 v[6:7], v[6:7], v[22:23] neg_lo:[0,1] neg_hi:[0,1]
	v_pk_add_f32 v[22:23], v[8:9], v[24:25]
	v_mul_f32_e32 v35, 0x3c000000, v34
	v_cos_f32_e32 v34, v35
	v_sin_f32_e32 v36, v35
	v_pk_add_f32 v[8:9], v[8:9], v[24:25] neg_lo:[0,1] neg_hi:[0,1]
	v_cmp_lt_i32_e32 vcc, s28, v0
	v_mul_f32_e32 v24, 0x3f3504f3, v9
	v_mov_b32_e32 v37, v34
	v_pk_fma_f32 v[8:9], v[8:9], s[56:57], v[24:25] op_sel_hi:[0,1,0]
	s_waitcnt lgkmcnt(0)
	v_pk_add_f32 v[24:25], v[14:15], v[30:31]
	v_pk_add_f32 v[14:15], v[14:15], v[30:31] neg_lo:[0,1] neg_hi:[0,1]
	v_xor_b32_e32 v35, 0x80000000, v36
	v_pk_mul_f32 v[38:39], v[36:37], v[36:37] op_sel_hi:[1,0] neg_lo:[0,1] neg_hi:[0,1]
	v_xor_b32_e32 v31, 0x80000000, v14
	v_mov_b32_e32 v30, v15
	v_pk_add_f32 v[14:15], v[16:17], v[32:33]
	v_pk_add_f32 v[16:17], v[16:17], v[32:33] neg_lo:[0,1] neg_hi:[0,1]
	v_pk_fma_f32 v[38:39], v[34:35], v[34:35], v[38:39] op_sel_hi:[1,0,1]
	v_mul_f32_e32 v32, 0xbf3504f3, v16
	v_xor_b32_e32 v42, 0x80000000, v39
	v_mov_b32_e32 v43, v38
	v_pk_fma_f32 v[16:17], v[16:17], s[56:57], v[32:33] op_sel:[1,0,0] op_sel_hi:[1,1,0]
	v_pk_add_f32 v[32:33], v[54:55], v[24:25]
	v_pk_add_f32 v[24:25], v[54:55], v[24:25] neg_lo:[0,1] neg_hi:[0,1]
	v_pk_add_f32 v[54:55], v[22:23], v[14:15]
	v_pk_add_f32 v[14:15], v[22:23], v[14:15] neg_lo:[0,1] neg_hi:[0,1]
	v_pk_mul_f32 v[40:41], v[36:37], v[38:39] op_sel:[0,1]
	v_pk_mul_f32 v[44:45], v[38:39], v[42:43] op_sel:[1,0]
	v_xor_b32_e32 v23, 0x80000000, v14
	v_mov_b32_e32 v22, v15
	v_pk_add_f32 v[14:15], v[6:7], v[30:31]
	v_pk_add_f32 v[6:7], v[6:7], v[30:31] neg_lo:[0,1] neg_hi:[0,1]
	v_pk_add_f32 v[30:31], v[8:9], v[16:17]
	v_pk_add_f32 v[8:9], v[8:9], v[16:17] neg_lo:[0,1] neg_hi:[0,1]
	v_pk_fma_f32 v[40:41], v[34:35], v[38:39], v[40:41] op_sel_hi:[1,0,1]
	v_pk_fma_f32 v[44:45], v[38:39], v[38:39], v[44:45] op_sel_hi:[1,0,1]
	v_xor_b32_e32 v17, 0x80000000, v8
	v_mov_b32_e32 v16, v9
	v_pk_add_f32 v[8:9], v[32:33], v[54:55]
	v_pk_add_f32 v[32:33], v[32:33], v[54:55] neg_lo:[0,1] neg_hi:[0,1]
	v_pk_add_f32 v[54:55], v[24:25], v[22:23]
	v_pk_add_f32 v[22:23], v[24:25], v[22:23] neg_lo:[0,1] neg_hi:[0,1]
	v_pk_add_f32 v[24:25], v[14:15], v[30:31]
	v_pk_mul_f32 v[46:47], v[36:37], v[44:45] op_sel:[0,1]
	v_xor_b32_e32 v50, 0x80000000, v41
	v_mov_b32_e32 v51, v40
	v_pk_add_f32 v[14:15], v[14:15], v[30:31] neg_lo:[0,1] neg_hi:[0,1]
	v_pk_add_f32 v[30:31], v[6:7], v[16:17]
	v_pk_add_f32 v[6:7], v[6:7], v[16:17] neg_lo:[0,1] neg_hi:[0,1]
	v_pk_mul_f32 v[16:17], v[36:37], v[24:25] op_sel:[0,1]
	v_pk_fma_f32 v[46:47], v[34:35], v[44:45], v[46:47] op_sel_hi:[1,0,1]
	v_pk_fma_f32 v[16:17], v[34:35], v[24:25], v[16:17] op_sel_hi:[1,0,1]
	v_pk_mul_f32 v[34:35], v[50:51], v[30:31] op_sel:[0,1]
	v_pk_mul_f32 v[48:49], v[42:43], v[44:45] op_sel:[0,1]
	v_pk_fma_f32 v[30:31], v[40:41], v[30:31], v[34:35] op_sel_hi:[1,0,1]
	v_pk_mul_f32 v[34:35], v[44:45], v[32:33] op_sel:[1,1] op_sel_hi:[0,1] neg_lo:[1,0]
	v_pk_fma_f32 v[48:49], v[38:39], v[44:45], v[48:49] op_sel_hi:[1,0,1]
	v_pk_fma_f32 v[32:33], v[44:45], v[32:33], v[34:35] op_sel_hi:[1,0,1]
	v_pk_mul_f32 v[34:35], v[46:47], v[14:15] op_sel:[1,1] op_sel_hi:[0,1] neg_lo:[1,0]
	v_pk_mul_f32 v[52:53], v[44:45], v[50:51] op_sel:[1,0]
	v_pk_fma_f32 v[14:15], v[46:47], v[14:15], v[34:35] op_sel_hi:[1,0,1]
	v_pk_fma_f32 v[52:53], v[40:41], v[44:45], v[52:53] op_sel_hi:[1,0,1]
	v_pk_mul_f32 v[34:35], v[48:49], v[22:23] op_sel:[1,1] op_sel_hi:[0,1] neg_lo:[1,0]
	v_pk_mul_f32 v[24:25], v[42:43], v[54:55] op_sel:[0,1]
	v_pk_fma_f32 v[22:23], v[48:49], v[22:23], v[34:35] op_sel_hi:[1,0,1]
	v_pk_mul_f32 v[34:35], v[52:53], v[6:7] op_sel:[1,1] op_sel_hi:[0,1] neg_lo:[1,0]
	v_add_u32_e32 v0, 0x400, v0
	s_or_b64 s[88:89], vcc, s[88:89]
	v_pk_fma_f32 v[24:25], v[38:39], v[54:55], v[24:25] op_sel_hi:[1,0,1]
	v_pk_fma_f32 v[6:7], v[52:53], v[6:7], v[34:35] op_sel_hi:[1,0,1]
	ds_write_b64 v1, v[4:5]
	ds_write_b64 v82, v[8:9]
	ds_write_b64 v1, v[28:29] offset:512
	ds_write_b64 v82, v[32:33] offset:512
	ds_write_b64 v1, v[20:21] offset:256
	ds_write_b64 v82, v[24:25] offset:256
	ds_write_b64 v1, v[18:19] offset:768
	ds_write_b64 v82, v[22:23] offset:768
	ds_write_b64 v1, v[12:13] offset:128
	ds_write_b64 v82, v[16:17] offset:128
	ds_write_b64 v1, v[10:11] offset:640
	ds_write_b64 v82, v[14:15] offset:640
	ds_write_b64 v1, v[26:27] offset:384
	ds_write_b64 v82, v[30:31] offset:384
	ds_write_b64 v1, v[2:3] offset:896
	ds_write_b64 v82, v[6:7] offset:896
	s_andn2_b64 exec, exec, s[88:89]
	s_cbranch_execnz .LBB0_294

.LBB0_343:
	v_ashrrev_i32_e32 v1, 7, v0
	v_mov_b32_e32 v22, v0
	v_mad_u64_u32 v[2:3], s[40:41], v1, s25, v[60:61]
	v_cvt_f32_i32_e32 v1, v22
	v_add_u32_e32 v52, 0x200, v0
	v_ashrrev_i32_e32 v4, 7, v52
	v_mul_f32_e32 v1, 0x38800000, v1
	v_cos_f32_e32 v22, v1
	v_sin_f32_e32 v24, v1
	v_mad_u64_u32 v[4:5], s[40:41], v4, s25, v[60:61]
	ds_read_b64 v[6:7], v2
	ds_read_b64 v[8:9], v4
	ds_read_b64 v[10:11], v2 offset:16512
	ds_read_b64 v[12:13], v4 offset:16512
	ds_read_b64 v[14:15], v2 offset:33024
	ds_read_b64 v[16:17], v4 offset:33024
	ds_read_b64 v[18:19], v2 offset:49536
	ds_read_b64 v[20:21], v4 offset:49536
	v_mov_b32_e32 v25, v22
	v_xor_b32_e32 v23, 0x80000000, v24
	v_pk_mul_f32 v[26:27], v[24:25], v[24:25] op_sel_hi:[1,0] neg_lo:[0,1] neg_hi:[0,1]
	s_waitcnt lgkmcnt(5)
	v_mul_f32_e32 v42, 0x3f3504f3, v11
	v_pk_fma_f32 v[26:27], v[22:23], v[22:23], v[26:27] op_sel_hi:[1,0,1]
	s_waitcnt lgkmcnt(1)
	v_mul_f32_e32 v46, 0xbf3504f3, v18
	v_xor_b32_e32 v30, 0x80000000, v27
	v_mov_b32_e32 v31, v26
	v_pk_fma_f32 v[42:43], v[10:11], s[56:57], v[42:43] op_sel_hi:[0,1,0]
	v_xor_b32_e32 v45, 0x80000000, v14
	v_mov_b32_e32 v44, v15
	v_pk_fma_f32 v[46:47], v[18:19], s[56:57], v[46:47] op_sel:[1,0,0] op_sel_hi:[1,1,0]
	v_pk_add_f32 v[50:51], v[10:11], v[18:19]
	v_pk_add_f32 v[10:11], v[10:11], v[18:19] neg_lo:[0,1] neg_hi:[0,1]
	v_pk_mul_f32 v[28:29], v[24:25], v[26:27] op_sel:[0,1]
	v_pk_mul_f32 v[32:33], v[26:27], v[30:31] op_sel:[1,0]
	v_pk_add_f32 v[48:49], v[6:7], v[14:15]
	v_pk_add_f32 v[14:15], v[6:7], v[14:15] neg_lo:[0,1] neg_hi:[0,1]
	v_xor_b32_e32 v19, 0x80000000, v10
	v_mov_b32_e32 v18, v11
	v_pk_add_f32 v[10:11], v[6:7], v[44:45]
	v_pk_add_f32 v[6:7], v[6:7], v[44:45] neg_lo:[0,1] neg_hi:[0,1]
	v_pk_add_f32 v[44:45], v[42:43], v[46:47]
	v_pk_add_f32 v[42:43], v[42:43], v[46:47] neg_lo:[0,1] neg_hi:[0,1]
	v_pk_fma_f32 v[28:29], v[22:23], v[26:27], v[28:29] op_sel_hi:[1,0,1]
	v_pk_fma_f32 v[32:33], v[26:27], v[26:27], v[32:33] op_sel_hi:[1,0,1]
	v_xor_b32_e32 v47, 0x80000000, v42
	v_mov_b32_e32 v46, v43
	v_pk_add_f32 v[42:43], v[48:49], v[50:51]
	v_pk_add_f32 v[48:49], v[48:49], v[50:51] neg_lo:[0,1] neg_hi:[0,1]
	v_pk_add_f32 v[50:51], v[14:15], v[18:19]
	v_pk_add_f32 v[14:15], v[14:15], v[18:19] neg_lo:[0,1] neg_hi:[0,1]
	v_pk_add_f32 v[18:19], v[10:11], v[44:45]
	v_pk_mul_f32 v[34:35], v[24:25], v[32:33] op_sel:[0,1]
	v_pk_add_f32 v[10:11], v[10:11], v[44:45] neg_lo:[0,1] neg_hi:[0,1]
	v_pk_add_f32 v[44:45], v[6:7], v[46:47]
	v_pk_mul_f32 v[24:25], v[24:25], v[18:19] op_sel:[0,1]
	v_pk_fma_f32 v[34:35], v[22:23], v[32:33], v[34:35] op_sel_hi:[1,0,1]
	v_pk_mul_f32 v[40:41], v[32:33], v[28:29] op_sel:[1,1] op_sel_hi:[1,0] neg_lo:[0,1]
	v_pk_fma_f32 v[18:19], v[22:23], v[18:19], v[24:25] op_sel_hi:[1,0,1]
	v_pk_mul_f32 v[24:25], v[28:29], v[44:45] op_sel:[1,1] op_sel_hi:[0,1] neg_lo:[1,0]
	v_pk_mul_f32 v[36:37], v[30:31], v[32:33] op_sel:[0,1]
	v_pk_fma_f32 v[40:41], v[28:29], v[32:33], v[40:41] op_sel_hi:[1,0,1]
	v_pk_fma_f32 v[24:25], v[28:29], v[44:45], v[24:25] op_sel_hi:[1,0,1]
	v_pk_fma_f32 v[36:37], v[26:27], v[32:33], v[36:37] op_sel_hi:[1,0,1]
	v_pk_mul_f32 v[28:29], v[10:11], v[34:35] op_sel:[1,1] op_sel_hi:[1,0] neg_lo:[0,1]
	v_cvt_f32_i32_e32 v1, v52
	v_pk_fma_f32 v[10:11], v[10:11], v[34:35], v[28:29] op_sel_hi:[0,1,1]
	v_pk_mul_f32 v[28:29], v[14:15], v[36:37] op_sel:[1,1] op_sel_hi:[1,0] neg_lo:[0,1]
	v_pk_add_f32 v[6:7], v[6:7], v[46:47] neg_lo:[0,1] neg_hi:[0,1]
	v_pk_fma_f32 v[14:15], v[14:15], v[36:37], v[28:29] op_sel_hi:[0,1,1]
	v_pk_mul_f32 v[28:29], v[6:7], v[40:41] op_sel:[1,1] op_sel_hi:[1,0] neg_lo:[0,1]
	v_mul_f32_e32 v1, 0x38800000, v1
	v_pk_fma_f32 v[6:7], v[40:41], v[6:7], v[28:29] op_sel_hi:[1,0,1]
	v_cos_f32_e32 v28, v1
	v_pk_mul_f32 v[22:23], v[30:31], v[50:51] op_sel:[0,1]
	v_sin_f32_e32 v30, v1
	v_pk_fma_f32 v[22:23], v[26:27], v[50:51], v[22:23] op_sel_hi:[1,0,1]
	v_pk_mul_f32 v[26:27], v[48:49], v[32:33] op_sel:[1,1] op_sel_hi:[1,0] neg_lo:[0,1]
	v_mov_b32_e32 v31, v28
	v_pk_fma_f32 v[26:27], v[48:49], v[32:33], v[26:27] op_sel_hi:[0,1,1]
	v_xor_b32_e32 v29, 0x80000000, v30
	v_pk_mul_f32 v[32:33], v[30:31], v[30:31] op_sel_hi:[1,0] neg_lo:[0,1] neg_hi:[0,1]
	v_mul_f32_e32 v50, 0x3f3504f3, v13
	v_pk_fma_f32 v[32:33], v[28:29], v[28:29], v[32:33] op_sel_hi:[1,0,1]
	s_waitcnt lgkmcnt(0)
	v_mul_f32_e32 v54, 0xbf3504f3, v20
	v_xor_b32_e32 v36, 0x80000000, v33
	v_mov_b32_e32 v37, v32
	v_pk_fma_f32 v[50:51], v[12:13], s[56:57], v[50:51] op_sel_hi:[0,1,0]
	v_xor_b32_e32 v53, 0x80000000, v16
	v_mov_b32_e32 v52, v17
	v_pk_fma_f32 v[54:55], v[20:21], s[56:57], v[54:55] op_sel:[1,0,0] op_sel_hi:[1,1,0]
	v_pk_add_f32 v[138:139], v[12:13], v[20:21]
	v_pk_add_f32 v[12:13], v[12:13], v[20:21] neg_lo:[0,1] neg_hi:[0,1]
	v_pk_mul_f32 v[34:35], v[30:31], v[32:33] op_sel:[0,1]
	v_pk_mul_f32 v[38:39], v[32:33], v[36:37] op_sel:[1,0]
	v_pk_add_f32 v[136:137], v[8:9], v[16:17]
	v_pk_add_f32 v[16:17], v[8:9], v[16:17] neg_lo:[0,1] neg_hi:[0,1]
	v_xor_b32_e32 v21, 0x80000000, v12
	v_mov_b32_e32 v20, v13
	v_pk_add_f32 v[12:13], v[8:9], v[52:53]
	v_pk_add_f32 v[8:9], v[8:9], v[52:53] neg_lo:[0,1] neg_hi:[0,1]
	v_pk_add_f32 v[52:53], v[50:51], v[54:55]
	v_pk_add_f32 v[50:51], v[50:51], v[54:55] neg_lo:[0,1] neg_hi:[0,1]
	v_pk_fma_f32 v[34:35], v[28:29], v[32:33], v[34:35] op_sel_hi:[1,0,1]
	v_pk_fma_f32 v[38:39], v[32:33], v[32:33], v[38:39] op_sel_hi:[1,0,1]
	v_xor_b32_e32 v55, 0x80000000, v50
	v_mov_b32_e32 v54, v51
	v_pk_add_f32 v[50:51], v[136:137], v[138:139]
	v_pk_add_f32 v[136:137], v[136:137], v[138:139] neg_lo:[0,1] neg_hi:[0,1]
	v_pk_add_f32 v[138:139], v[16:17], v[20:21]
	v_pk_add_f32 v[16:17], v[16:17], v[20:21] neg_lo:[0,1] neg_hi:[0,1]
	v_pk_add_f32 v[20:21], v[12:13], v[52:53]
	v_pk_mul_f32 v[40:41], v[30:31], v[38:39] op_sel:[0,1]
	v_xor_b32_e32 v46, 0x80000000, v35
	v_mov_b32_e32 v47, v34
	v_pk_add_f32 v[12:13], v[12:13], v[52:53] neg_lo:[0,1] neg_hi:[0,1]
	v_pk_add_f32 v[52:53], v[8:9], v[54:55]
	v_pk_mul_f32 v[30:31], v[30:31], v[20:21] op_sel:[0,1]
	v_pk_fma_f32 v[40:41], v[28:29], v[38:39], v[40:41] op_sel_hi:[1,0,1]
	v_pk_mul_f32 v[44:45], v[36:37], v[38:39] op_sel:[0,1]
	v_pk_mul_f32 v[48:49], v[38:39], v[46:47] op_sel:[1,0]
	v_pk_fma_f32 v[20:21], v[28:29], v[20:21], v[30:31] op_sel_hi:[1,0,1]
	v_pk_mul_f32 v[28:29], v[36:37], v[138:139] op_sel:[0,1]
	v_pk_mul_f32 v[30:31], v[46:47], v[52:53] op_sel:[0,1]
	v_pk_fma_f32 v[44:45], v[32:33], v[38:39], v[44:45] op_sel_hi:[1,0,1]
	v_pk_fma_f32 v[48:49], v[34:35], v[38:39], v[48:49] op_sel_hi:[1,0,1]
	v_pk_fma_f32 v[28:29], v[32:33], v[138:139], v[28:29] op_sel_hi:[1,0,1]
	v_pk_fma_f32 v[30:31], v[34:35], v[52:53], v[30:31] op_sel_hi:[1,0,1]
	v_pk_mul_f32 v[32:33], v[136:137], v[38:39] op_sel:[1,1] op_sel_hi:[1,0] neg_lo:[0,1]
	v_pk_mul_f32 v[34:35], v[12:13], v[40:41] op_sel:[1,1] op_sel_hi:[1,0] neg_lo:[0,1]
	v_add_u32_e32 v1, 0x10200, v2
	v_pk_fma_f32 v[32:33], v[136:137], v[38:39], v[32:33] op_sel_hi:[0,1,1]
	v_pk_fma_f32 v[12:13], v[12:13], v[40:41], v[34:35] op_sel_hi:[0,1,1]
	ds_write_b64 v2, v[42:43]
	ds_write_b64 v4, v[50:51]
	ds_write_b64 v1, v[26:27]
	v_add_u32_e32 v1, 0x10200, v4
	v_pk_mul_f32 v[34:35], v[16:17], v[44:45] op_sel:[1,1] op_sel_hi:[1,0] neg_lo:[0,1]
	ds_write_b64 v1, v[32:33]
	ds_write_b64 v2, v[22:23] offset:33024
	ds_write_b64 v4, v[28:29] offset:33024
	v_add_u32_e32 v1, 0x18300, v2
	v_pk_fma_f32 v[16:17], v[16:17], v[44:45], v[34:35] op_sel_hi:[0,1,1]
	ds_write_b64 v1, v[14:15]
	v_add_u32_e32 v1, 0x18300, v4
	ds_write_b64 v1, v[16:17]
	ds_write_b64 v2, v[18:19] offset:16512
	ds_write_b64 v4, v[20:21] offset:16512
	v_add_u32_e32 v1, 0x14280, v2
	v_pk_add_f32 v[8:9], v[8:9], v[54:55] neg_lo:[0,1] neg_hi:[0,1]
	ds_write_b64 v1, v[10:11]
	v_add_u32_e32 v1, 0x14280, v4
	v_pk_mul_f32 v[34:35], v[8:9], v[48:49] op_sel:[1,1] op_sel_hi:[1,0] neg_lo:[0,1]
	ds_write_b64 v1, v[12:13]
	ds_write_b64 v2, v[24:25] offset:49536
	ds_write_b64 v4, v[30:31] offset:49536
	v_add_u32_e32 v1, 0x1c380, v2
	v_cmp_lt_i32_e32 vcc, s28, v0
	v_pk_fma_f32 v[8:9], v[48:49], v[8:9], v[34:35] op_sel_hi:[1,0,1]
	ds_write_b64 v1, v[6:7]
	v_add_u32_e32 v1, 0x1c380, v4
	v_add_u32_e32 v0, 0x400, v0
	s_or_b64 s[92:93], vcc, s[92:93]
	ds_write_b64 v1, v[8:9]
	s_andn2_b64 exec, exec, s[92:93]
	s_cbranch_execnz .LBB0_343
	s_or_b64 exec, exec, s[92:93]

.LBB0_347:
	v_lshrrev_b32_e32 v0, 3, v66
	v_add_u32_e32 v1, 0x200, v66
	v_and_b32_e32 v0, 0x1ffffff0, v0
	v_lshrrev_b32_e32 v1, 3, v1
	v_and_b32_e32 v1, 0x1ffffff0, v1
	v_mad_u64_u32 v[136:137], s[40:41], v0, s25, v[60:61]
	v_mov_b32_e32 v140, v65
	v_mov_b32_e32 v216, v65
	v_mad_u64_u32 v[138:139], s[40:41], v1, s25, v[60:61]
	v_add_u32_e32 v16, 0x2000, v136
	ds_read2_b64 v[190:193], v136 offset1:129
	ds_read2_b64 v[12:15], v138 offset1:129
	ds_read2_b64 v[218:221], v16 offset0:8 offset1:137
	v_add_u32_e32 v16, 0x2000, v138
	v_add_u32_e32 v0, 0x800, v136
	ds_read2_b64 v[28:31], v16 offset0:8 offset1:137
	v_add_u32_e32 v16, 0x2800, v136
	ds_read2_b64 v[48:51], v0 offset0:2 offset1:131
	ds_read2_b64 v[52:55], v16 offset0:10 offset1:139
	v_add_u32_e32 v0, 0x800, v138
	v_add_u32_e32 v16, 0x2800, v138
	ds_read2_b64 v[8:11], v0 offset0:2 offset1:131
	v_add_u32_e32 v0, 0x1000, v136
	ds_read2_b64 v[24:27], v16 offset0:10 offset1:139
	v_add_u32_e32 v16, 0x3000, v136
	s_waitcnt lgkmcnt(5)
	v_pk_add_f32 v[188:189], v[190:191], v[218:219]
	v_pk_add_f32 v[186:187], v[190:191], v[218:219] neg_lo:[0,1] neg_hi:[0,1]
	v_pk_add_f32 v[190:191], v[192:193], v[220:221]
	v_pk_add_f32 v[192:193], v[192:193], v[220:221] neg_lo:[0,1] neg_hi:[0,1]
	ds_read2_b64 v[40:43], v0 offset0:4 offset1:133
	ds_read2_b64 v[44:47], v16 offset0:12 offset1:141
	v_pk_mul_f32 v[194:195], v[192:193], s[42:43] op_sel_hi:[0,1]
	s_mov_b32 s65, s42
	v_add_u32_e32 v0, 0x1000, v138
	v_add_u32_e32 v16, 0x3000, v138
	v_pk_fma_f32 v[192:193], v[192:193], s[64:65], v[194:195] op_sel:[1,0,0]
	s_waitcnt lgkmcnt(4)
	v_pk_add_f32 v[194:195], v[48:49], v[52:53]
	v_pk_add_f32 v[48:49], v[48:49], v[52:53] neg_lo:[0,1] neg_hi:[0,1]
	ds_read2_b64 v[4:7], v0 offset0:4 offset1:133
	v_add_u32_e32 v0, 0x1800, v136
	ds_read2_b64 v[20:23], v16 offset0:12 offset1:141
	v_add_u32_e32 v16, 0x3800, v136
	v_mul_f32_e32 v52, 0x3f3504f3, v49
	ds_read2_b64 v[32:35], v0 offset0:6 offset1:135
	ds_read2_b64 v[36:39], v16 offset0:14 offset1:143
	v_pk_fma_f32 v[48:49], v[48:49], s[56:57], v[52:53] op_sel_hi:[0,1,0]
	v_pk_add_f32 v[52:53], v[50:51], v[54:55]
	v_pk_add_f32 v[50:51], v[50:51], v[54:55] neg_lo:[0,1] neg_hi:[0,1]
	s_mov_b32 s66, s64
	v_pk_mul_f32 v[54:55], v[50:51], s[66:67] op_sel_hi:[0,1]
	s_mov_b32 s44, s42
	s_mov_b32 s45, s64
	v_cvt_f32_i32_e32 v137, v140
	v_pk_fma_f32 v[50:51], v[50:51], s[44:45], v[54:55] op_sel:[1,0,0]
	s_waitcnt lgkmcnt(4)
	v_pk_add_f32 v[54:55], v[40:41], v[44:45]
	v_pk_add_f32 v[40:41], v[40:41], v[44:45] neg_lo:[0,1] neg_hi:[0,1]
	s_mov_b32 s58, s43
	v_xor_b32_e32 v45, 0x80000000, v40
	v_mov_b32_e32 v44, v41
	v_pk_add_f32 v[40:41], v[42:43], v[46:47]
	v_pk_add_f32 v[42:43], v[42:43], v[46:47] neg_lo:[0,1] neg_hi:[0,1]
	s_mov_b32 s59, s67
	v_pk_mul_f32 v[46:47], v[42:43], s[58:59] op_sel_hi:[0,1]
	v_pk_fma_f32 v[42:43], v[42:43], s[42:43], v[46:47] op_sel:[1,0,0]
	s_waitcnt lgkmcnt(0)
	v_pk_add_f32 v[46:47], v[32:33], v[36:37]
	v_pk_add_f32 v[32:33], v[32:33], v[36:37] neg_lo:[0,1] neg_hi:[0,1]
	v_mul_f32_e32 v137, 0x3a000000, v137
	v_mul_f32_e32 v36, 0xbf3504f3, v32
	v_cos_f32_e32 v148, v137
	v_pk_fma_f32 v[32:33], v[32:33], s[56:57], v[36:37] op_sel:[1,0,0] op_sel_hi:[1,1,0]
	v_pk_add_f32 v[36:37], v[34:35], v[38:39]
	v_pk_add_f32 v[34:35], v[34:35], v[38:39] neg_lo:[0,1] neg_hi:[0,1]
	s_mov_b32 s40, s67
	s_mov_b32 s41, s43
	v_sin_f32_e32 v152, v137
	v_pk_mul_f32 v[38:39], v[34:35], s[40:41] op_sel_hi:[0,1]
	v_pk_fma_f32 v[34:35], v[34:35], s[66:67], v[38:39] op_sel:[1,0,0]
	v_pk_add_f32 v[38:39], v[188:189], v[54:55]
	v_pk_add_f32 v[54:55], v[188:189], v[54:55] neg_lo:[0,1] neg_hi:[0,1]
	v_pk_add_f32 v[188:189], v[190:191], v[40:41]
	v_pk_add_f32 v[40:41], v[190:191], v[40:41] neg_lo:[0,1] neg_hi:[0,1]
	v_mov_b32_e32 v153, v148
	v_mul_f32_e32 v190, 0x3f3504f3, v41
	v_pk_fma_f32 v[40:41], v[40:41], s[56:57], v[190:191] op_sel_hi:[0,1,0]
	v_pk_add_f32 v[190:191], v[194:195], v[46:47]
	v_pk_add_f32 v[46:47], v[194:195], v[46:47] neg_lo:[0,1] neg_hi:[0,1]
	v_xor_b32_e32 v149, 0x80000000, v152
	v_pk_mul_f32 v[140:141], v[152:153], v[152:153] op_sel_hi:[1,0] neg_lo:[0,1] neg_hi:[0,1]
	v_xor_b32_e32 v195, 0x80000000, v46
	v_mov_b32_e32 v194, v47
	v_pk_add_f32 v[46:47], v[52:53], v[36:37]
	v_pk_add_f32 v[36:37], v[52:53], v[36:37] neg_lo:[0,1] neg_hi:[0,1]
	v_pk_fma_f32 v[154:155], v[148:149], v[148:149], v[140:141] op_sel_hi:[1,0,1]
	v_mul_f32_e32 v52, 0xbf3504f3, v36
	v_pk_mul_f32 v[140:141], v[152:153], v[154:155] op_sel:[0,1]
	v_pk_fma_f32 v[36:37], v[36:37], s[56:57], v[52:53] op_sel:[1,0,0] op_sel_hi:[1,1,0]
	v_pk_add_f32 v[52:53], v[186:187], v[44:45]
	v_pk_add_f32 v[44:45], v[186:187], v[44:45] neg_lo:[0,1] neg_hi:[0,1]
	v_pk_add_f32 v[186:187], v[192:193], v[42:43]
	v_pk_add_f32 v[42:43], v[192:193], v[42:43] neg_lo:[0,1] neg_hi:[0,1]
	v_pk_fma_f32 v[156:157], v[148:149], v[154:155], v[140:141] op_sel_hi:[1,0,1]
	v_pk_mul_f32 v[140:141], v[154:155], v[154:155] op_sel:[1,1] op_sel_hi:[1,0] neg_lo:[0,1]
	v_mul_f32_e32 v192, 0x3f3504f3, v43
	v_pk_fma_f32 v[160:161], v[154:155], v[154:155], v[140:141] op_sel_hi:[1,0,1]
	v_pk_fma_f32 v[42:43], v[42:43], s[56:57], v[192:193] op_sel_hi:[0,1,0]
	v_pk_add_f32 v[192:193], v[48:49], v[32:33]
	v_pk_add_f32 v[32:33], v[48:49], v[32:33] neg_lo:[0,1] neg_hi:[0,1]
	v_pk_mul_f32 v[140:141], v[152:153], v[160:161] op_sel:[0,1]
	v_xor_b32_e32 v49, 0x80000000, v32
	v_mov_b32_e32 v48, v33
	v_pk_add_f32 v[32:33], v[50:51], v[34:35]
	v_pk_add_f32 v[34:35], v[50:51], v[34:35] neg_lo:[0,1] neg_hi:[0,1]
	v_pk_fma_f32 v[162:163], v[148:149], v[160:161], v[140:141] op_sel_hi:[1,0,1]
	v_pk_mul_f32 v[140:141], v[154:155], v[160:161] op_sel:[1,1] op_sel_hi:[0,1] neg_lo:[1,0]
	v_mul_f32_e32 v50, 0xbf3504f3, v34
	v_pk_fma_f32 v[164:165], v[154:155], v[160:161], v[140:141] op_sel_hi:[1,0,1]
	v_pk_mul_f32 v[140:141], v[160:161], v[156:157] op_sel:[1,1] op_sel_hi:[1,0] neg_lo:[0,1]
	v_pk_fma_f32 v[34:35], v[34:35], s[56:57], v[50:51] op_sel:[1,0,0] op_sel_hi:[1,1,0]
	v_pk_add_f32 v[50:51], v[38:39], v[190:191]
	v_pk_add_f32 v[38:39], v[38:39], v[190:191] neg_lo:[0,1] neg_hi:[0,1]
	v_pk_add_f32 v[190:191], v[188:189], v[46:47]
	v_pk_add_f32 v[46:47], v[188:189], v[46:47] neg_lo:[0,1] neg_hi:[0,1]
	v_pk_fma_f32 v[170:171], v[156:157], v[160:161], v[140:141] op_sel_hi:[1,0,1]
	v_pk_mul_f32 v[140:141], v[160:161], v[160:161] op_sel:[1,1] op_sel_hi:[1,0] neg_lo:[0,1]
	v_xor_b32_e32 v189, 0x80000000, v46
	v_mov_b32_e32 v188, v47
	v_pk_add_f32 v[46:47], v[54:55], v[194:195]
	v_pk_add_f32 v[54:55], v[54:55], v[194:195] neg_lo:[0,1] neg_hi:[0,1]
	v_pk_add_f32 v[194:195], v[40:41], v[36:37]
	v_pk_add_f32 v[36:37], v[40:41], v[36:37] neg_lo:[0,1] neg_hi:[0,1]
	v_pk_fma_f32 v[172:173], v[160:161], v[160:161], v[140:141] op_sel_hi:[1,0,1]
	v_xor_b32_e32 v41, 0x80000000, v36
	v_mov_b32_e32 v40, v37
	v_pk_add_f32 v[36:37], v[52:53], v[192:193]
	v_pk_add_f32 v[52:53], v[52:53], v[192:193] neg_lo:[0,1] neg_hi:[0,1]
	v_pk_add_f32 v[192:193], v[186:187], v[32:33]
	v_pk_add_f32 v[32:33], v[186:187], v[32:33] neg_lo:[0,1] neg_hi:[0,1]
	v_pk_mul_f32 v[140:141], v[152:153], v[172:173] op_sel:[0,1]
	v_xor_b32_e32 v187, 0x80000000, v32
	v_mov_b32_e32 v186, v33
	v_pk_add_f32 v[32:33], v[44:45], v[48:49]
	v_pk_add_f32 v[44:45], v[44:45], v[48:49] neg_lo:[0,1] neg_hi:[0,1]
	v_pk_add_f32 v[48:49], v[42:43], v[34:35]
	v_pk_add_f32 v[34:35], v[42:43], v[34:35] neg_lo:[0,1] neg_hi:[0,1]
	v_pk_fma_f32 v[166:167], v[148:149], v[172:173], v[140:141] op_sel_hi:[1,0,1]
	v_pk_mul_f32 v[140:141], v[154:155], v[172:173] op_sel:[1,1] op_sel_hi:[0,1] neg_lo:[1,0]
	v_xor_b32_e32 v43, 0x80000000, v34
	v_mov_b32_e32 v42, v35
	v_pk_add_f32 v[34:35], v[50:51], v[190:191]
	v_pk_add_f32 v[50:51], v[50:51], v[190:191] neg_lo:[0,1] neg_hi:[0,1]
	v_pk_add_f32 v[190:191], v[38:39], v[188:189]
	v_pk_add_f32 v[38:39], v[38:39], v[188:189] neg_lo:[0,1] neg_hi:[0,1]
	v_pk_add_f32 v[188:189], v[46:47], v[194:195]
	v_pk_add_f32 v[46:47], v[46:47], v[194:195] neg_lo:[0,1] neg_hi:[0,1]
	v_pk_add_f32 v[194:195], v[54:55], v[40:41]
	v_pk_add_f32 v[40:41], v[54:55], v[40:41] neg_lo:[0,1] neg_hi:[0,1]
	v_pk_add_f32 v[54:55], v[36:37], v[192:193]
	v_pk_fma_f32 v[158:159], v[154:155], v[172:173], v[140:141] op_sel_hi:[1,0,1]
	v_pk_mul_f32 v[140:141], v[156:157], v[172:173] op_sel:[1,1] op_sel_hi:[0,1] neg_lo:[1,0]
	v_pk_add_f32 v[36:37], v[36:37], v[192:193] neg_lo:[0,1] neg_hi:[0,1]
	v_pk_add_f32 v[192:193], v[52:53], v[186:187]
	v_pk_add_f32 v[52:53], v[52:53], v[186:187] neg_lo:[0,1] neg_hi:[0,1]
	v_pk_add_f32 v[186:187], v[32:33], v[48:49]
	v_pk_add_f32 v[48:49], v[32:33], v[48:49] neg_lo:[0,1] neg_hi:[0,1]
	v_pk_mul_f32 v[32:33], v[152:153], v[54:55] op_sel:[0,1]
	v_pk_fma_f32 v[150:151], v[156:157], v[172:173], v[140:141] op_sel_hi:[1,0,1]
	v_pk_mul_f32 v[140:141], v[160:161], v[172:173] op_sel:[1,1] op_sel_hi:[0,1] neg_lo:[1,0]
	v_pk_add_f32 v[218:219], v[44:45], v[42:43]
	v_pk_add_f32 v[42:43], v[44:45], v[42:43] neg_lo:[0,1] neg_hi:[0,1]
	v_pk_fma_f32 v[44:45], v[148:149], v[54:55], v[32:33] op_sel_hi:[1,0,1]
	v_pk_mul_f32 v[32:33], v[154:155], v[188:189] op_sel:[1,1] op_sel_hi:[0,1] neg_lo:[1,0]
	v_pk_mul_f32 v[148:149], v[160:161], v[190:191] op_sel:[1,1] op_sel_hi:[0,1] neg_lo:[1,0]
	v_pk_fma_f32 v[140:141], v[160:161], v[172:173], v[140:141] op_sel_hi:[1,0,1]
	v_pk_fma_f32 v[54:55], v[154:155], v[188:189], v[32:33] op_sel_hi:[1,0,1]
	v_pk_fma_f32 v[148:149], v[160:161], v[190:191], v[148:149] op_sel_hi:[1,0,1]
	v_pk_mul_f32 v[154:155], v[164:165], v[194:195] op_sel:[1,1] op_sel_hi:[0,1] neg_lo:[1,0]
	v_pk_fma_f32 v[154:155], v[164:165], v[194:195], v[154:155] op_sel_hi:[1,0,1]
	v_pk_mul_f32 v[160:161], v[172:173], v[50:51] op_sel:[1,1] op_sel_hi:[0,1] neg_lo:[1,0]
	v_pk_add_f32 v[194:195], v[12:13], v[28:29]
	v_pk_add_f32 v[12:13], v[12:13], v[28:29] neg_lo:[0,1] neg_hi:[0,1]
	v_pk_add_f32 v[28:29], v[14:15], v[30:31]
	v_pk_add_f32 v[14:15], v[14:15], v[30:31] neg_lo:[0,1] neg_hi:[0,1]
	v_pk_fma_f32 v[50:51], v[172:173], v[50:51], v[160:161] op_sel_hi:[1,0,1]
	v_pk_mul_f32 v[30:31], v[14:15], s[42:43] op_sel_hi:[0,1]
	v_pk_mul_f32 v[160:161], v[166:167], v[36:37] op_sel:[1,1] op_sel_hi:[0,1] neg_lo:[1,0]
	v_pk_fma_f32 v[14:15], v[14:15], s[64:65], v[30:31] op_sel:[1,0,0]
	v_pk_add_f32 v[30:31], v[8:9], v[24:25]
	v_pk_add_f32 v[8:9], v[8:9], v[24:25] neg_lo:[0,1] neg_hi:[0,1]
	v_add_u32_e32 v0, 0x1800, v138
	v_add_u32_e32 v16, 0x3800, v138
	v_pk_fma_f32 v[36:37], v[166:167], v[36:37], v[160:161] op_sel_hi:[1,0,1]
	v_mul_f32_e32 v24, 0x3f3504f3, v9
	ds_read2_b64 v[0:3], v0 offset0:6 offset1:135
	ds_read2_b64 v[16:19], v16 offset0:14 offset1:143
	v_pk_mul_f32 v[160:161], v[158:159], v[46:47] op_sel:[1,1] op_sel_hi:[0,1] neg_lo:[1,0]
	v_pk_fma_f32 v[8:9], v[8:9], s[56:57], v[24:25] op_sel_hi:[0,1,0]
	v_pk_add_f32 v[24:25], v[10:11], v[26:27]
	v_pk_add_f32 v[10:11], v[10:11], v[26:27] neg_lo:[0,1] neg_hi:[0,1]
	v_pk_fma_f32 v[46:47], v[158:159], v[46:47], v[160:161] op_sel_hi:[1,0,1]
	v_pk_mul_f32 v[26:27], v[10:11], s[66:67] op_sel_hi:[0,1]
	v_pk_mul_f32 v[158:159], v[150:151], v[48:49] op_sel:[1,1] op_sel_hi:[0,1] neg_lo:[1,0]
	v_pk_fma_f32 v[10:11], v[10:11], s[44:45], v[26:27] op_sel:[1,0,0]
	v_pk_add_f32 v[26:27], v[4:5], v[20:21]
	v_pk_add_f32 v[4:5], v[4:5], v[20:21] neg_lo:[0,1] neg_hi:[0,1]
	v_pk_mul_f32 v[142:143], v[172:173], v[162:163] op_sel:[1,1] op_sel_hi:[1,0] neg_lo:[0,1]
	v_pk_fma_f32 v[48:49], v[150:151], v[48:49], v[158:159] op_sel_hi:[1,0,1]
	v_xor_b32_e32 v21, 0x80000000, v4
	v_mov_b32_e32 v20, v5
	v_pk_add_f32 v[4:5], v[6:7], v[22:23]
	v_pk_add_f32 v[6:7], v[6:7], v[22:23] neg_lo:[0,1] neg_hi:[0,1]
	v_pk_fma_f32 v[142:143], v[162:163], v[172:173], v[142:143] op_sel_hi:[1,0,1]
	v_pk_mul_f32 v[150:151], v[140:141], v[38:39] op_sel:[1,1] op_sel_hi:[0,1] neg_lo:[1,0]
	v_pk_mul_f32 v[22:23], v[6:7], s[58:59] op_sel_hi:[0,1]
	v_pk_mul_f32 v[144:145], v[172:173], v[164:165] op_sel:[1,1] op_sel_hi:[1,0] neg_lo:[0,1]
	v_pk_fma_f32 v[38:39], v[140:141], v[38:39], v[150:151] op_sel_hi:[1,0,1]
	v_pk_fma_f32 v[6:7], v[6:7], s[42:43], v[22:23] op_sel:[1,0,0]
	s_waitcnt lgkmcnt(0)
	v_pk_add_f32 v[22:23], v[0:1], v[16:17]
	v_pk_add_f32 v[0:1], v[0:1], v[16:17] neg_lo:[0,1] neg_hi:[0,1]
	v_pk_fma_f32 v[144:145], v[164:165], v[172:173], v[144:145] op_sel_hi:[1,0,1]
	v_pk_mul_f32 v[140:141], v[142:143], v[52:53] op_sel:[1,1] op_sel_hi:[0,1] neg_lo:[1,0]
	v_cvt_f32_i32_e32 v137, v216
	v_mul_f32_e32 v16, 0xbf3504f3, v0
	v_pk_mul_f32 v[146:147], v[172:173], v[170:171] op_sel:[1,1] op_sel_hi:[1,0] neg_lo:[0,1]
	v_pk_fma_f32 v[52:53], v[142:143], v[52:53], v[140:141] op_sel_hi:[1,0,1]
	v_pk_fma_f32 v[0:1], v[0:1], s[56:57], v[16:17] op_sel:[1,0,0] op_sel_hi:[1,1,0]
	v_pk_add_f32 v[16:17], v[2:3], v[18:19]
	v_pk_add_f32 v[2:3], v[2:3], v[18:19] neg_lo:[0,1] neg_hi:[0,1]
	v_pk_fma_f32 v[146:147], v[170:171], v[172:173], v[146:147] op_sel_hi:[1,0,1]
	v_pk_mul_f32 v[140:141], v[144:145], v[40:41] op_sel:[1,1] op_sel_hi:[0,1] neg_lo:[1,0]
	v_pk_mul_f32 v[18:19], v[2:3], s[40:41] op_sel_hi:[0,1]
	v_pk_fma_f32 v[40:41], v[144:145], v[40:41], v[140:141] op_sel_hi:[1,0,1]
	v_pk_fma_f32 v[2:3], v[2:3], s[66:67], v[18:19] op_sel:[1,0,0]
	v_pk_add_f32 v[18:19], v[194:195], v[26:27]
	v_pk_add_f32 v[26:27], v[194:195], v[26:27] neg_lo:[0,1] neg_hi:[0,1]
	v_pk_add_f32 v[194:195], v[28:29], v[4:5]
	v_pk_add_f32 v[4:5], v[28:29], v[4:5] neg_lo:[0,1] neg_hi:[0,1]
	v_pk_mul_f32 v[140:141], v[146:147], v[42:43] op_sel:[1,1] op_sel_hi:[0,1] neg_lo:[1,0]
	v_mul_f32_e32 v137, 0x3a000000, v137
	v_mul_f32_e32 v28, 0x3f3504f3, v5
	v_pk_fma_f32 v[42:43], v[146:147], v[42:43], v[140:141] op_sel_hi:[1,0,1]
	v_cos_f32_e32 v140, v137
	v_pk_fma_f32 v[4:5], v[4:5], s[56:57], v[28:29] op_sel_hi:[0,1,0]
	v_pk_add_f32 v[28:29], v[30:31], v[22:23]
	v_pk_add_f32 v[22:23], v[30:31], v[22:23] neg_lo:[0,1] neg_hi:[0,1]
	v_sin_f32_e32 v142, v137
	v_xor_b32_e32 v31, 0x80000000, v22
	v_mov_b32_e32 v30, v23
	v_pk_add_f32 v[22:23], v[24:25], v[16:17]
	v_pk_add_f32 v[16:17], v[24:25], v[16:17] neg_lo:[0,1] neg_hi:[0,1]
	v_mov_b32_e32 v143, v140
	v_mul_f32_e32 v24, 0xbf3504f3, v16
	v_pk_fma_f32 v[16:17], v[16:17], s[56:57], v[24:25] op_sel:[1,0,0] op_sel_hi:[1,1,0]
	v_pk_add_f32 v[24:25], v[12:13], v[20:21]
	v_pk_add_f32 v[12:13], v[12:13], v[20:21] neg_lo:[0,1] neg_hi:[0,1]
	v_pk_add_f32 v[20:21], v[14:15], v[6:7]
	v_pk_add_f32 v[6:7], v[14:15], v[6:7] neg_lo:[0,1] neg_hi:[0,1]
	v_xor_b32_e32 v141, 0x80000000, v142
	v_mul_f32_e32 v14, 0x3f3504f3, v7
	v_pk_mul_f32 v[144:145], v[142:143], v[142:143] op_sel_hi:[1,0] neg_lo:[0,1] neg_hi:[0,1]
	v_pk_fma_f32 v[6:7], v[6:7], s[56:57], v[14:15] op_sel_hi:[0,1,0]
	v_pk_add_f32 v[14:15], v[8:9], v[0:1]
	v_pk_add_f32 v[0:1], v[8:9], v[0:1] neg_lo:[0,1] neg_hi:[0,1]
	v_pk_fma_f32 v[144:145], v[140:141], v[140:141], v[144:145] op_sel_hi:[1,0,1]
	v_xor_b32_e32 v9, 0x80000000, v0
	v_mov_b32_e32 v8, v1
	v_pk_add_f32 v[0:1], v[10:11], v[2:3]
	v_pk_add_f32 v[2:3], v[10:11], v[2:3] neg_lo:[0,1] neg_hi:[0,1]
	v_xor_b32_e32 v150, 0x80000000, v145
	v_mov_b32_e32 v151, v144
	v_mul_f32_e32 v10, 0xbf3504f3, v2
	v_pk_mul_f32 v[32:33], v[156:157], v[186:187] op_sel:[1,1] op_sel_hi:[0,1] neg_lo:[1,0]
	v_pk_mul_f32 v[158:159], v[144:145], v[150:151] op_sel:[1,0]
	v_pk_fma_f32 v[2:3], v[2:3], s[56:57], v[10:11] op_sel:[1,0,0] op_sel_hi:[1,1,0]
	v_pk_add_f32 v[10:11], v[18:19], v[28:29]
	v_pk_add_f32 v[18:19], v[18:19], v[28:29] neg_lo:[0,1] neg_hi:[0,1]
	v_pk_add_f32 v[28:29], v[194:195], v[22:23]
	v_pk_add_f32 v[22:23], v[194:195], v[22:23] neg_lo:[0,1] neg_hi:[0,1]
	v_pk_fma_f32 v[32:33], v[156:157], v[186:187], v[32:33] op_sel_hi:[1,0,1]
	v_pk_mul_f32 v[156:157], v[170:171], v[218:219] op_sel:[1,1] op_sel_hi:[0,1] neg_lo:[1,0]
	v_pk_fma_f32 v[158:159], v[144:145], v[144:145], v[158:159] op_sel_hi:[1,0,1]
	v_xor_b32_e32 v195, 0x80000000, v22
	v_mov_b32_e32 v194, v23
	v_pk_add_f32 v[22:23], v[26:27], v[30:31]
	v_pk_add_f32 v[26:27], v[26:27], v[30:31] neg_lo:[0,1] neg_hi:[0,1]
	v_pk_add_f32 v[30:31], v[4:5], v[16:17]
	v_pk_add_f32 v[4:5], v[4:5], v[16:17] neg_lo:[0,1] neg_hi:[0,1]
	v_pk_fma_f32 v[156:157], v[170:171], v[218:219], v[156:157] op_sel_hi:[1,0,1]
	v_xor_b32_e32 v170, 0x80000000, v159
	v_mov_b32_e32 v171, v158
	v_xor_b32_e32 v17, 0x80000000, v4
	v_mov_b32_e32 v16, v5
	v_pk_add_f32 v[4:5], v[24:25], v[14:15]
	v_pk_add_f32 v[14:15], v[24:25], v[14:15] neg_lo:[0,1] neg_hi:[0,1]
	v_pk_add_f32 v[24:25], v[20:21], v[0:1]
	v_pk_add_f32 v[0:1], v[20:21], v[0:1] neg_lo:[0,1] neg_hi:[0,1]
	v_pk_mul_f32 v[146:147], v[142:143], v[144:145] op_sel:[0,1]
	v_pk_mul_f32 v[172:173], v[158:159], v[170:171] op_sel:[1,0]
	v_xor_b32_e32 v21, 0x80000000, v0
	v_mov_b32_e32 v20, v1
	v_pk_add_f32 v[0:1], v[12:13], v[8:9]
	v_pk_add_f32 v[8:9], v[12:13], v[8:9] neg_lo:[0,1] neg_hi:[0,1]
	v_pk_add_f32 v[12:13], v[6:7], v[2:3]
	v_pk_add_f32 v[2:3], v[6:7], v[2:3] neg_lo:[0,1] neg_hi:[0,1]
	v_pk_fma_f32 v[146:147], v[140:141], v[144:145], v[146:147] op_sel_hi:[1,0,1]
	v_pk_fma_f32 v[172:173], v[158:159], v[158:159], v[172:173] op_sel_hi:[1,0,1]
	v_xor_b32_e32 v7, 0x80000000, v2
	v_mov_b32_e32 v6, v3
	v_pk_add_f32 v[2:3], v[10:11], v[28:29]
	v_pk_add_f32 v[10:11], v[10:11], v[28:29] neg_lo:[0,1] neg_hi:[0,1]
	v_pk_add_f32 v[28:29], v[18:19], v[194:195]
	v_pk_add_f32 v[18:19], v[18:19], v[194:195] neg_lo:[0,1] neg_hi:[0,1]
	v_pk_add_f32 v[194:195], v[22:23], v[30:31]
	v_pk_add_f32 v[22:23], v[22:23], v[30:31] neg_lo:[0,1] neg_hi:[0,1]
	v_pk_add_f32 v[30:31], v[26:27], v[16:17]
	v_pk_add_f32 v[16:17], v[26:27], v[16:17] neg_lo:[0,1] neg_hi:[0,1]
	v_pk_add_f32 v[26:27], v[4:5], v[24:25]
	v_pk_mul_f32 v[152:153], v[162:163], v[192:193] op_sel:[1,1] op_sel_hi:[0,1] neg_lo:[1,0]
	v_pk_mul_f32 v[160:161], v[142:143], v[158:159] op_sel:[0,1]
	v_xor_b32_e32 v164, 0x80000000, v147
	v_mov_b32_e32 v165, v146
	v_pk_mul_f32 v[174:175], v[142:143], v[172:173] op_sel:[0,1]
	v_pk_add_f32 v[4:5], v[4:5], v[24:25] neg_lo:[0,1] neg_hi:[0,1]
	v_pk_add_f32 v[24:25], v[14:15], v[20:21]
	v_pk_add_f32 v[14:15], v[14:15], v[20:21] neg_lo:[0,1] neg_hi:[0,1]
	v_pk_add_f32 v[20:21], v[0:1], v[12:13]
	v_pk_add_f32 v[0:1], v[0:1], v[12:13] neg_lo:[0,1] neg_hi:[0,1]
	v_pk_add_f32 v[12:13], v[8:9], v[6:7]
	v_pk_add_f32 v[6:7], v[8:9], v[6:7] neg_lo:[0,1] neg_hi:[0,1]
	v_pk_mul_f32 v[8:9], v[142:143], v[26:27] op_sel:[0,1]
	v_pk_fma_f32 v[152:153], v[162:163], v[192:193], v[152:153] op_sel_hi:[1,0,1]
	v_pk_fma_f32 v[160:161], v[140:141], v[158:159], v[160:161] op_sel_hi:[1,0,1]
	v_pk_mul_f32 v[162:163], v[150:151], v[158:159] op_sel:[0,1]
	v_pk_fma_f32 v[174:175], v[140:141], v[172:173], v[174:175] op_sel_hi:[1,0,1]
	v_pk_fma_f32 v[8:9], v[140:141], v[26:27], v[8:9] op_sel_hi:[1,0,1]
	v_pk_mul_f32 v[140:141], v[164:165], v[20:21] op_sel:[0,1]
	v_pk_fma_f32 v[162:163], v[144:145], v[158:159], v[162:163] op_sel_hi:[1,0,1]
	v_pk_mul_f32 v[166:167], v[158:159], v[164:165] op_sel:[1,0]
	v_xor_b32_e32 v182, 0x80000000, v161
	v_mov_b32_e32 v183, v160
	v_pk_fma_f32 v[20:21], v[146:147], v[20:21], v[140:141] op_sel_hi:[1,0,1]
	v_pk_mul_f32 v[140:141], v[170:171], v[28:29] op_sel:[0,1]
	v_pk_fma_f32 v[166:167], v[146:147], v[158:159], v[166:167] op_sel_hi:[1,0,1]
	v_xor_b32_e32 v186, 0x80000000, v163
	v_mov_b32_e32 v187, v162
	v_pk_fma_f32 v[28:29], v[158:159], v[28:29], v[140:141] op_sel_hi:[1,0,1]
	v_pk_mul_f32 v[140:141], v[182:183], v[24:25] op_sel:[0,1]
	v_xor_b32_e32 v190, 0x80000000, v167
	v_mov_b32_e32 v191, v166
	v_pk_fma_f32 v[24:25], v[160:161], v[24:25], v[140:141] op_sel_hi:[1,0,1]
	v_pk_mul_f32 v[140:141], v[186:187], v[30:31] op_sel:[0,1]
	v_pk_mul_f32 v[176:177], v[150:151], v[172:173] op_sel:[0,1]
	v_pk_fma_f32 v[30:31], v[162:163], v[30:31], v[140:141] op_sel_hi:[1,0,1]
	v_pk_mul_f32 v[140:141], v[190:191], v[12:13] op_sel:[0,1]
	v_pk_fma_f32 v[176:177], v[144:145], v[172:173], v[176:177] op_sel_hi:[1,0,1]
	v_pk_fma_f32 v[12:13], v[166:167], v[12:13], v[140:141] op_sel_hi:[1,0,1]
	v_pk_mul_f32 v[140:141], v[172:173], v[10:11] op_sel:[1,1] op_sel_hi:[0,1] neg_lo:[1,0]
	v_pk_mul_f32 v[178:179], v[164:165], v[172:173] op_sel:[0,1]
	v_pk_fma_f32 v[10:11], v[172:173], v[10:11], v[140:141] op_sel_hi:[1,0,1]
	v_pk_mul_f32 v[140:141], v[174:175], v[4:5] op_sel:[1,1] op_sel_hi:[0,1] neg_lo:[1,0]
	v_pk_fma_f32 v[178:179], v[146:147], v[172:173], v[178:179] op_sel_hi:[1,0,1]
	v_pk_fma_f32 v[4:5], v[174:175], v[4:5], v[140:141] op_sel_hi:[1,0,1]
	v_pk_mul_f32 v[140:141], v[176:177], v[22:23] op_sel:[1,1] op_sel_hi:[0,1] neg_lo:[1,0]
	v_pk_mul_f32 v[180:181], v[170:171], v[172:173] op_sel:[0,1]
	v_pk_fma_f32 v[22:23], v[176:177], v[22:23], v[140:141] op_sel_hi:[1,0,1]
	v_pk_fma_f32 v[180:181], v[158:159], v[172:173], v[180:181] op_sel_hi:[1,0,1]
	v_pk_mul_f32 v[140:141], v[178:179], v[0:1] op_sel:[1,1] op_sel_hi:[0,1] neg_lo:[1,0]
	v_pk_mul_f32 v[184:185], v[172:173], v[182:183] op_sel:[1,0]
	v_pk_fma_f32 v[0:1], v[178:179], v[0:1], v[140:141] op_sel_hi:[1,0,1]
	v_pk_fma_f32 v[184:185], v[160:161], v[172:173], v[184:185] op_sel_hi:[1,0,1]
	v_pk_mul_f32 v[140:141], v[180:181], v[18:19] op_sel:[1,1] op_sel_hi:[0,1] neg_lo:[1,0]
	v_pk_mul_f32 v[188:189], v[172:173], v[186:187] op_sel:[1,0]
	v_pk_fma_f32 v[18:19], v[180:181], v[18:19], v[140:141] op_sel_hi:[1,0,1]
	v_pk_fma_f32 v[188:189], v[162:163], v[172:173], v[188:189] op_sel_hi:[1,0,1]
	v_pk_mul_f32 v[140:141], v[184:185], v[14:15] op_sel:[1,1] op_sel_hi:[0,1] neg_lo:[1,0]
	v_pk_mul_f32 v[192:193], v[172:173], v[190:191] op_sel:[1,0]
	v_pk_fma_f32 v[14:15], v[184:185], v[14:15], v[140:141] op_sel_hi:[1,0,1]
	v_pk_fma_f32 v[192:193], v[166:167], v[172:173], v[192:193] op_sel_hi:[1,0,1]
	v_pk_mul_f32 v[140:141], v[188:189], v[16:17] op_sel:[1,1] op_sel_hi:[0,1] neg_lo:[1,0]
	v_cmp_lt_i32_e32 vcc, -1, v66
	v_pk_fma_f32 v[16:17], v[188:189], v[16:17], v[140:141] op_sel_hi:[1,0,1]
	v_pk_mul_f32 v[26:27], v[150:151], v[194:195] op_sel:[0,1]
	v_pk_mul_f32 v[140:141], v[192:193], v[6:7] op_sel:[1,1] op_sel_hi:[0,1] neg_lo:[1,0]
	v_add_u32_e32 v66, 0x400, v66
	s_or_b64 s[92:93], vcc, s[92:93]
	v_pk_fma_f32 v[26:27], v[144:145], v[194:195], v[26:27] op_sel_hi:[1,0,1]
	v_pk_fma_f32 v[6:7], v[192:193], v[6:7], v[140:141] op_sel_hi:[1,0,1]
	ds_write_b64 v136, v[34:35]
	ds_write_b64 v138, v[2:3]
	ds_write_b64 v136, v[50:51] offset:8256
	ds_write_b64 v138, v[10:11] offset:8256
	ds_write_b64 v136, v[148:149] offset:4128
	ds_write_b64 v138, v[28:29] offset:4128
	ds_write_b64 v136, v[38:39] offset:12384
	ds_write_b64 v138, v[18:19] offset:12384
	ds_write_b64 v136, v[54:55] offset:2064
	ds_write_b64 v138, v[26:27] offset:2064
	ds_write_b64 v136, v[46:47] offset:10320
	ds_write_b64 v138, v[22:23] offset:10320
	ds_write_b64 v136, v[154:155] offset:6192
	ds_write_b64 v138, v[30:31] offset:6192
	ds_write_b64 v136, v[40:41] offset:14448
	ds_write_b64 v138, v[16:17] offset:14448
	ds_write_b64 v136, v[44:45] offset:1032
	ds_write_b64 v138, v[8:9] offset:1032
	ds_write_b64 v136, v[36:37] offset:9288
	ds_write_b64 v138, v[4:5] offset:9288
	ds_write_b64 v136, v[152:153] offset:5160
	ds_write_b64 v138, v[24:25] offset:5160
	ds_write_b64 v136, v[52:53] offset:13416
	ds_write_b64 v138, v[14:15] offset:13416
	ds_write_b64 v136, v[32:33] offset:3096
	ds_write_b64 v138, v[20:21] offset:3096
	ds_write_b64 v136, v[48:49] offset:11352
	ds_write_b64 v138, v[0:1] offset:11352
	ds_write_b64 v136, v[156:157] offset:7224
	ds_write_b64 v138, v[12:13] offset:7224
	ds_write_b64 v136, v[42:43] offset:15480
	ds_write_b64 v138, v[6:7] offset:15480
	s_andn2_b64 exec, exec, s[92:93]
	s_cbranch_execnz .LBB0_347

.LBB0_350:
	v_ashrrev_i32_e32 v1, 7, v0
	v_mov_b32_e32 v34, v1
	v_add_u32_e32 v2, 0x200, v0
	v_cvt_f32_i32_e32 v34, v34
	v_ashrrev_i32_e32 v2, 7, v2
	v_mov_b32_e32 v66, v2
	v_lshl_add_u32 v1, v1, 3, v196
	v_mul_f32_e32 v35, 0x3c000000, v34
	v_lshl_add_u32 v136, v2, 3, v196
	ds_read2_b64 v[2:5], v1 offset1:16
	ds_read2_b64 v[6:9], v136 offset1:16
	ds_read2_b64 v[10:13], v1 offset0:32 offset1:48
	ds_read2_b64 v[14:17], v136 offset0:32 offset1:48
	ds_read2_b64 v[18:21], v1 offset0:64 offset1:80
	ds_read2_b64 v[22:25], v136 offset0:64 offset1:80
	ds_read2_b64 v[26:29], v1 offset0:96 offset1:112
	ds_read2_b64 v[30:33], v136 offset0:96 offset1:112
	v_cos_f32_e32 v34, v35
	v_sin_f32_e32 v36, v35
	s_waitcnt lgkmcnt(3)
	v_pk_add_f32 v[54:55], v[2:3], v[18:19]
	v_pk_add_f32 v[2:3], v[2:3], v[18:19] neg_lo:[0,1] neg_hi:[0,1]
	v_pk_add_f32 v[18:19], v[4:5], v[20:21]
	v_pk_add_f32 v[4:5], v[4:5], v[20:21] neg_lo:[0,1] neg_hi:[0,1]
	v_mov_b32_e32 v37, v34
	v_mul_f32_e32 v20, 0x3f3504f3, v5
	v_pk_fma_f32 v[4:5], v[4:5], s[56:57], v[20:21] op_sel_hi:[0,1,0]
	s_waitcnt lgkmcnt(1)
	v_pk_add_f32 v[20:21], v[10:11], v[26:27]
	v_pk_add_f32 v[10:11], v[10:11], v[26:27] neg_lo:[0,1] neg_hi:[0,1]
	v_xor_b32_e32 v35, 0x80000000, v36
	v_pk_mul_f32 v[38:39], v[36:37], v[36:37] op_sel_hi:[1,0] neg_lo:[0,1] neg_hi:[0,1]
	v_xor_b32_e32 v27, 0x80000000, v10
	v_mov_b32_e32 v26, v11
	v_pk_add_f32 v[10:11], v[12:13], v[28:29]
	v_pk_add_f32 v[12:13], v[12:13], v[28:29] neg_lo:[0,1] neg_hi:[0,1]
	v_pk_fma_f32 v[38:39], v[34:35], v[34:35], v[38:39] op_sel_hi:[1,0,1]
	v_mul_f32_e32 v28, 0xbf3504f3, v12
	v_pk_fma_f32 v[12:13], v[12:13], s[56:57], v[28:29] op_sel:[1,0,0] op_sel_hi:[1,1,0]
	v_pk_add_f32 v[28:29], v[54:55], v[20:21]
	v_pk_add_f32 v[20:21], v[54:55], v[20:21] neg_lo:[0,1] neg_hi:[0,1]
	v_pk_add_f32 v[54:55], v[18:19], v[10:11]
	v_pk_add_f32 v[10:11], v[18:19], v[10:11] neg_lo:[0,1] neg_hi:[0,1]
	v_pk_mul_f32 v[40:41], v[36:37], v[38:39] op_sel:[0,1]
	v_pk_mul_f32 v[44:45], v[38:39], v[38:39] op_sel:[1,1] op_sel_hi:[1,0] neg_lo:[0,1]
	v_xor_b32_e32 v19, 0x80000000, v10
	v_mov_b32_e32 v18, v11
	v_pk_add_f32 v[10:11], v[2:3], v[26:27]
	v_pk_add_f32 v[2:3], v[2:3], v[26:27] neg_lo:[0,1] neg_hi:[0,1]
	v_pk_add_f32 v[26:27], v[4:5], v[12:13]
	v_pk_add_f32 v[4:5], v[4:5], v[12:13] neg_lo:[0,1] neg_hi:[0,1]
	v_pk_fma_f32 v[40:41], v[34:35], v[38:39], v[40:41] op_sel_hi:[1,0,1]
	v_pk_fma_f32 v[44:45], v[38:39], v[38:39], v[44:45] op_sel_hi:[1,0,1]
	v_xor_b32_e32 v13, 0x80000000, v4
	v_mov_b32_e32 v12, v5
	v_pk_add_f32 v[4:5], v[28:29], v[54:55]
	v_pk_add_f32 v[28:29], v[28:29], v[54:55] neg_lo:[0,1] neg_hi:[0,1]
	v_pk_add_f32 v[54:55], v[20:21], v[18:19]
	v_pk_add_f32 v[18:19], v[20:21], v[18:19] neg_lo:[0,1] neg_hi:[0,1]
	v_pk_add_f32 v[20:21], v[10:11], v[26:27]
	v_pk_mul_f32 v[46:47], v[36:37], v[44:45] op_sel:[0,1]
	v_pk_add_f32 v[10:11], v[10:11], v[26:27] neg_lo:[0,1] neg_hi:[0,1]
	v_pk_add_f32 v[26:27], v[2:3], v[12:13]
	v_pk_add_f32 v[2:3], v[2:3], v[12:13] neg_lo:[0,1] neg_hi:[0,1]
	v_pk_mul_f32 v[12:13], v[36:37], v[20:21] op_sel:[0,1]
	v_pk_fma_f32 v[46:47], v[34:35], v[44:45], v[46:47] op_sel_hi:[1,0,1]
	v_pk_fma_f32 v[12:13], v[34:35], v[20:21], v[12:13] op_sel_hi:[1,0,1]
	v_pk_mul_f32 v[34:35], v[40:41], v[26:27] op_sel:[1,1] op_sel_hi:[0,1] neg_lo:[1,0]
	v_pk_mul_f32 v[48:49], v[38:39], v[44:45] op_sel:[1,1] op_sel_hi:[0,1] neg_lo:[1,0]
	v_pk_fma_f32 v[26:27], v[40:41], v[26:27], v[34:35] op_sel_hi:[1,0,1]
	v_pk_mul_f32 v[34:35], v[44:45], v[28:29] op_sel:[1,1] op_sel_hi:[0,1] neg_lo:[1,0]
	v_pk_fma_f32 v[48:49], v[38:39], v[44:45], v[48:49] op_sel_hi:[1,0,1]
	v_pk_fma_f32 v[28:29], v[44:45], v[28:29], v[34:35] op_sel_hi:[1,0,1]
	v_pk_mul_f32 v[34:35], v[46:47], v[10:11] op_sel:[1,1] op_sel_hi:[0,1] neg_lo:[1,0]
	v_pk_mul_f32 v[52:53], v[44:45], v[40:41] op_sel:[1,1] op_sel_hi:[1,0] neg_lo:[0,1]
	v_pk_fma_f32 v[10:11], v[46:47], v[10:11], v[34:35] op_sel_hi:[1,0,1]
	v_pk_fma_f32 v[52:53], v[40:41], v[44:45], v[52:53] op_sel_hi:[1,0,1]
	v_pk_mul_f32 v[34:35], v[48:49], v[18:19] op_sel:[1,1] op_sel_hi:[0,1] neg_lo:[1,0]
	v_pk_mul_f32 v[20:21], v[38:39], v[54:55] op_sel:[1,1] op_sel_hi:[0,1] neg_lo:[1,0]
	v_pk_fma_f32 v[18:19], v[48:49], v[18:19], v[34:35] op_sel_hi:[1,0,1]
	v_pk_mul_f32 v[34:35], v[52:53], v[2:3] op_sel:[1,1] op_sel_hi:[0,1] neg_lo:[1,0]
	v_pk_fma_f32 v[20:21], v[38:39], v[54:55], v[20:21] op_sel_hi:[1,0,1]
	v_pk_fma_f32 v[2:3], v[52:53], v[2:3], v[34:35] op_sel_hi:[1,0,1]
	v_cvt_f32_i32_e32 v34, v66
	v_pk_add_f32 v[54:55], v[6:7], v[22:23]
	v_pk_add_f32 v[6:7], v[6:7], v[22:23] neg_lo:[0,1] neg_hi:[0,1]
	v_pk_add_f32 v[22:23], v[8:9], v[24:25]
	v_mul_f32_e32 v35, 0x3c000000, v34
	v_cos_f32_e32 v34, v35
	v_sin_f32_e32 v36, v35
	v_pk_add_f32 v[8:9], v[8:9], v[24:25] neg_lo:[0,1] neg_hi:[0,1]
	v_cmp_lt_i32_e32 vcc, s28, v0
	v_mul_f32_e32 v24, 0x3f3504f3, v9
	v_mov_b32_e32 v37, v34
	v_pk_fma_f32 v[8:9], v[8:9], s[56:57], v[24:25] op_sel_hi:[0,1,0]
	s_waitcnt lgkmcnt(0)
	v_pk_add_f32 v[24:25], v[14:15], v[30:31]
	v_pk_add_f32 v[14:15], v[14:15], v[30:31] neg_lo:[0,1] neg_hi:[0,1]
	v_xor_b32_e32 v35, 0x80000000, v36
	v_pk_mul_f32 v[38:39], v[36:37], v[36:37] op_sel_hi:[1,0] neg_lo:[0,1] neg_hi:[0,1]
	v_xor_b32_e32 v31, 0x80000000, v14
	v_mov_b32_e32 v30, v15
	v_pk_add_f32 v[14:15], v[16:17], v[32:33]
	v_pk_add_f32 v[16:17], v[16:17], v[32:33] neg_lo:[0,1] neg_hi:[0,1]
	v_pk_fma_f32 v[38:39], v[34:35], v[34:35], v[38:39] op_sel_hi:[1,0,1]
	v_mul_f32_e32 v32, 0xbf3504f3, v16
	v_xor_b32_e32 v42, 0x80000000, v39
	v_mov_b32_e32 v43, v38
	v_pk_fma_f32 v[16:17], v[16:17], s[56:57], v[32:33] op_sel:[1,0,0] op_sel_hi:[1,1,0]
	v_pk_add_f32 v[32:33], v[54:55], v[24:25]
	v_pk_add_f32 v[24:25], v[54:55], v[24:25] neg_lo:[0,1] neg_hi:[0,1]
	v_pk_add_f32 v[54:55], v[22:23], v[14:15]
	v_pk_add_f32 v[14:15], v[22:23], v[14:15] neg_lo:[0,1] neg_hi:[0,1]
	v_pk_mul_f32 v[40:41], v[36:37], v[38:39] op_sel:[0,1]
	v_pk_mul_f32 v[44:45], v[38:39], v[42:43] op_sel:[1,0]
	v_xor_b32_e32 v23, 0x80000000, v14
	v_mov_b32_e32 v22, v15
	v_pk_add_f32 v[14:15], v[6:7], v[30:31]
	v_pk_add_f32 v[6:7], v[6:7], v[30:31] neg_lo:[0,1] neg_hi:[0,1]
	v_pk_add_f32 v[30:31], v[8:9], v[16:17]
	v_pk_add_f32 v[8:9], v[8:9], v[16:17] neg_lo:[0,1] neg_hi:[0,1]
	v_pk_fma_f32 v[40:41], v[34:35], v[38:39], v[40:41] op_sel_hi:[1,0,1]
	v_pk_fma_f32 v[44:45], v[38:39], v[38:39], v[44:45] op_sel_hi:[1,0,1]
	v_xor_b32_e32 v17, 0x80000000, v8
	v_mov_b32_e32 v16, v9
	v_pk_add_f32 v[8:9], v[32:33], v[54:55]
	v_pk_add_f32 v[32:33], v[32:33], v[54:55] neg_lo:[0,1] neg_hi:[0,1]
	v_pk_add_f32 v[54:55], v[24:25], v[22:23]
	v_pk_add_f32 v[22:23], v[24:25], v[22:23] neg_lo:[0,1] neg_hi:[0,1]
	v_pk_add_f32 v[24:25], v[14:15], v[30:31]
	v_pk_mul_f32 v[46:47], v[36:37], v[44:45] op_sel:[0,1]
	v_xor_b32_e32 v50, 0x80000000, v41
	v_mov_b32_e32 v51, v40
	v_pk_add_f32 v[14:15], v[14:15], v[30:31] neg_lo:[0,1] neg_hi:[0,1]
	v_pk_add_f32 v[30:31], v[6:7], v[16:17]
	v_pk_add_f32 v[6:7], v[6:7], v[16:17] neg_lo:[0,1] neg_hi:[0,1]
	v_pk_mul_f32 v[16:17], v[36:37], v[24:25] op_sel:[0,1]
	v_pk_fma_f32 v[46:47], v[34:35], v[44:45], v[46:47] op_sel_hi:[1,0,1]
	v_pk_fma_f32 v[16:17], v[34:35], v[24:25], v[16:17] op_sel_hi:[1,0,1]
	v_pk_mul_f32 v[34:35], v[50:51], v[30:31] op_sel:[0,1]
	v_pk_mul_f32 v[48:49], v[42:43], v[44:45] op_sel:[0,1]
	v_pk_fma_f32 v[30:31], v[40:41], v[30:31], v[34:35] op_sel_hi:[1,0,1]
	v_pk_mul_f32 v[34:35], v[44:45], v[32:33] op_sel:[1,1] op_sel_hi:[0,1] neg_lo:[1,0]
	v_pk_fma_f32 v[48:49], v[38:39], v[44:45], v[48:49] op_sel_hi:[1,0,1]
	v_pk_fma_f32 v[32:33], v[44:45], v[32:33], v[34:35] op_sel_hi:[1,0,1]
	v_pk_mul_f32 v[34:35], v[46:47], v[14:15] op_sel:[1,1] op_sel_hi:[0,1] neg_lo:[1,0]
	v_pk_mul_f32 v[52:53], v[44:45], v[50:51] op_sel:[1,0]
	v_pk_fma_f32 v[14:15], v[46:47], v[14:15], v[34:35] op_sel_hi:[1,0,1]
	v_pk_fma_f32 v[52:53], v[40:41], v[44:45], v[52:53] op_sel_hi:[1,0,1]
	v_pk_mul_f32 v[34:35], v[48:49], v[22:23] op_sel:[1,1] op_sel_hi:[0,1] neg_lo:[1,0]
	v_pk_mul_f32 v[24:25], v[42:43], v[54:55] op_sel:[0,1]
	v_pk_fma_f32 v[22:23], v[48:49], v[22:23], v[34:35] op_sel_hi:[1,0,1]
	v_pk_mul_f32 v[34:35], v[52:53], v[6:7] op_sel:[1,1] op_sel_hi:[0,1] neg_lo:[1,0]
	v_add_u32_e32 v0, 0x400, v0
	s_or_b64 s[92:93], vcc, s[92:93]
	v_pk_fma_f32 v[24:25], v[38:39], v[54:55], v[24:25] op_sel_hi:[1,0,1]
	v_pk_fma_f32 v[6:7], v[52:53], v[6:7], v[34:35] op_sel_hi:[1,0,1]
	ds_write_b64 v1, v[4:5]
	ds_write_b64 v136, v[8:9]
	ds_write_b64 v1, v[28:29] offset:512
	ds_write_b64 v136, v[32:33] offset:512
	ds_write_b64 v1, v[20:21] offset:256
	ds_write_b64 v136, v[24:25] offset:256
	ds_write_b64 v1, v[18:19] offset:768
	ds_write_b64 v136, v[22:23] offset:768
	ds_write_b64 v1, v[12:13] offset:128
	ds_write_b64 v136, v[16:17] offset:128
	ds_write_b64 v1, v[10:11] offset:640
	ds_write_b64 v136, v[14:15] offset:640
	ds_write_b64 v1, v[26:27] offset:384
	ds_write_b64 v136, v[30:31] offset:384
	ds_write_b64 v1, v[2:3] offset:896
	ds_write_b64 v136, v[6:7] offset:896
	s_andn2_b64 exec, exec, s[92:93]
	s_cbranch_execnz .LBB0_350
.LBB0_351:
	s_or_b64 exec, exec, s[90:91]
	v_ashrrev_i32_e32 v254, 3, v56
	v_and_b32_e32 v254, -16, v254
	v_add_u32_e32 v254, v254, v197
	v_ashrrev_i32_e32 v255, 31, v254
	v_lshl_add_u64 v[250:251], v[254:255], 3, s[86:87]
	v_add_u32_e32 v254, 0x200, v56
	v_ashrrev_i32_e32 v254, 3, v254
	v_and_b32_e32 v254, -16, v254
	v_add_u32_e32 v254, v254, v197
	v_ashrrev_i32_e32 v255, 31, v254
	v_lshl_add_u64 v[254:255], v[254:255], 3, s[86:87]
	global_load_dwordx4 v[104:107], v[250:251], off offset:48
	global_load_dwordx4 v[108:111], v[250:251], off offset:32
	global_load_dwordx4 v[112:115], v[250:251], off offset:16
	global_load_dwordx4 v[116:119], v[250:251], off
	global_load_dwordx4 v[120:123], v[254:255], off offset:48
	global_load_dwordx4 v[124:127], v[254:255], off offset:32
	global_load_dwordx4 v[128:131], v[254:255], off offset:16
	global_load_dwordx4 v[132:135], v[254:255], off
	global_load_dwordx4 v[228:231], v[250:251], off offset:112
	global_load_dwordx4 v[232:235], v[250:251], off offset:96
	global_load_dwordx4 v[236:239], v[250:251], off offset:80
	global_load_dwordx4 v[246:249], v[250:251], off offset:64
	s_waitcnt lgkmcnt(0)
	s_barrier
	s_and_saveexec_b64 s[90:91], s[6:7]
	s_cbranch_execz .LBB0_354
	s_mov_b64 s[92:93], 0
	v_mov_b32_e32 v42, v56
.LBB0_353:
	v_ashrrev_i32_e32 v0, 3, v42
	v_add_u32_e32 v1, 0x200, v42
	v_and_b32_e32 v0, -16, v0
	v_ashrrev_i32_e32 v1, 3, v1
	v_and_b32_e32 v1, -16, v1
	v_lshl_add_u32 v43, v0, 3, v196
	v_add_u32_e32 v32, v0, v197
	v_add_u32_e32 v34, v1, v197
	v_lshl_add_u32 v44, v1, 3, v196
	ds_read2_b64 v[46:49], v43 offset1:1
	ds_read2_b64 v[20:23], v44 offset1:1
	ds_read2_b64 v[50:53], v43 offset0:2 offset1:3
	ds_read2_b64 v[12:15], v44 offset0:2 offset1:3
	ds_read2_b64 v[136:139], v43 offset0:4 offset1:5
	ds_read2_b64 v[4:7], v44 offset0:4 offset1:5
	ds_read2_b64 v[140:143], v43 offset0:6 offset1:7
	ds_read2_b64 v[0:3], v44 offset0:6 offset1:7
	ds_read2_b64 v[144:147], v43 offset0:8 offset1:9
	ds_read2_b64 v[28:31], v44 offset0:8 offset1:9
	ds_read2_b64 v[148:151], v43 offset0:10 offset1:11
	ds_read2_b64 v[24:27], v44 offset0:10 offset1:11
	ds_read2_b64 v[152:155], v43 offset0:12 offset1:13
	ds_read2_b64 v[16:19], v44 offset0:12 offset1:13
	ds_read2_b64 v[156:159], v43 offset0:14 offset1:15
	ds_read2_b64 v[8:11], v44 offset0:14 offset1:15
	s_waitcnt lgkmcnt(7)
	v_pk_add_f32 v[38:39], v[46:47], v[144:145]
	v_pk_add_f32 v[36:37], v[46:47], v[144:145] neg_lo:[0,1] neg_hi:[0,1]
	v_pk_add_f32 v[46:47], v[48:49], v[146:147] neg_lo:[0,1] neg_hi:[0,1]
	v_pk_add_f32 v[40:41], v[48:49], v[146:147]
	v_pk_mul_f32 v[48:49], v[46:47], s[42:43] op_sel_hi:[0,1]
	s_mov_b32 s65, s42
	v_pk_fma_f32 v[46:47], v[46:47], s[64:65], v[48:49] op_sel:[1,0,0]
	s_waitcnt lgkmcnt(5)
	v_pk_add_f32 v[48:49], v[50:51], v[148:149]
	v_pk_add_f32 v[50:51], v[50:51], v[148:149] neg_lo:[0,1] neg_hi:[0,1]
	s_mov_b32 s66, s64
	v_mul_f32_e32 v54, 0x3f3504f3, v51
	v_pk_fma_f32 v[50:51], v[50:51], s[56:57], v[54:55] op_sel_hi:[0,1,0]
	v_pk_add_f32 v[54:55], v[52:53], v[150:151]
	v_pk_add_f32 v[52:53], v[52:53], v[150:151] neg_lo:[0,1] neg_hi:[0,1]
	s_mov_b32 s40, s42
	v_pk_mul_f32 v[144:145], v[52:53], s[66:67] op_sel_hi:[0,1]
	s_mov_b32 s41, s64
	v_pk_fma_f32 v[52:53], v[52:53], s[40:41], v[144:145] op_sel:[1,0,0]
	s_waitcnt lgkmcnt(3)
	v_pk_add_f32 v[144:145], v[136:137], v[152:153]
	v_pk_add_f32 v[136:137], v[136:137], v[152:153] neg_lo:[0,1] neg_hi:[0,1]
	s_mov_b32 s44, s43
	v_xor_b32_e32 v147, 0x80000000, v136
	v_mov_b32_e32 v146, v137
	v_pk_add_f32 v[136:137], v[138:139], v[154:155]
	v_pk_add_f32 v[138:139], v[138:139], v[154:155] neg_lo:[0,1] neg_hi:[0,1]
	s_mov_b32 s45, s67
	v_pk_mul_f32 v[148:149], v[138:139], s[44:45] op_sel_hi:[0,1]
	s_waitcnt lgkmcnt(1)
	v_pk_add_f32 v[150:151], v[142:143], v[158:159]
	v_pk_add_f32 v[142:143], v[142:143], v[158:159] neg_lo:[0,1] neg_hi:[0,1]
	s_mov_b32 s58, s67
	s_mov_b32 s59, s43
	v_pk_fma_f32 v[138:139], v[138:139], s[42:43], v[148:149] op_sel:[1,0,0]
	v_pk_add_f32 v[148:149], v[140:141], v[156:157]
	v_pk_add_f32 v[140:141], v[140:141], v[156:157] neg_lo:[0,1] neg_hi:[0,1]
	v_pk_mul_f32 v[152:153], v[142:143], s[58:59] op_sel_hi:[0,1]
	v_mul_f32_e32 v66, 0xbf3504f3, v140
	v_pk_fma_f32 v[142:143], v[142:143], s[66:67], v[152:153] op_sel:[1,0,0]
	v_pk_add_f32 v[152:153], v[38:39], v[144:145]
	v_pk_add_f32 v[38:39], v[38:39], v[144:145] neg_lo:[0,1] neg_hi:[0,1]
	v_pk_add_f32 v[144:145], v[40:41], v[136:137]
	v_pk_add_f32 v[40:41], v[40:41], v[136:137] neg_lo:[0,1] neg_hi:[0,1]
	v_pk_add_f32 v[136:137], v[48:49], v[148:149]
	v_pk_add_f32 v[48:49], v[48:49], v[148:149] neg_lo:[0,1] neg_hi:[0,1]
	v_pk_fma_f32 v[140:141], v[140:141], s[56:57], v[66:67] op_sel:[1,0,0] op_sel_hi:[1,1,0]
	v_mul_f32_e32 v66, 0x3f3504f3, v41
	v_xor_b32_e32 v149, 0x80000000, v48
	v_mov_b32_e32 v148, v49
	v_pk_add_f32 v[48:49], v[54:55], v[150:151]
	v_pk_add_f32 v[54:55], v[54:55], v[150:151] neg_lo:[0,1] neg_hi:[0,1]
	v_pk_fma_f32 v[40:41], v[40:41], s[56:57], v[66:67] op_sel_hi:[0,1,0]
	v_mul_f32_e32 v66, 0xbf3504f3, v54
	v_pk_add_f32 v[150:151], v[36:37], v[146:147]
	v_pk_add_f32 v[36:37], v[36:37], v[146:147] neg_lo:[0,1] neg_hi:[0,1]
	v_pk_add_f32 v[146:147], v[46:47], v[138:139]
	v_pk_add_f32 v[46:47], v[46:47], v[138:139] neg_lo:[0,1] neg_hi:[0,1]
	v_pk_add_f32 v[138:139], v[50:51], v[140:141]
	v_pk_add_f32 v[50:51], v[50:51], v[140:141] neg_lo:[0,1] neg_hi:[0,1]
	v_pk_fma_f32 v[54:55], v[54:55], s[56:57], v[66:67] op_sel:[1,0,0] op_sel_hi:[1,1,0]
	v_xor_b32_e32 v141, 0x80000000, v50
	v_mov_b32_e32 v140, v51
	v_pk_add_f32 v[50:51], v[52:53], v[142:143]
	v_pk_add_f32 v[52:53], v[52:53], v[142:143] neg_lo:[0,1] neg_hi:[0,1]
	v_pk_add_f32 v[142:143], v[152:153], v[136:137]
	v_pk_add_f32 v[136:137], v[152:153], v[136:137] neg_lo:[0,1] neg_hi:[0,1]
	v_pk_add_f32 v[152:153], v[144:145], v[48:49]
	v_pk_add_f32 v[48:49], v[144:145], v[48:49] neg_lo:[0,1] neg_hi:[0,1]
	v_mul_f32_e32 v66, 0x3f3504f3, v47
	v_xor_b32_e32 v145, 0x80000000, v48
	v_mov_b32_e32 v144, v49
	v_pk_add_f32 v[48:49], v[38:39], v[148:149]
	v_pk_add_f32 v[38:39], v[38:39], v[148:149] neg_lo:[0,1] neg_hi:[0,1]
	v_pk_add_f32 v[148:149], v[40:41], v[54:55]
	v_pk_fma_f32 v[46:47], v[46:47], s[56:57], v[66:67] op_sel_hi:[0,1,0]
	v_pk_add_f32 v[160:161], v[48:49], v[148:149]
	v_pk_add_f32 v[162:163], v[48:49], v[148:149] neg_lo:[0,1] neg_hi:[0,1]
	v_pk_add_f32 v[48:49], v[20:21], v[28:29]
	v_pk_add_f32 v[20:21], v[20:21], v[28:29] neg_lo:[0,1] neg_hi:[0,1]
	v_pk_add_f32 v[28:29], v[22:23], v[30:31]
	v_pk_add_f32 v[22:23], v[22:23], v[30:31] neg_lo:[0,1] neg_hi:[0,1]
	v_mul_f32_e32 v66, 0xbf3504f3, v52
	v_pk_mul_f32 v[30:31], v[22:23], s[42:43] op_sel_hi:[0,1]
	v_pk_fma_f32 v[22:23], v[22:23], s[64:65], v[30:31] op_sel:[1,0,0]
	v_pk_add_f32 v[30:31], v[12:13], v[24:25]
	v_pk_add_f32 v[12:13], v[12:13], v[24:25] neg_lo:[0,1] neg_hi:[0,1]
	v_pk_add_f32 v[40:41], v[40:41], v[54:55] neg_lo:[0,1] neg_hi:[0,1]
	v_mul_f32_e32 v24, 0x3f3504f3, v13
	v_pk_fma_f32 v[12:13], v[12:13], s[56:57], v[24:25] op_sel_hi:[0,1,0]
	v_pk_add_f32 v[24:25], v[14:15], v[26:27]
	v_pk_add_f32 v[14:15], v[14:15], v[26:27] neg_lo:[0,1] neg_hi:[0,1]
	v_pk_fma_f32 v[52:53], v[52:53], s[56:57], v[66:67] op_sel:[1,0,0] op_sel_hi:[1,1,0]
	v_pk_mul_f32 v[26:27], v[14:15], s[66:67] op_sel_hi:[0,1]
	v_pk_fma_f32 v[14:15], v[14:15], s[40:41], v[26:27] op_sel:[1,0,0]
	v_pk_add_f32 v[26:27], v[4:5], v[16:17]
	v_pk_add_f32 v[4:5], v[4:5], v[16:17] neg_lo:[0,1] neg_hi:[0,1]
	v_xor_b32_e32 v55, 0x80000000, v40
	v_xor_b32_e32 v17, 0x80000000, v4
	v_mov_b32_e32 v16, v5
	v_pk_add_f32 v[4:5], v[6:7], v[18:19]
	v_pk_add_f32 v[6:7], v[6:7], v[18:19] neg_lo:[0,1] neg_hi:[0,1]
	v_mov_b32_e32 v54, v41
	v_pk_mul_f32 v[18:19], v[6:7], s[44:45] op_sel_hi:[0,1]
	v_pk_fma_f32 v[6:7], v[6:7], s[42:43], v[18:19] op_sel:[1,0,0]
	s_waitcnt lgkmcnt(0)
	v_pk_add_f32 v[18:19], v[0:1], v[8:9]
	v_pk_add_f32 v[0:1], v[0:1], v[8:9] neg_lo:[0,1] neg_hi:[0,1]
	v_pk_add_f32 v[40:41], v[150:151], v[138:139]
	v_mul_f32_e32 v8, 0xbf3504f3, v0
	v_pk_fma_f32 v[0:1], v[0:1], s[56:57], v[8:9] op_sel:[1,0,0] op_sel_hi:[1,1,0]
	v_pk_add_f32 v[8:9], v[2:3], v[10:11]
	v_pk_add_f32 v[2:3], v[2:3], v[10:11] neg_lo:[0,1] neg_hi:[0,1]
	v_pk_add_f32 v[138:139], v[150:151], v[138:139] neg_lo:[0,1] neg_hi:[0,1]
	v_pk_mul_f32 v[10:11], v[2:3], s[58:59] op_sel_hi:[0,1]
	v_pk_fma_f32 v[2:3], v[2:3], s[66:67], v[10:11] op_sel:[1,0,0]
	v_pk_add_f32 v[10:11], v[48:49], v[26:27]
	v_pk_add_f32 v[26:27], v[48:49], v[26:27] neg_lo:[0,1] neg_hi:[0,1]
	v_pk_add_f32 v[48:49], v[28:29], v[4:5]
	v_pk_add_f32 v[4:5], v[28:29], v[4:5] neg_lo:[0,1] neg_hi:[0,1]
	v_pk_add_f32 v[150:151], v[146:147], v[50:51]
	v_mul_f32_e32 v28, 0x3f3504f3, v5
	v_pk_fma_f32 v[4:5], v[4:5], s[56:57], v[28:29] op_sel_hi:[0,1,0]
	v_pk_add_f32 v[28:29], v[30:31], v[18:19]
	v_pk_add_f32 v[18:19], v[30:31], v[18:19] neg_lo:[0,1] neg_hi:[0,1]
	v_pk_add_f32 v[50:51], v[146:147], v[50:51] neg_lo:[0,1] neg_hi:[0,1]
	v_xor_b32_e32 v31, 0x80000000, v18
	v_mov_b32_e32 v30, v19
	v_pk_add_f32 v[18:19], v[24:25], v[8:9]
	v_pk_add_f32 v[8:9], v[24:25], v[8:9] neg_lo:[0,1] neg_hi:[0,1]
	v_ashrrev_i32_e32 v33, 31, v32
	v_mul_f32_e32 v24, 0xbf3504f3, v8
	v_pk_fma_f32 v[8:9], v[8:9], s[56:57], v[24:25] op_sel:[1,0,0] op_sel_hi:[1,1,0]
	v_pk_add_f32 v[24:25], v[20:21], v[16:17]
	v_pk_add_f32 v[16:17], v[20:21], v[16:17] neg_lo:[0,1] neg_hi:[0,1]
	v_pk_add_f32 v[20:21], v[22:23], v[6:7]
	v_pk_add_f32 v[6:7], v[22:23], v[6:7] neg_lo:[0,1] neg_hi:[0,1]
	v_xor_b32_e32 v147, 0x80000000, v50
	v_mul_f32_e32 v22, 0x3f3504f3, v7
	v_pk_fma_f32 v[6:7], v[6:7], s[56:57], v[22:23] op_sel_hi:[0,1,0]
	v_pk_add_f32 v[22:23], v[12:13], v[0:1]
	v_pk_add_f32 v[0:1], v[12:13], v[0:1] neg_lo:[0,1] neg_hi:[0,1]
	v_mov_b32_e32 v146, v51
	v_xor_b32_e32 v13, 0x80000000, v0
	v_mov_b32_e32 v12, v1
	v_pk_add_f32 v[0:1], v[14:15], v[2:3]
	v_pk_add_f32 v[2:3], v[14:15], v[2:3] neg_lo:[0,1] neg_hi:[0,1]
	v_pk_add_f32 v[50:51], v[36:37], v[140:141]
	v_mul_f32_e32 v14, 0xbf3504f3, v2
	v_pk_fma_f32 v[2:3], v[2:3], s[56:57], v[14:15] op_sel:[1,0,0] op_sel_hi:[1,1,0]
	v_pk_add_f32 v[14:15], v[10:11], v[28:29]
	v_pk_add_f32 v[10:11], v[10:11], v[28:29] neg_lo:[0,1] neg_hi:[0,1]
	v_pk_add_f32 v[28:29], v[48:49], v[18:19]
	v_pk_add_f32 v[18:19], v[48:49], v[18:19] neg_lo:[0,1] neg_hi:[0,1]
	v_pk_add_f32 v[36:37], v[36:37], v[140:141] neg_lo:[0,1] neg_hi:[0,1]
	v_xor_b32_e32 v49, 0x80000000, v18
	v_mov_b32_e32 v48, v19
	v_pk_add_f32 v[18:19], v[26:27], v[30:31]
	v_pk_add_f32 v[26:27], v[26:27], v[30:31] neg_lo:[0,1] neg_hi:[0,1]
	v_pk_add_f32 v[30:31], v[4:5], v[8:9]
	v_pk_add_f32 v[4:5], v[4:5], v[8:9] neg_lo:[0,1] neg_hi:[0,1]
	v_pk_add_f32 v[140:141], v[46:47], v[52:53]
	v_xor_b32_e32 v9, 0x80000000, v4
	v_mov_b32_e32 v8, v5
	v_pk_add_f32 v[4:5], v[24:25], v[22:23]
	v_pk_add_f32 v[22:23], v[24:25], v[22:23] neg_lo:[0,1] neg_hi:[0,1]
	v_pk_add_f32 v[24:25], v[20:21], v[0:1]
	v_pk_add_f32 v[0:1], v[20:21], v[0:1] neg_lo:[0,1] neg_hi:[0,1]
	v_pk_add_f32 v[156:157], v[136:137], v[144:145]
	v_xor_b32_e32 v21, 0x80000000, v0
	v_mov_b32_e32 v20, v1
	v_pk_add_f32 v[0:1], v[16:17], v[12:13]
	v_pk_add_f32 v[12:13], v[16:17], v[12:13] neg_lo:[0,1] neg_hi:[0,1]
	v_pk_add_f32 v[16:17], v[6:7], v[2:3]
	v_pk_add_f32 v[2:3], v[6:7], v[2:3] neg_lo:[0,1] neg_hi:[0,1]
	v_pk_add_f32 v[158:159], v[136:137], v[144:145] neg_lo:[0,1] neg_hi:[0,1]
	v_lshl_add_u64 v[136:137], v[32:33], 3, s[86:87]
	v_pk_add_f32 v[174:175], v[50:51], v[140:141]
	v_pk_add_f32 v[176:177], v[50:51], v[140:141] neg_lo:[0,1] neg_hi:[0,1]
	v_pk_add_f32 v[50:51], v[14:15], v[28:29]
	v_pk_add_f32 v[178:179], v[14:15], v[28:29] neg_lo:[0,1] neg_hi:[0,1]
	v_pk_add_f32 v[180:181], v[10:11], v[48:49]
	v_pk_add_f32 v[182:183], v[10:11], v[48:49] neg_lo:[0,1] neg_hi:[0,1]
	v_pk_add_f32 v[188:189], v[26:27], v[8:9]
	v_pk_add_f32 v[190:191], v[26:27], v[8:9] neg_lo:[0,1] neg_hi:[0,1]
	v_pk_add_f32 v[192:193], v[4:5], v[24:25]
	v_pk_add_f32 v[194:195], v[4:5], v[24:25] neg_lo:[0,1] neg_hi:[0,1]
	v_pk_add_f32 v[220:221], v[0:1], v[16:17]
	v_pk_add_f32 v[222:223], v[0:1], v[16:17] neg_lo:[0,1] neg_hi:[0,1]
	v_pk_add_f32 v[224:225], v[12:13], v[2:3] op_sel:[0,1] op_sel_hi:[1,0] neg_hi:[0,1]
	v_pk_add_f32 v[226:227], v[12:13], v[2:3] op_sel:[0,1] op_sel_hi:[1,0] neg_lo:[0,1]
	s_waitcnt vmcnt(0)
	v_mov_b32_e32 v0, v104
	v_mov_b32_e32 v1, v105
	v_mov_b32_e32 v2, v106
	v_mov_b32_e32 v3, v107
	v_mov_b32_e32 v4, v108
	v_mov_b32_e32 v5, v109
	v_mov_b32_e32 v6, v110
	v_mov_b32_e32 v7, v111
	v_mov_b32_e32 v8, v112
	v_mov_b32_e32 v9, v113
	v_mov_b32_e32 v10, v114
	v_mov_b32_e32 v11, v115
	v_mov_b32_e32 v12, v116
	v_mov_b32_e32 v13, v117
	v_mov_b32_e32 v14, v118
	v_mov_b32_e32 v15, v119
	global_load_dwordx4 v[104:107], v[254:255], off offset:112
	global_load_dwordx4 v[108:111], v[254:255], off offset:96
	global_load_dwordx4 v[112:115], v[254:255], off offset:80
	global_load_dwordx4 v[116:119], v[254:255], off offset:64
	v_pk_add_f32 v[46:47], v[46:47], v[52:53] neg_lo:[0,1] neg_hi:[0,1]
	v_ashrrev_i32_e32 v35, 31, v34
	v_xor_b32_e32 v53, 0x80000000, v46
	v_mov_b32_e32 v52, v47
	v_pk_add_f32 v[46:47], v[142:143], v[152:153]
	v_pk_add_f32 v[142:143], v[142:143], v[152:153] neg_lo:[0,1] neg_hi:[0,1]
	v_lshl_add_u64 v[152:153], v[34:35], 3, s[86:87]
	v_pk_add_f32 v[184:185], v[18:19], v[30:31]
	v_pk_add_f32 v[186:187], v[18:19], v[30:31] neg_lo:[0,1] neg_hi:[0,1]
	v_pk_add_f32 v[216:217], v[22:23], v[20:21]
	v_pk_add_f32 v[218:219], v[22:23], v[20:21] neg_lo:[0,1] neg_hi:[0,1]
	v_pk_add_f32 v[164:165], v[38:39], v[54:55]
	v_pk_add_f32 v[54:55], v[38:39], v[54:55] neg_lo:[0,1] neg_hi:[0,1]
	v_pk_add_f32 v[170:171], v[138:139], v[146:147]
	v_pk_add_f32 v[172:173], v[138:139], v[146:147] neg_lo:[0,1] neg_hi:[0,1]
	v_pk_add_f32 v[38:39], v[36:37], v[52:53]
	v_pk_add_f32 v[36:37], v[36:37], v[52:53] neg_lo:[0,1] neg_hi:[0,1]
	v_pk_add_f32 v[166:167], v[40:41], v[150:151]
	v_pk_add_f32 v[40:41], v[40:41], v[150:151] neg_lo:[0,1] neg_hi:[0,1]
	v_cmp_lt_i32_e32 vcc, -1, v42
	v_add_u32_e32 v42, 0x400, v42
	s_or_b64 s[92:93], vcc, s[92:93]
	s_waitcnt vmcnt(4)
	v_pk_mul_f32 v[16:17], v[46:47], v[12:13] op_sel:[1,1] op_sel_hi:[1,0] neg_lo:[0,1]
	s_nop 0
	v_pk_fma_f32 v[12:13], v[12:13], v[46:47], v[16:17] op_sel_hi:[1,0,1]
	v_pk_fma_f32 v[12:13], v[46:47], v[252:253], v[12:13]
	v_mov_b32_e32 v16, v120
	v_mov_b32_e32 v17, v121
	v_mov_b32_e32 v18, v122
	v_mov_b32_e32 v19, v123
	v_mov_b32_e32 v20, v124
	v_mov_b32_e32 v21, v125
	v_mov_b32_e32 v22, v126
	v_mov_b32_e32 v23, v127
	v_mov_b32_e32 v24, v128
	v_mov_b32_e32 v25, v129
	v_mov_b32_e32 v26, v130
	v_mov_b32_e32 v27, v131
	v_mov_b32_e32 v28, v132
	v_mov_b32_e32 v29, v133
	v_mov_b32_e32 v30, v134
	v_mov_b32_e32 v31, v135
	s_waitcnt vmcnt(4)
	v_pk_mul_f32 v[32:33], v[50:51], v[28:29] op_sel:[1,1] op_sel_hi:[1,0] neg_lo:[0,1]
	s_nop 0
	v_pk_fma_f32 v[28:29], v[28:29], v[50:51], v[32:33] op_sel_hi:[1,0,1]
	v_pk_fma_f32 v[28:29], v[50:51], v[252:253], v[28:29]
	ds_write_b64 v43, v[12:13]
	ds_write_b64 v44, v[28:29]
	v_mov_b32_e32 v32, v228
	v_mov_b32_e32 v33, v229
	v_mov_b32_e32 v34, v230
	v_mov_b32_e32 v35, v231
	v_mov_b32_e32 v46, v232
	v_mov_b32_e32 v47, v233
	v_mov_b32_e32 v48, v234
	v_mov_b32_e32 v49, v235
	v_mov_b32_e32 v50, v236
	v_mov_b32_e32 v51, v237
	v_mov_b32_e32 v52, v238
	v_mov_b32_e32 v53, v239
	s_nop 0
	v_mov_b32_e32 v136, v246
	v_mov_b32_e32 v137, v247
	v_mov_b32_e32 v138, v248
	v_mov_b32_e32 v139, v249
	s_waitcnt vmcnt(4)
	v_pk_mul_f32 v[12:13], v[142:143], v[136:137] op_sel:[1,1] op_sel_hi:[1,0] neg_lo:[0,1]
	s_nop 0
	v_pk_fma_f32 v[12:13], v[142:143], v[136:137], v[12:13] op_sel_hi:[0,1,1]
	v_pk_fma_f32 v[12:13], v[142:143], v[252:253], v[12:13]
	s_nop 0
	s_waitcnt vmcnt(0)
	v_mov_b32_e32 v140, v104
	v_mov_b32_e32 v141, v105
	v_mov_b32_e32 v142, v106
	v_mov_b32_e32 v143, v107
	v_mov_b32_e32 v144, v108
	v_mov_b32_e32 v145, v109
	v_mov_b32_e32 v146, v110
	v_mov_b32_e32 v147, v111
	v_mov_b32_e32 v148, v112
	v_mov_b32_e32 v149, v113
	v_mov_b32_e32 v150, v114
	v_mov_b32_e32 v151, v115
	v_mov_b32_e32 v152, v116
	v_mov_b32_e32 v153, v117
	v_mov_b32_e32 v154, v118
	v_mov_b32_e32 v155, v119
	v_pk_mul_f32 v[28:29], v[178:179], v[152:153] op_sel:[1,1] op_sel_hi:[1,0] neg_lo:[0,1]
	s_nop 0
	v_pk_fma_f32 v[28:29], v[178:179], v[152:153], v[28:29] op_sel_hi:[0,1,1]
	v_pk_fma_f32 v[28:29], v[178:179], v[252:253], v[28:29]
	ds_write_b64 v43, v[12:13] offset:64
	ds_write_b64 v44, v[28:29] offset:64
	v_pk_mul_f32 v[12:13], v[156:157], v[4:5] op_sel:[1,1] op_sel_hi:[1,0] neg_lo:[0,1]
	s_nop 0
	v_pk_fma_f32 v[4:5], v[156:157], v[4:5], v[12:13] op_sel_hi:[0,1,1]
	v_pk_fma_f32 v[4:5], v[156:157], v[252:253], v[4:5]
	v_pk_mul_f32 v[12:13], v[180:181], v[20:21] op_sel:[1,1] op_sel_hi:[1,0] neg_lo:[0,1]
	s_nop 0
	v_pk_fma_f32 v[12:13], v[180:181], v[20:21], v[12:13] op_sel_hi:[0,1,1]
	v_pk_fma_f32 v[12:13], v[180:181], v[252:253], v[12:13]
	ds_write_b64 v43, v[4:5] offset:32
	ds_write_b64 v44, v[12:13] offset:32
	v_pk_mul_f32 v[4:5], v[158:159], v[46:47] op_sel:[1,1] op_sel_hi:[1,0] neg_lo:[0,1]
	v_pk_fma_f32 v[4:5], v[158:159], v[46:47], v[4:5] op_sel_hi:[0,1,1]
	v_pk_fma_f32 v[4:5], v[158:159], v[252:253], v[4:5]
	v_pk_mul_f32 v[12:13], v[182:183], v[144:145] op_sel:[1,1] op_sel_hi:[1,0] neg_lo:[0,1]
	s_nop 0
	v_pk_fma_f32 v[12:13], v[182:183], v[144:145], v[12:13] op_sel_hi:[0,1,1]
	v_pk_fma_f32 v[12:13], v[182:183], v[252:253], v[12:13]
	ds_write_b64 v43, v[4:5] offset:96
	ds_write_b64 v44, v[12:13] offset:96
	v_pk_mul_f32 v[4:5], v[160:161], v[8:9] op_sel:[1,1] op_sel_hi:[1,0] neg_lo:[0,1]
	s_nop 0
	v_pk_fma_f32 v[4:5], v[160:161], v[8:9], v[4:5] op_sel_hi:[0,1,1]
	v_pk_fma_f32 v[4:5], v[160:161], v[252:253], v[4:5]
	v_pk_mul_f32 v[8:9], v[184:185], v[24:25] op_sel:[1,1] op_sel_hi:[1,0] neg_lo:[0,1]
	s_nop 0
	v_pk_fma_f32 v[8:9], v[184:185], v[24:25], v[8:9] op_sel_hi:[0,1,1]
	v_pk_fma_f32 v[8:9], v[184:185], v[252:253], v[8:9]
	ds_write_b64 v43, v[4:5] offset:16
	ds_write_b64 v44, v[8:9] offset:16
	v_pk_mul_f32 v[4:5], v[162:163], v[50:51] op_sel:[1,1] op_sel_hi:[1,0] neg_lo:[0,1]
	v_pk_fma_f32 v[4:5], v[162:163], v[50:51], v[4:5] op_sel_hi:[0,1,1]
	v_pk_fma_f32 v[4:5], v[162:163], v[252:253], v[4:5]
	v_pk_mul_f32 v[8:9], v[186:187], v[148:149] op_sel:[1,1] op_sel_hi:[1,0] neg_lo:[0,1]
	s_nop 0
	v_pk_fma_f32 v[8:9], v[186:187], v[148:149], v[8:9] op_sel_hi:[0,1,1]
	v_pk_fma_f32 v[8:9], v[186:187], v[252:253], v[8:9]
	ds_write_b64 v43, v[4:5] offset:80
	ds_write_b64 v44, v[8:9] offset:80
	v_pk_mul_f32 v[4:5], v[164:165], v[0:1] op_sel:[1,1] op_sel_hi:[1,0] neg_lo:[0,1]
	s_nop 0
	v_pk_fma_f32 v[0:1], v[164:165], v[0:1], v[4:5] op_sel_hi:[0,1,1]
	v_pk_fma_f32 v[0:1], v[164:165], v[252:253], v[0:1]
	v_pk_mul_f32 v[4:5], v[188:189], v[16:17] op_sel:[1,1] op_sel_hi:[1,0] neg_lo:[0,1]
	s_nop 0
	v_pk_fma_f32 v[4:5], v[188:189], v[16:17], v[4:5] op_sel_hi:[0,1,1]
	v_pk_fma_f32 v[4:5], v[188:189], v[252:253], v[4:5]
	ds_write_b64 v43, v[0:1] offset:48
	ds_write_b64 v44, v[4:5] offset:48
	v_pk_mul_f32 v[0:1], v[54:55], v[32:33] op_sel:[1,1] op_sel_hi:[1,0] neg_lo:[0,1]
	v_pk_fma_f32 v[0:1], v[54:55], v[32:33], v[0:1] op_sel_hi:[0,1,1]
	v_pk_fma_f32 v[0:1], v[54:55], v[252:253], v[0:1]
	v_pk_mul_f32 v[4:5], v[190:191], v[140:141] op_sel:[1,1] op_sel_hi:[1,0] neg_lo:[0,1]
	s_nop 0
	v_pk_fma_f32 v[4:5], v[190:191], v[140:141], v[4:5] op_sel_hi:[0,1,1]
	v_pk_fma_f32 v[4:5], v[190:191], v[252:253], v[4:5]
	ds_write_b64 v43, v[0:1] offset:112
	ds_write_b64 v44, v[4:5] offset:112
	v_pk_mul_f32 v[0:1], v[166:167], v[14:15] op_sel:[1,1] op_sel_hi:[1,0] neg_lo:[0,1]
	v_pk_fma_f32 v[0:1], v[166:167], v[14:15], v[0:1] op_sel_hi:[0,1,1]
	v_pk_fma_f32 v[0:1], v[166:167], v[252:253], v[0:1]
	v_pk_mul_f32 v[4:5], v[192:193], v[30:31] op_sel:[1,1] op_sel_hi:[1,0] neg_lo:[0,1]
	s_nop 0
	v_pk_fma_f32 v[4:5], v[192:193], v[30:31], v[4:5] op_sel_hi:[0,1,1]
	v_pk_fma_f32 v[4:5], v[192:193], v[252:253], v[4:5]
	ds_write_b64 v43, v[0:1] offset:8
	ds_write_b64 v44, v[4:5] offset:8
	v_pk_mul_f32 v[0:1], v[40:41], v[138:139] op_sel:[1,1] op_sel_hi:[1,0] neg_lo:[0,1]
	v_pk_fma_f32 v[0:1], v[40:41], v[138:139], v[0:1] op_sel_hi:[0,1,1]
	v_pk_fma_f32 v[0:1], v[40:41], v[252:253], v[0:1]
	v_pk_mul_f32 v[4:5], v[194:195], v[154:155] op_sel:[1,1] op_sel_hi:[1,0] neg_lo:[0,1]
	s_nop 0
	v_pk_fma_f32 v[4:5], v[194:195], v[154:155], v[4:5] op_sel_hi:[0,1,1]
	v_pk_fma_f32 v[4:5], v[194:195], v[252:253], v[4:5]
	ds_write_b64 v43, v[0:1] offset:72
	ds_write_b64 v44, v[4:5] offset:72
	v_pk_mul_f32 v[0:1], v[170:171], v[6:7] op_sel:[1,1] op_sel_hi:[1,0] neg_lo:[0,1]
	v_pk_fma_f32 v[0:1], v[170:171], v[6:7], v[0:1] op_sel_hi:[0,1,1]
	v_pk_fma_f32 v[0:1], v[170:171], v[252:253], v[0:1]
	v_pk_mul_f32 v[4:5], v[216:217], v[22:23] op_sel:[1,1] op_sel_hi:[1,0] neg_lo:[0,1]
	s_nop 0
	v_pk_fma_f32 v[4:5], v[216:217], v[22:23], v[4:5] op_sel_hi:[0,1,1]
	v_pk_fma_f32 v[4:5], v[216:217], v[252:253], v[4:5]
	ds_write_b64 v43, v[0:1] offset:40
	ds_write_b64 v44, v[4:5] offset:40
	v_pk_mul_f32 v[0:1], v[172:173], v[48:49] op_sel:[1,1] op_sel_hi:[1,0] neg_lo:[0,1]
	v_pk_fma_f32 v[0:1], v[172:173], v[48:49], v[0:1] op_sel_hi:[0,1,1]
	v_pk_fma_f32 v[0:1], v[172:173], v[252:253], v[0:1]
	v_pk_mul_f32 v[4:5], v[218:219], v[146:147] op_sel:[1,1] op_sel_hi:[1,0] neg_lo:[0,1]
	s_nop 0
	v_pk_fma_f32 v[4:5], v[218:219], v[146:147], v[4:5] op_sel_hi:[0,1,1]
	v_pk_fma_f32 v[4:5], v[218:219], v[252:253], v[4:5]
	ds_write_b64 v43, v[0:1] offset:104
	ds_write_b64 v44, v[4:5] offset:104
	v_pk_mul_f32 v[0:1], v[174:175], v[10:11] op_sel:[1,1] op_sel_hi:[1,0] neg_lo:[0,1]
	v_pk_fma_f32 v[0:1], v[174:175], v[10:11], v[0:1] op_sel_hi:[0,1,1]
	v_pk_fma_f32 v[0:1], v[174:175], v[252:253], v[0:1]
	v_pk_mul_f32 v[4:5], v[220:221], v[26:27] op_sel:[1,1] op_sel_hi:[1,0] neg_lo:[0,1]
	s_nop 0
	v_pk_fma_f32 v[4:5], v[220:221], v[26:27], v[4:5] op_sel_hi:[0,1,1]
	v_pk_fma_f32 v[4:5], v[220:221], v[252:253], v[4:5]
	ds_write_b64 v43, v[0:1] offset:24
	ds_write_b64 v44, v[4:5] offset:24
	v_pk_mul_f32 v[0:1], v[176:177], v[52:53] op_sel:[1,1] op_sel_hi:[1,0] neg_lo:[0,1]
	v_pk_fma_f32 v[0:1], v[176:177], v[52:53], v[0:1] op_sel_hi:[0,1,1]
	v_pk_fma_f32 v[0:1], v[176:177], v[252:253], v[0:1]
	v_pk_mul_f32 v[4:5], v[222:223], v[150:151] op_sel:[1,1] op_sel_hi:[1,0] neg_lo:[0,1]
	s_nop 0
	v_pk_fma_f32 v[4:5], v[222:223], v[150:151], v[4:5] op_sel_hi:[0,1,1]
	v_pk_fma_f32 v[4:5], v[222:223], v[252:253], v[4:5]
	ds_write_b64 v43, v[0:1] offset:88
	ds_write_b64 v44, v[4:5] offset:88
	v_pk_mul_f32 v[0:1], v[38:39], v[2:3] op_sel:[1,1] op_sel_hi:[1,0] neg_lo:[0,1]
	s_nop 0
	v_pk_fma_f32 v[0:1], v[38:39], v[2:3], v[0:1] op_sel_hi:[0,1,1]
	v_pk_fma_f32 v[0:1], v[38:39], v[252:253], v[0:1]
	v_pk_mul_f32 v[2:3], v[224:225], v[18:19] op_sel:[1,1] op_sel_hi:[1,0] neg_lo:[0,1]
	s_nop 0
	v_pk_fma_f32 v[2:3], v[224:225], v[18:19], v[2:3] op_sel_hi:[0,1,1]
	v_pk_fma_f32 v[2:3], v[224:225], v[252:253], v[2:3]
	ds_write_b64 v43, v[0:1] offset:56
	ds_write_b64 v44, v[2:3] offset:56
	v_pk_mul_f32 v[0:1], v[36:37], v[34:35] op_sel:[1,1] op_sel_hi:[1,0] neg_lo:[0,1]
	v_pk_fma_f32 v[0:1], v[36:37], v[34:35], v[0:1] op_sel_hi:[0,1,1]
	v_pk_fma_f32 v[0:1], v[36:37], v[252:253], v[0:1]
	v_pk_mul_f32 v[2:3], v[226:227], v[142:143] op_sel:[1,1] op_sel_hi:[1,0] neg_lo:[0,1]
	s_nop 0
	v_pk_fma_f32 v[2:3], v[226:227], v[142:143], v[2:3] op_sel_hi:[0,1,1]
	v_pk_fma_f32 v[2:3], v[226:227], v[252:253], v[2:3]
	ds_write_b64 v43, v[0:1] offset:120
	ds_write_b64 v44, v[2:3] offset:120
	s_andn2_b64 exec, exec, s[92:93]
	s_cbranch_execnz .LBB0_353
.LBB0_354:
	s_or_b64 exec, exec, s[90:91]
	s_waitcnt lgkmcnt(0)
	s_and_saveexec_b64 s[90:91], s[6:7]
	s_cbranch_execz .LBB0_357
	s_mov_b64 s[92:93], 0
	v_mov_b32_e32 v38, v56

.LBB0_359:
	v_ashrrev_i32_e32 v0, 7, v33
	v_mov_b32_e32 v16, v0
	v_add_u32_e32 v1, 0x200, v33
	v_cvt_f32_i32_e32 v16, v16
	v_ashrrev_i32_e32 v1, 7, v1
	v_mov_b32_e32 v54, v1
	v_lshl_add_u32 v55, v0, 3, v196
	v_mul_f32_e32 v17, 0x3c000000, v16
	v_cos_f32_e32 v16, v17
	v_sin_f32_e32 v17, v17
	v_lshl_add_u32 v66, v1, 3, v196
	v_mov_b32_e32 v39, v16
	v_mov_b32_e32 v18, v17
	v_xor_b32_e32 v38, 0x80000000, v17
	v_pk_mul_f32 v[18:19], v[38:39], v[18:19] op_sel_hi:[1,0]
	ds_read2_b64 v[20:23], v55 offset1:16
	ds_read2_b64 v[0:3], v66 offset1:16
	ds_read2_b64 v[24:27], v55 offset0:32 offset1:48
	ds_read2_b64 v[12:15], v66 offset0:32 offset1:48
	ds_read2_b64 v[28:31], v55 offset0:64 offset1:80
	ds_read2_b64 v[8:11], v66 offset0:64 offset1:80
	ds_read2_b64 v[34:37], v55 offset0:96 offset1:112
	ds_read2_b64 v[4:7], v66 offset0:96 offset1:112
	v_pk_fma_f32 v[18:19], v[16:17], v[16:17], v[18:19] op_sel_hi:[1,0,1]
	s_mov_b32 s40, s57
	v_pk_mul_f32 v[44:45], v[18:19], v[18:19] op_sel:[1,1] op_sel_hi:[1,0] neg_lo:[0,1]
	v_pk_mul_f32 v[40:41], v[38:39], v[18:19] op_sel:[0,1]
	v_pk_fma_f32 v[44:45], v[18:19], v[18:19], v[44:45] op_sel_hi:[1,0,1]
	v_pk_fma_f32 v[40:41], v[16:17], v[18:19], v[40:41] op_sel_hi:[1,0,1]
	v_pk_mul_f32 v[46:47], v[38:39], v[44:45] op_sel:[0,1]
	s_waitcnt lgkmcnt(7)
	v_pk_mul_f32 v[38:39], v[38:39], v[22:23] op_sel:[0,1]
	v_pk_fma_f32 v[46:47], v[16:17], v[44:45], v[46:47] op_sel_hi:[1,0,1]
	v_pk_fma_f32 v[38:39], v[16:17], v[22:23], v[38:39] op_sel_hi:[1,0,1]
	v_pk_mul_f32 v[48:49], v[18:19], v[44:45] op_sel:[1,1] op_sel_hi:[0,1] neg_lo:[1,0]
	s_waitcnt lgkmcnt(5)
	v_pk_mul_f32 v[16:17], v[24:25], v[18:19] op_sel:[1,1] op_sel_hi:[1,0] neg_lo:[0,1]
	s_waitcnt lgkmcnt(3)
	v_pk_mul_f32 v[22:23], v[28:29], v[44:45] op_sel:[1,1] op_sel_hi:[1,0] neg_lo:[0,1]
	v_pk_fma_f32 v[48:49], v[18:19], v[44:45], v[48:49] op_sel_hi:[1,0,1]
	v_pk_fma_f32 v[18:19], v[24:25], v[18:19], v[16:17] op_sel_hi:[0,1,1]
	v_pk_fma_f32 v[24:25], v[28:29], v[44:45], v[22:23] op_sel_hi:[0,1,1]
	v_pk_mul_f32 v[22:23], v[30:31], v[46:47] op_sel:[1,1] op_sel_hi:[1,0] neg_lo:[0,1]
	v_pk_mul_f32 v[52:53], v[44:45], v[40:41] op_sel:[1,1] op_sel_hi:[1,0] neg_lo:[0,1]
	v_pk_fma_f32 v[30:31], v[30:31], v[46:47], v[22:23] op_sel_hi:[0,1,1]
	v_pk_fma_f32 v[52:53], v[40:41], v[44:45], v[52:53] op_sel_hi:[1,0,1]
	v_pk_mul_f32 v[16:17], v[26:27], v[40:41] op_sel:[1,1] op_sel_hi:[1,0] neg_lo:[0,1]
	s_waitcnt lgkmcnt(1)
	v_pk_mul_f32 v[22:23], v[34:35], v[48:49] op_sel:[1,1] op_sel_hi:[1,0] neg_lo:[0,1]
	v_pk_fma_f32 v[16:17], v[26:27], v[40:41], v[16:17] op_sel_hi:[0,1,1]
	v_pk_fma_f32 v[26:27], v[34:35], v[48:49], v[22:23] op_sel_hi:[0,1,1]
	v_pk_mul_f32 v[22:23], v[36:37], v[52:53] op_sel:[1,1] op_sel_hi:[1,0] neg_lo:[0,1]
	v_pk_add_f32 v[34:35], v[18:19], v[26:27]
	v_pk_fma_f32 v[28:29], v[52:53], v[36:37], v[22:23] op_sel_hi:[1,0,1]
	v_pk_add_f32 v[18:19], v[18:19], v[26:27] neg_lo:[0,1] neg_hi:[0,1]
	v_pk_add_f32 v[22:23], v[20:21], v[24:25]
	v_pk_add_f32 v[20:21], v[20:21], v[24:25] neg_lo:[0,1] neg_hi:[0,1]
	v_pk_add_f32 v[24:25], v[38:39], v[30:31]
	v_pk_add_f32 v[30:31], v[38:39], v[30:31] neg_lo:[0,1] neg_hi:[0,1]
	v_xor_b32_e32 v26, 0x80000000, v19
	v_mov_b32_e32 v27, v18
	v_pk_add_f32 v[18:19], v[16:17], v[28:29]
	v_pk_add_f32 v[16:17], v[16:17], v[28:29] neg_lo:[0,1] neg_hi:[0,1]
	v_mul_f32_e32 v32, 0x3f3504f3, v30
	s_mov_b32 s41, s56
	v_mul_f32_e32 v28, 0xbf3504f3, v17
	v_pk_fma_f32 v[30:31], v[30:31], s[40:41], v[32:33] op_sel:[1,0,0] op_sel_hi:[1,1,0]
	v_pk_fma_f32 v[16:17], v[16:17], s[40:41], v[28:29] op_sel_hi:[0,1,0]
	v_pk_add_f32 v[28:29], v[22:23], v[34:35]
	v_pk_add_f32 v[22:23], v[22:23], v[34:35] neg_lo:[0,1] neg_hi:[0,1]
	v_pk_add_f32 v[34:35], v[24:25], v[18:19]
	v_pk_add_f32 v[18:19], v[24:25], v[18:19] neg_lo:[0,1] neg_hi:[0,1]
	v_cmp_lt_i32_e32 vcc, s28, v33
	v_xor_b32_e32 v24, 0x80000000, v19
	v_mov_b32_e32 v25, v18
	v_pk_add_f32 v[18:19], v[20:21], v[26:27]
	v_pk_add_f32 v[20:21], v[20:21], v[26:27] neg_lo:[0,1] neg_hi:[0,1]
	v_pk_add_f32 v[26:27], v[30:31], v[16:17]
	v_pk_add_f32 v[16:17], v[30:31], v[16:17] neg_lo:[0,1] neg_hi:[0,1]
	s_or_b64 s[92:93], vcc, s[92:93]
	v_xor_b32_e32 v30, 0x80000000, v17
	v_mov_b32_e32 v31, v16
	v_pk_add_f32 v[16:17], v[28:29], v[34:35]
	v_pk_add_f32 v[28:29], v[28:29], v[34:35] neg_lo:[0,1] neg_hi:[0,1]
	v_pk_add_f32 v[34:35], v[22:23], v[24:25]
	v_pk_add_f32 v[22:23], v[22:23], v[24:25] neg_lo:[0,1] neg_hi:[0,1]
	v_pk_add_f32 v[24:25], v[18:19], v[26:27]
	v_pk_add_f32 v[18:19], v[18:19], v[26:27] neg_lo:[0,1] neg_hi:[0,1]
	v_pk_add_f32 v[26:27], v[20:21], v[30:31]
	v_pk_add_f32 v[20:21], v[20:21], v[30:31] neg_lo:[0,1] neg_hi:[0,1]
	v_cvt_f32_i32_e32 v30, v54
	v_mul_f32_e32 v31, 0x3c000000, v30
	v_cos_f32_e32 v30, v31
	v_sin_f32_e32 v31, v31
	v_mov_b32_e32 v37, v30
	v_mov_b32_e32 v32, v31
	v_xor_b32_e32 v36, 0x80000000, v31
	v_pk_mul_f32 v[38:39], v[36:37], v[32:33] op_sel_hi:[1,0]
	v_add_u32_e32 v33, 0x400, v33
	v_pk_fma_f32 v[38:39], v[30:31], v[30:31], v[38:39] op_sel_hi:[1,0,1]
	s_nop 0
	v_xor_b32_e32 v42, 0x80000000, v39
	v_mov_b32_e32 v43, v38
	v_pk_mul_f32 v[44:45], v[38:39], v[42:43] op_sel:[1,0]
	v_pk_mul_f32 v[40:41], v[36:37], v[38:39] op_sel:[0,1]
	v_pk_fma_f32 v[44:45], v[38:39], v[38:39], v[44:45] op_sel_hi:[1,0,1]
	v_pk_fma_f32 v[40:41], v[30:31], v[38:39], v[40:41] op_sel_hi:[1,0,1]
	v_pk_mul_f32 v[46:47], v[36:37], v[44:45] op_sel:[0,1]
	v_pk_mul_f32 v[36:37], v[36:37], v[2:3] op_sel:[0,1]
	v_pk_fma_f32 v[46:47], v[30:31], v[44:45], v[46:47] op_sel_hi:[1,0,1]
	v_xor_b32_e32 v50, 0x80000000, v41
	v_mov_b32_e32 v51, v40
	v_pk_fma_f32 v[2:3], v[30:31], v[2:3], v[36:37] op_sel_hi:[1,0,1]
	v_pk_mul_f32 v[30:31], v[12:13], v[42:43] op_sel:[1,0]
	v_pk_mul_f32 v[48:49], v[42:43], v[44:45] op_sel:[0,1]
	v_pk_fma_f32 v[12:13], v[12:13], v[38:39], v[30:31] op_sel_hi:[0,1,1]
	v_pk_mul_f32 v[30:31], v[14:15], v[50:51] op_sel:[1,0]
	v_pk_fma_f32 v[48:49], v[38:39], v[44:45], v[48:49] op_sel_hi:[1,0,1]
	v_pk_fma_f32 v[14:15], v[14:15], v[40:41], v[30:31] op_sel_hi:[0,1,1]
	v_pk_mul_f32 v[30:31], v[8:9], v[44:45] op_sel:[1,1] op_sel_hi:[1,0] neg_lo:[0,1]
	v_pk_mul_f32 v[52:53], v[44:45], v[50:51] op_sel:[1,0]
	v_pk_fma_f32 v[8:9], v[8:9], v[44:45], v[30:31] op_sel_hi:[0,1,1]
	v_pk_mul_f32 v[30:31], v[10:11], v[46:47] op_sel:[1,1] op_sel_hi:[1,0] neg_lo:[0,1]
	v_pk_fma_f32 v[52:53], v[40:41], v[44:45], v[52:53] op_sel_hi:[1,0,1]
	v_pk_fma_f32 v[10:11], v[10:11], v[46:47], v[30:31] op_sel_hi:[0,1,1]
	s_waitcnt lgkmcnt(0)
	v_pk_mul_f32 v[30:31], v[4:5], v[48:49] op_sel:[1,1] op_sel_hi:[1,0] neg_lo:[0,1]
	s_nop 0
	v_pk_fma_f32 v[4:5], v[4:5], v[48:49], v[30:31] op_sel_hi:[0,1,1]
	v_pk_mul_f32 v[30:31], v[6:7], v[52:53] op_sel:[1,1] op_sel_hi:[1,0] neg_lo:[0,1]
	s_nop 0
	v_pk_fma_f32 v[6:7], v[52:53], v[6:7], v[30:31] op_sel_hi:[1,0,1]
	v_pk_add_f32 v[30:31], v[0:1], v[8:9]
	v_pk_add_f32 v[0:1], v[0:1], v[8:9] neg_lo:[0,1] neg_hi:[0,1]
	v_pk_add_f32 v[8:9], v[2:3], v[10:11]
	v_pk_add_f32 v[2:3], v[2:3], v[10:11] neg_lo:[0,1] neg_hi:[0,1]
	s_nop 0
	v_mul_f32_e32 v10, 0x3f3504f3, v2
	v_pk_fma_f32 v[2:3], v[2:3], s[40:41], v[10:11] op_sel:[1,0,0] op_sel_hi:[1,1,0]
	v_pk_add_f32 v[10:11], v[12:13], v[4:5]
	v_pk_add_f32 v[4:5], v[12:13], v[4:5] neg_lo:[0,1] neg_hi:[0,1]
	s_nop 0
	v_xor_b32_e32 v12, 0x80000000, v5
	v_mov_b32_e32 v13, v4
	v_pk_add_f32 v[4:5], v[14:15], v[6:7]
	v_pk_add_f32 v[6:7], v[14:15], v[6:7] neg_lo:[0,1] neg_hi:[0,1]
	s_nop 0
	v_mul_f32_e32 v14, 0xbf3504f3, v7
	v_pk_fma_f32 v[6:7], v[6:7], s[40:41], v[14:15] op_sel_hi:[0,1,0]
	v_pk_add_f32 v[14:15], v[30:31], v[10:11]
	v_pk_add_f32 v[10:11], v[30:31], v[10:11] neg_lo:[0,1] neg_hi:[0,1]
	v_pk_add_f32 v[30:31], v[8:9], v[4:5]
	v_pk_add_f32 v[4:5], v[8:9], v[4:5] neg_lo:[0,1] neg_hi:[0,1]
	s_nop 0
	v_xor_b32_e32 v8, 0x80000000, v5
	v_mov_b32_e32 v9, v4
	v_pk_add_f32 v[4:5], v[0:1], v[12:13]
	v_pk_add_f32 v[0:1], v[0:1], v[12:13] neg_lo:[0,1] neg_hi:[0,1]
	v_pk_add_f32 v[12:13], v[2:3], v[6:7]
	v_pk_add_f32 v[2:3], v[2:3], v[6:7] neg_lo:[0,1] neg_hi:[0,1]
	s_nop 0
	v_xor_b32_e32 v6, 0x80000000, v3
	v_mov_b32_e32 v7, v2
	v_pk_add_f32 v[2:3], v[14:15], v[30:31]
	v_pk_add_f32 v[14:15], v[14:15], v[30:31] neg_lo:[0,1] neg_hi:[0,1]
	v_pk_add_f32 v[30:31], v[10:11], v[8:9]
	v_pk_add_f32 v[8:9], v[10:11], v[8:9] neg_lo:[0,1] neg_hi:[0,1]
	v_pk_add_f32 v[10:11], v[4:5], v[12:13]
	v_pk_add_f32 v[4:5], v[4:5], v[12:13] neg_lo:[0,1] neg_hi:[0,1]
	v_pk_add_f32 v[12:13], v[0:1], v[6:7]
	v_pk_add_f32 v[0:1], v[0:1], v[6:7] neg_lo:[0,1] neg_hi:[0,1]
	ds_write_b64 v55, v[16:17]
	ds_write_b64 v66, v[2:3]
	ds_write_b64 v55, v[28:29] offset:512
	ds_write_b64 v66, v[14:15] offset:512
	ds_write_b64 v55, v[34:35] offset:256
	ds_write_b64 v66, v[30:31] offset:256
	ds_write_b64 v55, v[22:23] offset:768
	ds_write_b64 v66, v[8:9] offset:768
	ds_write_b64 v55, v[24:25] offset:128
	ds_write_b64 v66, v[10:11] offset:128
	ds_write_b64 v55, v[18:19] offset:640
	ds_write_b64 v66, v[4:5] offset:640
	ds_write_b64 v55, v[26:27] offset:384
	ds_write_b64 v66, v[12:13] offset:384
	ds_write_b64 v55, v[20:21] offset:896
	ds_write_b64 v66, v[0:1] offset:896
	s_andn2_b64 exec, exec, s[92:93]
	s_cbranch_execnz .LBB0_359

.LBB0_362:
	v_lshrrev_b32_e32 v0, 3, v66
	v_and_b32_e32 v0, 0x1ffffff0, v0
	v_mov_b32_e32 v48, v65
	v_mad_u64_u32 v[32:33], s[40:41], v0, s25, v[60:61]
	v_add_u32_e32 v1, 0x200, v66
	v_cvt_f32_i32_e32 v33, v48
	v_lshrrev_b32_e32 v1, 3, v1
	v_and_b32_e32 v1, 0x1ffffff0, v1
	v_mov_b32_e32 v148, v65
	v_mul_f32_e32 v33, 0x3a000000, v33
	v_cos_f32_e32 v48, v33
	v_sin_f32_e32 v49, v33
	v_mad_u64_u32 v[34:35], s[40:41], v1, s25, v[60:61]
	v_mov_b32_e32 v53, v48
	v_mov_b32_e32 v50, v49
	v_xor_b32_e32 v52, 0x80000000, v49
	v_pk_mul_f32 v[50:51], v[52:53], v[50:51] op_sel_hi:[1,0]
	v_add_u32_e32 v4, 0x800, v32
	v_pk_fma_f32 v[50:51], v[48:49], v[48:49], v[50:51] op_sel_hi:[1,0,1]
	ds_read2_b64 v[36:39], v32 offset1:129
	ds_read2_b64 v[0:3], v34 offset1:129
	v_pk_mul_f32 v[142:143], v[50:51], v[50:51] op_sel:[1,1] op_sel_hi:[1,0] neg_lo:[0,1]
	v_pk_mul_f32 v[54:55], v[52:53], v[50:51] op_sel:[0,1]
	v_pk_fma_f32 v[162:163], v[50:51], v[50:51], v[142:143] op_sel_hi:[1,0,1]
	v_pk_fma_f32 v[54:55], v[48:49], v[50:51], v[54:55] op_sel_hi:[1,0,1]
	v_pk_mul_f32 v[142:143], v[52:53], v[162:163] op_sel:[0,1]
	v_pk_fma_f32 v[164:165], v[48:49], v[162:163], v[142:143] op_sel_hi:[1,0,1]
	v_pk_mul_f32 v[142:143], v[50:51], v[162:163] op_sel:[1,1] op_sel_hi:[0,1] neg_lo:[1,0]
	v_pk_fma_f32 v[166:167], v[50:51], v[162:163], v[142:143] op_sel_hi:[1,0,1]
	v_pk_mul_f32 v[142:143], v[162:163], v[54:55] op_sel:[1,1] op_sel_hi:[1,0] neg_lo:[0,1]
	v_pk_fma_f32 v[172:173], v[54:55], v[162:163], v[142:143] op_sel_hi:[1,0,1]
	v_pk_mul_f32 v[142:143], v[162:163], v[162:163] op_sel:[1,1] op_sel_hi:[1,0] neg_lo:[0,1]
	ds_read2_b64 v[40:43], v4 offset0:2 offset1:131
	v_pk_fma_f32 v[176:177], v[162:163], v[162:163], v[142:143] op_sel_hi:[1,0,1]
	v_add_u32_e32 v4, 0x800, v34
	v_pk_mul_f32 v[142:143], v[52:53], v[176:177] op_sel:[0,1]
	ds_read2_b64 v[20:23], v4 offset0:2 offset1:131
	v_pk_fma_f32 v[178:179], v[48:49], v[176:177], v[142:143] op_sel_hi:[1,0,1]
	v_pk_mul_f32 v[142:143], v[50:51], v[176:177] op_sel:[1,1] op_sel_hi:[0,1] neg_lo:[1,0]
	v_add_u32_e32 v4, 0x1000, v32
	v_pk_fma_f32 v[180:181], v[50:51], v[176:177], v[142:143] op_sel_hi:[1,0,1]
	v_pk_mul_f32 v[142:143], v[54:55], v[176:177] op_sel:[1,1] op_sel_hi:[0,1] neg_lo:[1,0]
	ds_read2_b64 v[44:47], v4 offset0:4 offset1:133
	v_add_u32_e32 v4, 0x1000, v34
	v_pk_fma_f32 v[182:183], v[54:55], v[176:177], v[142:143] op_sel_hi:[1,0,1]
	v_pk_mul_f32 v[142:143], v[162:163], v[176:177] op_sel:[1,1] op_sel_hi:[0,1] neg_lo:[1,0]
	ds_read2_b64 v[24:27], v4 offset0:4 offset1:133
	v_add_u32_e32 v4, 0x1800, v32
	v_pk_fma_f32 v[184:185], v[162:163], v[176:177], v[142:143] op_sel_hi:[1,0,1]
	v_pk_mul_f32 v[142:143], v[176:177], v[164:165] op_sel:[1,1] op_sel_hi:[1,0] neg_lo:[0,1]
	ds_read2_b64 v[136:139], v4 offset0:6 offset1:135
	v_pk_fma_f32 v[188:189], v[164:165], v[176:177], v[142:143] op_sel_hi:[1,0,1]
	v_pk_mul_f32 v[142:143], v[176:177], v[166:167] op_sel:[1,1] op_sel_hi:[1,0] neg_lo:[0,1]
	v_xor_b32_e32 v194, 0x80000000, v173
	v_mov_b32_e32 v195, v172
	s_waitcnt lgkmcnt(6)
	v_pk_mul_f32 v[52:53], v[52:53], v[38:39] op_sel:[0,1]
	v_add_u32_e32 v4, 0x1800, v34
	v_pk_fma_f32 v[192:193], v[166:167], v[176:177], v[142:143] op_sel_hi:[1,0,1]
	v_pk_mul_f32 v[142:143], v[176:177], v[194:195] op_sel:[1,0]
	v_pk_fma_f32 v[218:219], v[48:49], v[38:39], v[52:53] op_sel_hi:[1,0,1]
	s_waitcnt lgkmcnt(4)
	v_pk_mul_f32 v[38:39], v[40:41], v[50:51] op_sel:[1,1] op_sel_hi:[1,0] neg_lo:[0,1]
	ds_read2_b64 v[28:31], v4 offset0:6 offset1:135
	v_add_u32_e32 v4, 0x2000, v32
	v_pk_fma_f32 v[216:217], v[172:173], v[176:177], v[142:143] op_sel_hi:[1,0,1]
	v_pk_fma_f32 v[142:143], v[40:41], v[50:51], v[38:39] op_sel_hi:[0,1,1]
	v_pk_mul_f32 v[38:39], v[42:43], v[54:55] op_sel:[1,1] op_sel_hi:[1,0] neg_lo:[0,1]
	ds_read2_b64 v[144:147], v4 offset0:8 offset1:137
	v_pk_fma_f32 v[54:55], v[42:43], v[54:55], v[38:39] op_sel_hi:[0,1,1]
	s_waitcnt lgkmcnt(4)
	v_pk_mul_f32 v[38:39], v[44:45], v[162:163] op_sel:[1,1] op_sel_hi:[1,0] neg_lo:[0,1]
	v_add_u32_e32 v4, 0x2000, v34
	v_pk_fma_f32 v[52:53], v[44:45], v[162:163], v[38:39] op_sel_hi:[0,1,1]
	v_pk_mul_f32 v[38:39], v[46:47], v[164:165] op_sel:[1,1] op_sel_hi:[1,0] neg_lo:[0,1]
	ds_read2_b64 v[16:19], v4 offset0:8 offset1:137
	v_pk_fma_f32 v[50:51], v[46:47], v[164:165], v[38:39] op_sel_hi:[0,1,1]
	s_waitcnt lgkmcnt(3)
	v_pk_mul_f32 v[38:39], v[136:137], v[166:167] op_sel:[1,1] op_sel_hi:[1,0] neg_lo:[0,1]
	v_add_u32_e32 v4, 0x2800, v32
	v_pk_fma_f32 v[44:45], v[136:137], v[166:167], v[38:39] op_sel_hi:[0,1,1]
	v_pk_mul_f32 v[38:39], v[138:139], v[194:195] op_sel:[1,0]
	ds_read2_b64 v[150:153], v4 offset0:10 offset1:139
	v_pk_fma_f32 v[42:43], v[172:173], v[138:139], v[38:39] op_sel_hi:[1,0,1]
	s_waitcnt lgkmcnt(2)
	v_pk_mul_f32 v[38:39], v[144:145], v[176:177] op_sel:[1,1] op_sel_hi:[1,0] neg_lo:[0,1]
	v_add_u32_e32 v4, 0x2800, v34
	v_pk_fma_f32 v[40:41], v[176:177], v[144:145], v[38:39] op_sel_hi:[1,0,1]
	ds_read2_b64 v[12:15], v4 offset0:10 offset1:139
	v_add_u32_e32 v4, 0x3000, v32
	v_pk_mul_f32 v[38:39], v[146:147], v[178:179] op_sel:[1,1] op_sel_hi:[1,0] neg_lo:[0,1]
	ds_read2_b64 v[154:157], v4 offset0:12 offset1:141
	v_pk_fma_f32 v[146:147], v[178:179], v[146:147], v[38:39] op_sel_hi:[1,0,1]
	s_waitcnt lgkmcnt(2)
	v_pk_mul_f32 v[38:39], v[150:151], v[180:181] op_sel:[1,1] op_sel_hi:[1,0] neg_lo:[0,1]
	v_add_u32_e32 v4, 0x3000, v34
	v_pk_fma_f32 v[144:145], v[180:181], v[150:151], v[38:39] op_sel_hi:[1,0,1]
	ds_read2_b64 v[8:11], v4 offset0:12 offset1:141
	v_add_u32_e32 v4, 0x3800, v32
	v_pk_mul_f32 v[38:39], v[182:183], v[152:153] op_sel:[1,1] op_sel_hi:[0,1] neg_lo:[1,0]
	ds_read2_b64 v[158:161], v4 offset0:14 offset1:143
	v_pk_fma_f32 v[140:141], v[182:183], v[152:153], v[38:39] op_sel_hi:[1,0,1]
	s_waitcnt lgkmcnt(2)
	v_pk_mul_f32 v[38:39], v[184:185], v[154:155] op_sel:[1,1] op_sel_hi:[0,1] neg_lo:[1,0]
	s_mov_b32 s96, s43
	v_pk_fma_f32 v[136:137], v[184:185], v[154:155], v[38:39] op_sel_hi:[1,0,1]
	v_pk_mul_f32 v[38:39], v[188:189], v[156:157] op_sel:[1,1] op_sel_hi:[0,1] neg_lo:[1,0]
	s_mov_b32 s97, s42
	v_pk_fma_f32 v[138:139], v[188:189], v[156:157], v[38:39] op_sel_hi:[1,0,1]
	s_waitcnt lgkmcnt(0)
	v_pk_mul_f32 v[38:39], v[192:193], v[158:159] op_sel:[1,1] op_sel_hi:[0,1] neg_lo:[1,0]
	s_mov_b32 s58, s42
	v_pk_fma_f32 v[46:47], v[192:193], v[158:159], v[38:39] op_sel_hi:[1,0,1]
	v_pk_mul_f32 v[38:39], v[216:217], v[160:161] op_sel:[1,1] op_sel_hi:[0,1] neg_lo:[1,0]
	s_mov_b32 s59, s64
	v_pk_fma_f32 v[48:49], v[216:217], v[160:161], v[38:39] op_sel_hi:[1,0,1]
	v_pk_add_f32 v[38:39], v[36:37], v[40:41]
	v_pk_add_f32 v[36:37], v[36:37], v[40:41] neg_lo:[0,1] neg_hi:[0,1]
	v_pk_add_f32 v[40:41], v[218:219], v[146:147]
	v_pk_add_f32 v[146:147], v[218:219], v[146:147] neg_lo:[0,1] neg_hi:[0,1]
	s_mov_b32 s94, s57
	v_pk_mul_f32 v[150:151], v[146:147], s[96:97] op_sel:[1,0]
	s_mov_b32 s95, s56
	v_pk_fma_f32 v[146:147], v[146:147], s[58:59], v[150:151] op_sel_hi:[0,1,1]
	v_pk_add_f32 v[150:151], v[142:143], v[144:145]
	v_pk_add_f32 v[142:143], v[142:143], v[144:145] neg_lo:[0,1] neg_hi:[0,1]
	s_mov_b32 s44, s67
	v_mul_f32_e32 v144, 0x3f3504f3, v142
	v_pk_fma_f32 v[142:143], v[142:143], s[94:95], v[144:145] op_sel:[1,0,0] op_sel_hi:[1,1,0]
	v_pk_add_f32 v[144:145], v[54:55], v[140:141]
	v_pk_add_f32 v[54:55], v[54:55], v[140:141] neg_lo:[0,1] neg_hi:[0,1]
	s_mov_b32 s45, s64
	s_mov_b32 s65, s42
	v_pk_mul_f32 v[140:141], v[54:55], s[44:45] op_sel:[1,0]
	s_mov_b32 s40, s67
	v_pk_fma_f32 v[54:55], v[54:55], s[64:65], v[140:141] op_sel_hi:[0,1,1]
	v_pk_add_f32 v[140:141], v[52:53], v[136:137]
	v_pk_add_f32 v[52:53], v[52:53], v[136:137] neg_lo:[0,1] neg_hi:[0,1]
	s_mov_b32 s41, s43
	v_xor_b32_e32 v136, 0x80000000, v53
	v_mov_b32_e32 v137, v52
	v_pk_add_f32 v[52:53], v[50:51], v[138:139]
	v_pk_add_f32 v[50:51], v[50:51], v[138:139] neg_lo:[0,1] neg_hi:[0,1]
	s_mov_b32 s66, s43
	v_pk_mul_f32 v[138:139], v[50:51], s[40:41] op_sel:[1,0]
	v_cvt_f32_i32_e32 v33, v148
	v_pk_fma_f32 v[50:51], v[50:51], s[96:97], v[138:139] op_sel_hi:[0,1,1]
	v_pk_add_f32 v[138:139], v[44:45], v[46:47]
	v_pk_add_f32 v[44:45], v[44:45], v[46:47] neg_lo:[0,1] neg_hi:[0,1]
	v_mul_f32_e32 v33, 0x3a000000, v33
	v_mul_f32_e32 v46, 0xbf3504f3, v45
	v_pk_fma_f32 v[44:45], v[44:45], s[94:95], v[46:47] op_sel_hi:[0,1,0]
	v_pk_add_f32 v[46:47], v[42:43], v[48:49]
	v_pk_add_f32 v[42:43], v[42:43], v[48:49] neg_lo:[0,1] neg_hi:[0,1]
	v_add_u32_e32 v4, 0x3800, v34
	v_pk_mul_f32 v[48:49], v[42:43], s[66:67] op_sel:[1,0]
	ds_read2_b64 v[4:7], v4 offset0:14 offset1:143
	v_pk_fma_f32 v[42:43], v[42:43], s[44:45], v[48:49] op_sel_hi:[0,1,1]
	v_pk_add_f32 v[48:49], v[38:39], v[140:141]
	v_pk_add_f32 v[38:39], v[38:39], v[140:141] neg_lo:[0,1] neg_hi:[0,1]
	v_pk_add_f32 v[140:141], v[40:41], v[52:53]
	v_pk_add_f32 v[40:41], v[40:41], v[52:53] neg_lo:[0,1] neg_hi:[0,1]
	v_cmp_lt_i32_e32 vcc, -1, v66
	v_mul_f32_e32 v52, 0x3f3504f3, v40
	v_pk_fma_f32 v[40:41], v[40:41], s[94:95], v[52:53] op_sel:[1,0,0] op_sel_hi:[1,1,0]
	v_pk_add_f32 v[52:53], v[150:151], v[138:139]
	v_pk_add_f32 v[138:139], v[150:151], v[138:139] neg_lo:[0,1] neg_hi:[0,1]
	v_add_u32_e32 v66, 0x400, v66
	v_xor_b32_e32 v150, 0x80000000, v139
	v_mov_b32_e32 v151, v138
	v_pk_add_f32 v[138:139], v[144:145], v[46:47]
	v_pk_add_f32 v[46:47], v[144:145], v[46:47] neg_lo:[0,1] neg_hi:[0,1]
	s_or_b64 s[92:93], vcc, s[92:93]
	v_mul_f32_e32 v144, 0xbf3504f3, v47
	v_pk_fma_f32 v[46:47], v[46:47], s[94:95], v[144:145] op_sel_hi:[0,1,0]
	v_pk_add_f32 v[144:145], v[36:37], v[136:137]
	v_pk_add_f32 v[36:37], v[36:37], v[136:137] neg_lo:[0,1] neg_hi:[0,1]
	v_pk_add_f32 v[136:137], v[146:147], v[50:51]
	v_pk_add_f32 v[50:51], v[146:147], v[50:51] neg_lo:[0,1] neg_hi:[0,1]
	s_nop 0
	v_mul_f32_e32 v146, 0x3f3504f3, v50
	v_pk_fma_f32 v[50:51], v[50:51], s[94:95], v[146:147] op_sel:[1,0,0] op_sel_hi:[1,1,0]
	v_pk_add_f32 v[146:147], v[142:143], v[44:45]
	v_pk_add_f32 v[44:45], v[142:143], v[44:45] neg_lo:[0,1] neg_hi:[0,1]
	s_nop 0
	v_xor_b32_e32 v142, 0x80000000, v45
	v_mov_b32_e32 v143, v44
	v_pk_add_f32 v[44:45], v[54:55], v[42:43]
	v_pk_add_f32 v[42:43], v[54:55], v[42:43] neg_lo:[0,1] neg_hi:[0,1]
	s_nop 0
	v_mul_f32_e32 v54, 0xbf3504f3, v43
	v_pk_fma_f32 v[42:43], v[42:43], s[94:95], v[54:55] op_sel_hi:[0,1,0]
	v_pk_add_f32 v[54:55], v[48:49], v[52:53]
	v_pk_add_f32 v[48:49], v[48:49], v[52:53] neg_lo:[0,1] neg_hi:[0,1]
	v_pk_add_f32 v[52:53], v[140:141], v[138:139]
	v_pk_add_f32 v[138:139], v[140:141], v[138:139] neg_lo:[0,1] neg_hi:[0,1]
	s_nop 0
	v_xor_b32_e32 v140, 0x80000000, v139
	v_mov_b32_e32 v141, v138
	v_pk_add_f32 v[138:139], v[38:39], v[150:151]
	v_pk_add_f32 v[38:39], v[38:39], v[150:151] neg_lo:[0,1] neg_hi:[0,1]
	v_pk_add_f32 v[150:151], v[40:41], v[46:47]
	v_pk_add_f32 v[40:41], v[40:41], v[46:47] neg_lo:[0,1] neg_hi:[0,1]
	s_nop 0
	v_xor_b32_e32 v46, 0x80000000, v41
	v_mov_b32_e32 v47, v40
	v_pk_add_f32 v[40:41], v[144:145], v[146:147]
	v_pk_add_f32 v[144:145], v[144:145], v[146:147] neg_lo:[0,1] neg_hi:[0,1]
	v_pk_add_f32 v[146:147], v[136:137], v[44:45]
	v_pk_add_f32 v[44:45], v[136:137], v[44:45] neg_lo:[0,1] neg_hi:[0,1]
	s_nop 0
	v_xor_b32_e32 v136, 0x80000000, v45
	v_mov_b32_e32 v137, v44
	v_pk_add_f32 v[44:45], v[36:37], v[142:143]
	v_pk_add_f32 v[36:37], v[36:37], v[142:143] neg_lo:[0,1] neg_hi:[0,1]
	v_pk_add_f32 v[142:143], v[50:51], v[42:43]
	v_pk_add_f32 v[42:43], v[50:51], v[42:43] neg_lo:[0,1] neg_hi:[0,1]
	s_nop 0
	v_xor_b32_e32 v50, 0x80000000, v43
	v_mov_b32_e32 v51, v42
	v_pk_add_f32 v[42:43], v[54:55], v[52:53]
	v_pk_add_f32 v[52:53], v[54:55], v[52:53] neg_lo:[0,1] neg_hi:[0,1]
	v_pk_add_f32 v[54:55], v[48:49], v[140:141]
	v_pk_add_f32 v[48:49], v[48:49], v[140:141] neg_lo:[0,1] neg_hi:[0,1]
	v_pk_add_f32 v[140:141], v[138:139], v[150:151]
	v_pk_add_f32 v[138:139], v[138:139], v[150:151] neg_lo:[0,1] neg_hi:[0,1]
	v_pk_add_f32 v[150:151], v[38:39], v[46:47]
	v_pk_add_f32 v[38:39], v[38:39], v[46:47] neg_lo:[0,1] neg_hi:[0,1]
	v_pk_add_f32 v[46:47], v[40:41], v[146:147]
	v_pk_add_f32 v[40:41], v[40:41], v[146:147] neg_lo:[0,1] neg_hi:[0,1]
	v_pk_add_f32 v[146:147], v[144:145], v[136:137]
	v_pk_add_f32 v[136:137], v[144:145], v[136:137] neg_lo:[0,1] neg_hi:[0,1]
	v_pk_add_f32 v[144:145], v[44:45], v[142:143]
	v_pk_add_f32 v[44:45], v[44:45], v[142:143] neg_lo:[0,1] neg_hi:[0,1]
	v_pk_add_f32 v[142:143], v[36:37], v[50:51]
	v_pk_add_f32 v[36:37], v[36:37], v[50:51] neg_lo:[0,1] neg_hi:[0,1]
	v_cos_f32_e32 v50, v33
	v_sin_f32_e32 v51, v33
	v_mov_b32_e32 v153, v50
	v_mov_b32_e32 v148, v51
	v_xor_b32_e32 v152, 0x80000000, v51
	v_pk_mul_f32 v[148:149], v[152:153], v[148:149] op_sel_hi:[1,0]
	s_nop 0
	v_pk_fma_f32 v[148:149], v[50:51], v[50:51], v[148:149] op_sel_hi:[1,0,1]
	s_nop 0
	v_xor_b32_e32 v156, 0x80000000, v149
	v_mov_b32_e32 v157, v148
	v_pk_mul_f32 v[158:159], v[148:149], v[156:157] op_sel:[1,0]
	v_pk_mul_f32 v[154:155], v[152:153], v[148:149] op_sel:[0,1]
	v_pk_fma_f32 v[158:159], v[148:149], v[148:149], v[158:159] op_sel_hi:[1,0,1]
	v_pk_fma_f32 v[154:155], v[50:51], v[148:149], v[154:155] op_sel_hi:[1,0,1]
	v_xor_b32_e32 v170, 0x80000000, v159
	v_mov_b32_e32 v171, v158
	v_pk_mul_f32 v[172:173], v[158:159], v[170:171] op_sel:[1,0]
	v_pk_mul_f32 v[160:161], v[152:153], v[158:159] op_sel:[0,1]
	v_pk_fma_f32 v[172:173], v[158:159], v[158:159], v[172:173] op_sel_hi:[1,0,1]
	v_pk_fma_f32 v[160:161], v[50:51], v[158:159], v[160:161] op_sel_hi:[1,0,1]
	v_pk_mul_f32 v[174:175], v[152:153], v[172:173] op_sel:[0,1]
	v_pk_mul_f32 v[152:153], v[152:153], v[2:3] op_sel:[0,1]
	v_xor_b32_e32 v164, 0x80000000, v155
	v_mov_b32_e32 v165, v154
	v_pk_fma_f32 v[174:175], v[50:51], v[172:173], v[174:175] op_sel_hi:[1,0,1]
	v_pk_fma_f32 v[2:3], v[50:51], v[2:3], v[152:153] op_sel_hi:[1,0,1]
	v_pk_mul_f32 v[50:51], v[20:21], v[156:157] op_sel:[1,0]
	v_pk_mul_f32 v[162:163], v[156:157], v[158:159] op_sel:[0,1]
	v_pk_fma_f32 v[20:21], v[20:21], v[148:149], v[50:51] op_sel_hi:[0,1,1]
	v_pk_mul_f32 v[50:51], v[22:23], v[164:165] op_sel:[1,0]
	v_pk_fma_f32 v[162:163], v[148:149], v[158:159], v[162:163] op_sel_hi:[1,0,1]
	v_pk_mul_f32 v[166:167], v[158:159], v[164:165] op_sel:[1,0]
	v_xor_b32_e32 v182, 0x80000000, v161
	v_mov_b32_e32 v183, v160
	v_pk_fma_f32 v[22:23], v[22:23], v[154:155], v[50:51] op_sel_hi:[0,1,1]
	v_pk_mul_f32 v[50:51], v[24:25], v[170:171] op_sel:[1,0]
	v_pk_fma_f32 v[166:167], v[154:155], v[158:159], v[166:167] op_sel_hi:[1,0,1]
	v_xor_b32_e32 v186, 0x80000000, v163
	v_mov_b32_e32 v187, v162
	v_pk_fma_f32 v[24:25], v[24:25], v[158:159], v[50:51] op_sel_hi:[0,1,1]
	v_pk_mul_f32 v[50:51], v[26:27], v[182:183] op_sel:[1,0]
	v_xor_b32_e32 v190, 0x80000000, v167
	v_mov_b32_e32 v191, v166
	v_pk_fma_f32 v[26:27], v[26:27], v[160:161], v[50:51] op_sel_hi:[0,1,1]
	v_pk_mul_f32 v[50:51], v[28:29], v[186:187] op_sel:[1,0]
	v_pk_mul_f32 v[176:177], v[156:157], v[172:173] op_sel:[0,1]
	v_pk_fma_f32 v[28:29], v[28:29], v[162:163], v[50:51] op_sel_hi:[0,1,1]
	v_pk_mul_f32 v[50:51], v[30:31], v[190:191] op_sel:[1,0]
	v_pk_fma_f32 v[176:177], v[148:149], v[172:173], v[176:177] op_sel_hi:[1,0,1]
	v_pk_fma_f32 v[30:31], v[166:167], v[30:31], v[50:51] op_sel_hi:[1,0,1]
	v_pk_mul_f32 v[50:51], v[16:17], v[172:173] op_sel:[1,1] op_sel_hi:[1,0] neg_lo:[0,1]
	v_pk_mul_f32 v[178:179], v[164:165], v[172:173] op_sel:[0,1]
	v_pk_fma_f32 v[16:17], v[172:173], v[16:17], v[50:51] op_sel_hi:[1,0,1]
	v_pk_mul_f32 v[50:51], v[18:19], v[174:175] op_sel:[1,1] op_sel_hi:[1,0] neg_lo:[0,1]
	v_pk_fma_f32 v[178:179], v[154:155], v[172:173], v[178:179] op_sel_hi:[1,0,1]
	v_pk_fma_f32 v[18:19], v[174:175], v[18:19], v[50:51] op_sel_hi:[1,0,1]
	v_pk_mul_f32 v[50:51], v[12:13], v[176:177] op_sel:[1,1] op_sel_hi:[1,0] neg_lo:[0,1]
	v_pk_mul_f32 v[180:181], v[170:171], v[172:173] op_sel:[0,1]
	v_pk_fma_f32 v[12:13], v[176:177], v[12:13], v[50:51] op_sel_hi:[1,0,1]
	v_pk_fma_f32 v[180:181], v[158:159], v[172:173], v[180:181] op_sel_hi:[1,0,1]
	v_pk_mul_f32 v[50:51], v[178:179], v[14:15] op_sel:[1,1] op_sel_hi:[0,1] neg_lo:[1,0]
	v_pk_mul_f32 v[184:185], v[172:173], v[182:183] op_sel:[1,0]
	v_pk_fma_f32 v[14:15], v[178:179], v[14:15], v[50:51] op_sel_hi:[1,0,1]
	v_pk_fma_f32 v[184:185], v[160:161], v[172:173], v[184:185] op_sel_hi:[1,0,1]
	v_pk_mul_f32 v[50:51], v[180:181], v[8:9] op_sel:[1,1] op_sel_hi:[0,1] neg_lo:[1,0]
	v_pk_mul_f32 v[188:189], v[172:173], v[186:187] op_sel:[1,0]
	v_pk_fma_f32 v[8:9], v[180:181], v[8:9], v[50:51] op_sel_hi:[1,0,1]
	v_pk_fma_f32 v[188:189], v[162:163], v[172:173], v[188:189] op_sel_hi:[1,0,1]
	v_pk_mul_f32 v[50:51], v[184:185], v[10:11] op_sel:[1,1] op_sel_hi:[0,1] neg_lo:[1,0]
	v_pk_mul_f32 v[192:193], v[172:173], v[190:191] op_sel:[1,0]
	v_pk_fma_f32 v[10:11], v[184:185], v[10:11], v[50:51] op_sel_hi:[1,0,1]
	v_pk_fma_f32 v[192:193], v[166:167], v[172:173], v[192:193] op_sel_hi:[1,0,1]
	s_waitcnt lgkmcnt(0)
	v_pk_mul_f32 v[50:51], v[188:189], v[4:5] op_sel:[1,1] op_sel_hi:[0,1] neg_lo:[1,0]
	s_nop 0
	v_pk_fma_f32 v[4:5], v[188:189], v[4:5], v[50:51] op_sel_hi:[1,0,1]
	v_pk_mul_f32 v[50:51], v[192:193], v[6:7] op_sel:[1,1] op_sel_hi:[0,1] neg_lo:[1,0]
	s_nop 0
	v_pk_fma_f32 v[6:7], v[192:193], v[6:7], v[50:51] op_sel_hi:[1,0,1]
	v_pk_add_f32 v[50:51], v[0:1], v[16:17]
	v_pk_add_f32 v[0:1], v[0:1], v[16:17] neg_lo:[0,1] neg_hi:[0,1]
	v_pk_add_f32 v[16:17], v[2:3], v[18:19]
	v_pk_add_f32 v[2:3], v[2:3], v[18:19] neg_lo:[0,1] neg_hi:[0,1]
	s_nop 0
	v_pk_mul_f32 v[18:19], v[2:3], s[96:97] op_sel:[1,0]
	s_nop 0
	v_pk_fma_f32 v[2:3], v[2:3], s[58:59], v[18:19] op_sel_hi:[0,1,1]
	v_pk_add_f32 v[18:19], v[20:21], v[12:13]
	v_pk_add_f32 v[12:13], v[20:21], v[12:13] neg_lo:[0,1] neg_hi:[0,1]
	s_nop 0
	v_mul_f32_e32 v20, 0x3f3504f3, v12
	v_pk_fma_f32 v[12:13], v[12:13], s[94:95], v[20:21] op_sel:[1,0,0] op_sel_hi:[1,1,0]
	v_pk_add_f32 v[20:21], v[22:23], v[14:15]
	v_pk_add_f32 v[14:15], v[22:23], v[14:15] neg_lo:[0,1] neg_hi:[0,1]
	s_nop 0
	v_pk_mul_f32 v[22:23], v[14:15], s[44:45] op_sel:[1,0]
	s_nop 0
	v_pk_fma_f32 v[14:15], v[14:15], s[64:65], v[22:23] op_sel_hi:[0,1,1]
	v_pk_add_f32 v[22:23], v[24:25], v[8:9]
	v_pk_add_f32 v[8:9], v[24:25], v[8:9] neg_lo:[0,1] neg_hi:[0,1]
	s_nop 0
	v_xor_b32_e32 v24, 0x80000000, v9
	v_mov_b32_e32 v25, v8
	v_pk_add_f32 v[8:9], v[26:27], v[10:11]
	v_pk_add_f32 v[10:11], v[26:27], v[10:11] neg_lo:[0,1] neg_hi:[0,1]
	s_nop 0
	v_pk_mul_f32 v[26:27], v[10:11], s[40:41] op_sel:[1,0]
	s_nop 0
	v_pk_fma_f32 v[10:11], v[10:11], s[96:97], v[26:27] op_sel_hi:[0,1,1]
	v_pk_add_f32 v[26:27], v[28:29], v[4:5]
	v_pk_add_f32 v[4:5], v[28:29], v[4:5] neg_lo:[0,1] neg_hi:[0,1]
	s_nop 0
	v_mul_f32_e32 v28, 0xbf3504f3, v5
	v_pk_fma_f32 v[4:5], v[4:5], s[94:95], v[28:29] op_sel_hi:[0,1,0]
	v_pk_add_f32 v[28:29], v[30:31], v[6:7]
	v_pk_add_f32 v[6:7], v[30:31], v[6:7] neg_lo:[0,1] neg_hi:[0,1]
	s_nop 0
	v_pk_mul_f32 v[30:31], v[6:7], s[66:67] op_sel:[1,0]
	s_nop 0
	v_pk_fma_f32 v[6:7], v[6:7], s[44:45], v[30:31] op_sel_hi:[0,1,1]
	v_pk_add_f32 v[30:31], v[50:51], v[22:23]
	v_pk_add_f32 v[22:23], v[50:51], v[22:23] neg_lo:[0,1] neg_hi:[0,1]
	v_pk_add_f32 v[50:51], v[16:17], v[8:9]
	v_pk_add_f32 v[8:9], v[16:17], v[8:9] neg_lo:[0,1] neg_hi:[0,1]
	s_nop 0
	v_mul_f32_e32 v16, 0x3f3504f3, v8
	v_pk_fma_f32 v[8:9], v[8:9], s[94:95], v[16:17] op_sel:[1,0,0] op_sel_hi:[1,1,0]
	v_pk_add_f32 v[16:17], v[18:19], v[26:27]
	v_pk_add_f32 v[18:19], v[18:19], v[26:27] neg_lo:[0,1] neg_hi:[0,1]
	s_nop 0
	v_xor_b32_e32 v26, 0x80000000, v19
	v_mov_b32_e32 v27, v18
	v_pk_add_f32 v[18:19], v[20:21], v[28:29]
	v_pk_add_f32 v[20:21], v[20:21], v[28:29] neg_lo:[0,1] neg_hi:[0,1]
	s_nop 0
	v_mul_f32_e32 v28, 0xbf3504f3, v21
	v_pk_fma_f32 v[20:21], v[20:21], s[94:95], v[28:29] op_sel_hi:[0,1,0]
	v_pk_add_f32 v[28:29], v[0:1], v[24:25]
	v_pk_add_f32 v[0:1], v[0:1], v[24:25] neg_lo:[0,1] neg_hi:[0,1]
	v_pk_add_f32 v[24:25], v[2:3], v[10:11]
	v_pk_add_f32 v[2:3], v[2:3], v[10:11] neg_lo:[0,1] neg_hi:[0,1]
	s_nop 0
	v_mul_f32_e32 v10, 0x3f3504f3, v2
	v_pk_fma_f32 v[2:3], v[2:3], s[94:95], v[10:11] op_sel:[1,0,0] op_sel_hi:[1,1,0]
	v_pk_add_f32 v[10:11], v[12:13], v[4:5]
	v_pk_add_f32 v[4:5], v[12:13], v[4:5] neg_lo:[0,1] neg_hi:[0,1]
	s_nop 0
	v_xor_b32_e32 v12, 0x80000000, v5
	v_mov_b32_e32 v13, v4
	v_pk_add_f32 v[4:5], v[14:15], v[6:7]
	v_pk_add_f32 v[6:7], v[14:15], v[6:7] neg_lo:[0,1] neg_hi:[0,1]
	s_nop 0
	v_mul_f32_e32 v14, 0xbf3504f3, v7
	v_pk_fma_f32 v[6:7], v[6:7], s[94:95], v[14:15] op_sel_hi:[0,1,0]
	v_pk_add_f32 v[14:15], v[30:31], v[16:17]
	v_pk_add_f32 v[16:17], v[30:31], v[16:17] neg_lo:[0,1] neg_hi:[0,1]
	v_pk_add_f32 v[30:31], v[50:51], v[18:19]
	v_pk_add_f32 v[18:19], v[50:51], v[18:19] neg_lo:[0,1] neg_hi:[0,1]
	s_nop 0
	v_xor_b32_e32 v50, 0x80000000, v19
	v_mov_b32_e32 v51, v18
	v_pk_add_f32 v[18:19], v[22:23], v[26:27]
	v_pk_add_f32 v[22:23], v[22:23], v[26:27] neg_lo:[0,1] neg_hi:[0,1]
	v_pk_add_f32 v[26:27], v[8:9], v[20:21]
	v_pk_add_f32 v[8:9], v[8:9], v[20:21] neg_lo:[0,1] neg_hi:[0,1]
	s_nop 0
	v_xor_b32_e32 v20, 0x80000000, v9
	v_mov_b32_e32 v21, v8
	v_pk_add_f32 v[8:9], v[28:29], v[10:11]
	v_pk_add_f32 v[10:11], v[28:29], v[10:11] neg_lo:[0,1] neg_hi:[0,1]
	v_pk_add_f32 v[28:29], v[24:25], v[4:5]
	v_pk_add_f32 v[4:5], v[24:25], v[4:5] neg_lo:[0,1] neg_hi:[0,1]
	s_nop 0
	v_xor_b32_e32 v24, 0x80000000, v5
	v_mov_b32_e32 v25, v4
	v_pk_add_f32 v[4:5], v[0:1], v[12:13]
	v_pk_add_f32 v[0:1], v[0:1], v[12:13] neg_lo:[0,1] neg_hi:[0,1]
	v_pk_add_f32 v[12:13], v[2:3], v[6:7]
	v_pk_add_f32 v[2:3], v[2:3], v[6:7] neg_lo:[0,1] neg_hi:[0,1]
	s_nop 0
	v_xor_b32_e32 v6, 0x80000000, v3
	v_mov_b32_e32 v7, v2
	v_pk_add_f32 v[2:3], v[14:15], v[30:31]
	v_pk_add_f32 v[14:15], v[14:15], v[30:31] neg_lo:[0,1] neg_hi:[0,1]
	v_pk_add_f32 v[30:31], v[16:17], v[50:51]
	v_pk_add_f32 v[16:17], v[16:17], v[50:51] neg_lo:[0,1] neg_hi:[0,1]
	v_pk_add_f32 v[50:51], v[18:19], v[26:27]
	v_pk_add_f32 v[18:19], v[18:19], v[26:27] neg_lo:[0,1] neg_hi:[0,1]
	v_pk_add_f32 v[26:27], v[22:23], v[20:21]
	v_pk_add_f32 v[20:21], v[22:23], v[20:21] neg_lo:[0,1] neg_hi:[0,1]
	v_pk_add_f32 v[22:23], v[8:9], v[28:29]
	v_pk_add_f32 v[8:9], v[8:9], v[28:29] neg_lo:[0,1] neg_hi:[0,1]
	v_pk_add_f32 v[28:29], v[10:11], v[24:25]
	v_pk_add_f32 v[10:11], v[10:11], v[24:25] neg_lo:[0,1] neg_hi:[0,1]
	v_pk_add_f32 v[24:25], v[4:5], v[12:13]
	v_pk_add_f32 v[4:5], v[4:5], v[12:13] neg_lo:[0,1] neg_hi:[0,1]
	v_pk_add_f32 v[12:13], v[0:1], v[6:7]
	v_pk_add_f32 v[0:1], v[0:1], v[6:7] neg_lo:[0,1] neg_hi:[0,1]
	ds_write_b64 v32, v[42:43]
	ds_write_b64 v34, v[2:3]
	ds_write_b64 v32, v[52:53] offset:8256
	ds_write_b64 v34, v[14:15] offset:8256
	ds_write_b64 v32, v[54:55] offset:4128
	ds_write_b64 v34, v[30:31] offset:4128
	ds_write_b64 v32, v[48:49] offset:12384
	ds_write_b64 v34, v[16:17] offset:12384
	ds_write_b64 v32, v[140:141] offset:2064
	ds_write_b64 v34, v[50:51] offset:2064
	ds_write_b64 v32, v[138:139] offset:10320
	ds_write_b64 v34, v[18:19] offset:10320
	ds_write_b64 v32, v[150:151] offset:6192
	ds_write_b64 v34, v[26:27] offset:6192
	ds_write_b64 v32, v[38:39] offset:14448
	ds_write_b64 v34, v[20:21] offset:14448
	ds_write_b64 v32, v[46:47] offset:1032
	ds_write_b64 v34, v[22:23] offset:1032
	ds_write_b64 v32, v[40:41] offset:9288
	ds_write_b64 v34, v[8:9] offset:9288
	ds_write_b64 v32, v[146:147] offset:5160
	ds_write_b64 v34, v[28:29] offset:5160
	ds_write_b64 v32, v[136:137] offset:13416
	ds_write_b64 v34, v[10:11] offset:13416
	ds_write_b64 v32, v[144:145] offset:3096
	ds_write_b64 v34, v[24:25] offset:3096
	ds_write_b64 v32, v[44:45] offset:11352
	ds_write_b64 v34, v[4:5] offset:11352
	ds_write_b64 v32, v[142:143] offset:7224
	ds_write_b64 v34, v[12:13] offset:7224
	ds_write_b64 v32, v[36:37] offset:15480
	ds_write_b64 v34, v[0:1] offset:15480
	s_andn2_b64 exec, exec, s[92:93]
	s_cbranch_execnz .LBB0_362

.LBB0_365:
	v_ashrrev_i32_e32 v0, 7, v37
	v_add_u32_e32 v66, 0x200, v37
	v_ashrrev_i32_e32 v2, 7, v66
	v_mad_u64_u32 v[0:1], s[40:41], v0, s25, v[60:61]
	v_mov_b32_e32 v26, v37
	v_mad_u64_u32 v[2:3], s[40:41], v2, s25, v[60:61]
	v_add_u32_e32 v1, 0x10200, v0
	ds_read_b64 v[22:23], v0
	ds_read_b64 v[4:5], v2
	ds_read_b64 v[20:21], v0 offset:16512
	ds_read_b64 v[6:7], v2 offset:16512
	ds_read_b64 v[24:25], v0 offset:33024
	ds_read_b64 v[8:9], v2 offset:33024
	ds_read_b64 v[28:29], v0 offset:49536
	ds_read_b64 v[10:11], v2 offset:49536
	ds_read_b64 v[30:31], v1
	v_add_u32_e32 v1, 0x10200, v2
	ds_read_b64 v[12:13], v1
	v_add_u32_e32 v1, 0x14280, v0
	ds_read_b64 v[32:33], v1
	v_add_u32_e32 v1, 0x14280, v2
	ds_read_b64 v[14:15], v1
	v_add_u32_e32 v1, 0x18300, v0
	ds_read_b64 v[34:35], v1
	v_add_u32_e32 v1, 0x18300, v2
	ds_read_b64 v[16:17], v1
	v_add_u32_e32 v1, 0x1c380, v0
	ds_read_b64 v[38:39], v1
	v_add_u32_e32 v1, 0x1c380, v2
	ds_read_b64 v[18:19], v1
	v_cvt_f32_i32_e32 v1, v26
	s_mov_b32 s40, s57
	s_mov_b32 s41, s56
	v_cmp_lt_i32_e32 vcc, s28, v37
	v_mul_f32_e32 v1, 0x38800000, v1
	v_cos_f32_e32 v26, v1
	v_sin_f32_e32 v27, v1
	v_cvt_f32_i32_e32 v1, v66
	s_or_b64 s[92:93], vcc, s[92:93]
	v_mov_b32_e32 v41, v26
	v_mov_b32_e32 v36, v27
	v_xor_b32_e32 v40, 0x80000000, v27
	v_pk_mul_f32 v[42:43], v[40:41], v[36:37] op_sel_hi:[1,0]
	v_mul_f32_e32 v1, 0x38800000, v1
	v_pk_fma_f32 v[42:43], v[26:27], v[26:27], v[42:43] op_sel_hi:[1,0,1]
	s_nop 0
	v_pk_mul_f32 v[48:49], v[42:43], v[42:43] op_sel:[1,1] op_sel_hi:[1,0] neg_lo:[0,1]
	v_pk_mul_f32 v[44:45], v[40:41], v[42:43] op_sel:[0,1]
	v_pk_fma_f32 v[48:49], v[42:43], v[42:43], v[48:49] op_sel_hi:[1,0,1]
	v_pk_fma_f32 v[44:45], v[26:27], v[42:43], v[44:45] op_sel_hi:[1,0,1]
	v_pk_mul_f32 v[50:51], v[40:41], v[48:49] op_sel:[0,1]
	s_waitcnt lgkmcnt(13)
	v_pk_mul_f32 v[40:41], v[40:41], v[20:21] op_sel:[0,1]
	v_pk_fma_f32 v[40:41], v[26:27], v[20:21], v[40:41] op_sel_hi:[1,0,1]
	s_waitcnt lgkmcnt(11)
	v_pk_mul_f32 v[20:21], v[24:25], v[42:43] op_sel:[1,1] op_sel_hi:[1,0] neg_lo:[0,1]
	v_pk_fma_f32 v[50:51], v[26:27], v[48:49], v[50:51] op_sel_hi:[1,0,1]
	v_pk_fma_f32 v[26:27], v[24:25], v[42:43], v[20:21] op_sel_hi:[0,1,1]
	s_waitcnt lgkmcnt(9)
	v_pk_mul_f32 v[20:21], v[28:29], v[44:45] op_sel:[1,1] op_sel_hi:[1,0] neg_lo:[0,1]
	v_pk_mul_f32 v[52:53], v[42:43], v[48:49] op_sel:[1,1] op_sel_hi:[0,1] neg_lo:[1,0]
	v_pk_fma_f32 v[24:25], v[28:29], v[44:45], v[20:21] op_sel_hi:[0,1,1]
	s_waitcnt lgkmcnt(7)
	v_pk_mul_f32 v[20:21], v[30:31], v[48:49] op_sel:[1,1] op_sel_hi:[1,0] neg_lo:[0,1]
	v_pk_fma_f32 v[52:53], v[42:43], v[48:49], v[52:53] op_sel_hi:[1,0,1]
	v_pk_fma_f32 v[28:29], v[30:31], v[48:49], v[20:21] op_sel_hi:[0,1,1]
	s_waitcnt lgkmcnt(5)
	v_pk_mul_f32 v[20:21], v[32:33], v[50:51] op_sel:[1,1] op_sel_hi:[1,0] neg_lo:[0,1]
	v_pk_mul_f32 v[136:137], v[48:49], v[44:45] op_sel:[1,1] op_sel_hi:[1,0] neg_lo:[0,1]
	v_pk_fma_f32 v[42:43], v[32:33], v[50:51], v[20:21] op_sel_hi:[0,1,1]
	v_pk_fma_f32 v[136:137], v[44:45], v[48:49], v[136:137] op_sel_hi:[1,0,1]
	s_waitcnt lgkmcnt(3)
	v_pk_mul_f32 v[20:21], v[34:35], v[52:53] op_sel:[1,1] op_sel_hi:[1,0] neg_lo:[0,1]
	s_nop 0
	v_pk_fma_f32 v[30:31], v[34:35], v[52:53], v[20:21] op_sel_hi:[0,1,1]
	s_waitcnt lgkmcnt(1)
	v_pk_mul_f32 v[20:21], v[38:39], v[136:137] op_sel:[1,1] op_sel_hi:[1,0] neg_lo:[0,1]
	v_pk_add_f32 v[34:35], v[40:41], v[42:43] neg_lo:[0,1] neg_hi:[0,1]
	v_pk_fma_f32 v[32:33], v[136:137], v[38:39], v[20:21] op_sel_hi:[1,0,1]
	v_pk_add_f32 v[38:39], v[26:27], v[30:31]
	v_pk_add_f32 v[26:27], v[26:27], v[30:31] neg_lo:[0,1] neg_hi:[0,1]
	v_pk_add_f32 v[20:21], v[22:23], v[28:29]
	v_xor_b32_e32 v30, 0x80000000, v27
	v_mov_b32_e32 v31, v26
	v_pk_add_f32 v[26:27], v[24:25], v[32:33]
	v_pk_add_f32 v[24:25], v[24:25], v[32:33] neg_lo:[0,1] neg_hi:[0,1]
	v_pk_add_f32 v[28:29], v[22:23], v[28:29] neg_lo:[0,1] neg_hi:[0,1]
	v_pk_add_f32 v[22:23], v[40:41], v[42:43]
	v_mul_f32_e32 v36, 0x3f3504f3, v34
	v_mul_f32_e32 v32, 0xbf3504f3, v25
	v_pk_fma_f32 v[34:35], v[34:35], s[40:41], v[36:37] op_sel:[1,0,0] op_sel_hi:[1,1,0]
	v_pk_fma_f32 v[24:25], v[24:25], s[40:41], v[32:33] op_sel_hi:[0,1,0]
	v_pk_add_f32 v[40:41], v[22:23], v[26:27] neg_lo:[0,1] neg_hi:[0,1]
	v_pk_add_f32 v[32:33], v[20:21], v[38:39] neg_lo:[0,1] neg_hi:[0,1]
	v_xor_b32_e32 v42, 0x80000000, v41
	v_mov_b32_e32 v43, v40
	v_pk_add_f32 v[40:41], v[28:29], v[30:31]
	v_pk_add_f32 v[28:29], v[28:29], v[30:31] neg_lo:[0,1] neg_hi:[0,1]
	v_pk_add_f32 v[30:31], v[34:35], v[24:25]
	v_pk_add_f32 v[24:25], v[34:35], v[24:25] neg_lo:[0,1] neg_hi:[0,1]
	v_pk_add_f32 v[30:31], v[40:41], v[30:31]
	v_xor_b32_e32 v34, 0x80000000, v25
	v_mov_b32_e32 v35, v24
	v_pk_add_f32 v[24:25], v[32:33], v[42:43]
	v_cos_f32_e32 v32, v1
	v_sin_f32_e32 v33, v1
	v_pk_add_f32 v[28:29], v[28:29], v[34:35]
	v_add_u32_e32 v37, 0x400, v37
	v_mov_b32_e32 v41, v32
	v_mov_b32_e32 v34, v33
	v_xor_b32_e32 v40, 0x80000000, v33
	v_pk_mul_f32 v[34:35], v[40:41], v[34:35] op_sel_hi:[1,0]
	s_nop 0
	v_pk_fma_f32 v[34:35], v[32:33], v[32:33], v[34:35] op_sel_hi:[1,0,1]
	s_nop 0
	v_xor_b32_e32 v44, 0x80000000, v35
	v_mov_b32_e32 v45, v34
	v_pk_mul_f32 v[46:47], v[34:35], v[44:45] op_sel:[1,0]
	v_pk_mul_f32 v[42:43], v[40:41], v[34:35] op_sel:[0,1]
	v_pk_fma_f32 v[46:47], v[34:35], v[34:35], v[46:47] op_sel_hi:[1,0,1]
	v_pk_fma_f32 v[42:43], v[32:33], v[34:35], v[42:43] op_sel_hi:[1,0,1]
	v_pk_mul_f32 v[48:49], v[40:41], v[46:47] op_sel:[0,1]
	v_pk_mul_f32 v[40:41], v[40:41], v[6:7] op_sel:[0,1]
	v_pk_fma_f32 v[48:49], v[32:33], v[46:47], v[48:49] op_sel_hi:[1,0,1]
	v_xor_b32_e32 v52, 0x80000000, v43
	v_mov_b32_e32 v53, v42
	v_pk_fma_f32 v[6:7], v[32:33], v[6:7], v[40:41] op_sel_hi:[1,0,1]
	v_pk_mul_f32 v[32:33], v[8:9], v[44:45] op_sel:[1,0]
	v_pk_mul_f32 v[50:51], v[44:45], v[46:47] op_sel:[0,1]
	v_pk_fma_f32 v[8:9], v[8:9], v[34:35], v[32:33] op_sel_hi:[0,1,1]
	v_pk_mul_f32 v[32:33], v[10:11], v[52:53] op_sel:[1,0]
	v_pk_fma_f32 v[50:51], v[34:35], v[46:47], v[50:51] op_sel_hi:[1,0,1]
	v_pk_fma_f32 v[10:11], v[10:11], v[42:43], v[32:33] op_sel_hi:[0,1,1]
	v_pk_mul_f32 v[32:33], v[12:13], v[46:47] op_sel:[1,1] op_sel_hi:[1,0] neg_lo:[0,1]
	v_pk_mul_f32 v[54:55], v[46:47], v[52:53] op_sel:[1,0]
	v_pk_fma_f32 v[12:13], v[12:13], v[46:47], v[32:33] op_sel_hi:[0,1,1]
	v_pk_mul_f32 v[32:33], v[14:15], v[48:49] op_sel:[1,1] op_sel_hi:[1,0] neg_lo:[0,1]
	v_pk_fma_f32 v[54:55], v[42:43], v[46:47], v[54:55] op_sel_hi:[1,0,1]
	v_pk_fma_f32 v[14:15], v[14:15], v[48:49], v[32:33] op_sel_hi:[0,1,1]
	v_pk_mul_f32 v[32:33], v[16:17], v[50:51] op_sel:[1,1] op_sel_hi:[1,0] neg_lo:[0,1]
	s_nop 0
	v_pk_fma_f32 v[16:17], v[16:17], v[50:51], v[32:33] op_sel_hi:[0,1,1]
	s_waitcnt lgkmcnt(0)
	v_pk_mul_f32 v[32:33], v[18:19], v[54:55] op_sel:[1,1] op_sel_hi:[1,0] neg_lo:[0,1]
	s_nop 0
	v_pk_fma_f32 v[18:19], v[54:55], v[18:19], v[32:33] op_sel_hi:[1,0,1]
	v_pk_add_f32 v[32:33], v[4:5], v[12:13]
	v_pk_add_f32 v[4:5], v[4:5], v[12:13] neg_lo:[0,1] neg_hi:[0,1]
	v_pk_add_f32 v[12:13], v[6:7], v[14:15]
	v_pk_add_f32 v[6:7], v[6:7], v[14:15] neg_lo:[0,1] neg_hi:[0,1]
	s_nop 0
	v_mul_f32_e32 v14, 0x3f3504f3, v6
	v_pk_fma_f32 v[6:7], v[6:7], s[40:41], v[14:15] op_sel:[1,0,0] op_sel_hi:[1,1,0]
	v_pk_add_f32 v[14:15], v[8:9], v[16:17]
	v_pk_add_f32 v[8:9], v[8:9], v[16:17] neg_lo:[0,1] neg_hi:[0,1]
	s_nop 0
	v_xor_b32_e32 v16, 0x80000000, v9
	v_mov_b32_e32 v17, v8
	v_pk_add_f32 v[8:9], v[10:11], v[18:19]
	v_pk_add_f32 v[10:11], v[10:11], v[18:19] neg_lo:[0,1] neg_hi:[0,1]
	v_pk_add_f32 v[34:35], v[12:13], v[8:9] neg_lo:[0,1] neg_hi:[0,1]
	v_mul_f32_e32 v18, 0xbf3504f3, v11
	v_pk_fma_f32 v[10:11], v[10:11], s[40:41], v[18:19] op_sel_hi:[0,1,0]
	v_xor_b32_e32 v40, 0x80000000, v35
	v_mov_b32_e32 v41, v34
	v_pk_add_f32 v[34:35], v[4:5], v[16:17]
	v_pk_add_f32 v[4:5], v[4:5], v[16:17] neg_lo:[0,1] neg_hi:[0,1]
	v_pk_add_f32 v[16:17], v[6:7], v[10:11]
	v_pk_add_f32 v[6:7], v[6:7], v[10:11] neg_lo:[0,1] neg_hi:[0,1]
	v_pk_add_f32 v[8:9], v[12:13], v[8:9]
	v_pk_add_f32 v[4:5], v[4:5], v[6:7] op_sel:[0,1] op_sel_hi:[1,0] neg_lo:[0,1]
	v_pk_add_f32 v[10:11], v[32:33], v[14:15]
	v_pk_add_f32 v[12:13], v[20:21], v[38:39]
	v_pk_add_f32 v[8:9], v[10:11], v[8:9]
	v_pk_add_f32 v[10:11], v[22:23], v[26:27]
	v_pk_add_f32 v[18:19], v[32:33], v[14:15] neg_lo:[0,1] neg_hi:[0,1]
	v_pk_add_f32 v[10:11], v[12:13], v[10:11]
	v_pk_add_f32 v[6:7], v[18:19], v[40:41]
	v_pk_add_f32 v[16:17], v[34:35], v[16:17]
	ds_write_b64 v0, v[10:11]
	ds_write_b64 v2, v[8:9]
	ds_write_b64 v0, v[24:25] offset:33024
	ds_write_b64 v2, v[6:7] offset:33024
	ds_write_b64 v0, v[30:31] offset:16512
	ds_write_b64 v2, v[16:17] offset:16512
	ds_write_b64 v0, v[28:29] offset:49536
	ds_write_b64 v2, v[4:5] offset:49536
	s_andn2_b64 exec, exec, s[92:93]
	s_cbranch_execnz .LBB0_365
